# v22 + staging-load pairing extended to layer-1 input projection and two up-projection loops (address temps renamed), attention counted vmcnt for two tiles in flight, cross-half row max via v_permlane3
# speedup vs baseline: 1.0112x; 1.0028x over previous
; DI f32x4 mfma16(bf16x8 a, bf16x8 b, f32x4 c) { return __builtin_amdgcn_mfma_f32_16x16x32_bf16(a, b, c, 0, 0, 0); }
; template <int MI, int NJ, bool SWAP, class AP, class BP>
; DI void gemm_main(f32x4 (&acc)[MI][NJ], const AP& ap, int a_kstep, const BP& bp, int b_kstep, int nk, bf16_t* smem) {
;     ...
;   auto gload = [&](int kt) {
;     const bf16_t* ab = ap.base + (size_t)kt * a_kstep; const bf16_t* bb = bp.base + (size_t)kt * b_kstep;
; #pragma unroll
;     for (int i = 0; i < CA; ++i) ra[i] = *(const u32x4*)(ab + pa[i]);
; #pragma unroll
;     for (int i = 0; i < CB; ++i) rb[i] = *(const u32x4*)(bb + pb[i]);
;   };
;   auto sstore = [&](int buf) {
;     bf16_t* As = smem + buf * L::STAGE; bf16_t* Bs = As + L::A_ELEMS;
; #pragma unroll
;     for (int i = 0; i < CA; ++i) { const int c = tid + NTHR * i; *(u32x4*)(As + (c >> 3) * LDT + (c & 7) * 8) = oka[i] ? ra[i] : (u32x4){0u, 0u, 0u, 0u}; }
; #pragma unroll
;     for (int i = 0; i < CB; ++i) { const int c = tid + NTHR * i; *(u32x4*)(Bs + (c >> 3) * LDT + (c & 7) * 8) = rb[i]; }
;   };
;   gload(0); sstore(0); gload(nk > 1 ? 1 : 0); __syncthreads();
; #pragma unroll 1
;   for (int kt = 0; kt < nk; ++kt) {
;     const int buf = kt & 1;
;     sstore(buf ^ 1);
;     gload(kt + 2 < nk ? kt + 2 : nk - 1);
;     __builtin_amdgcn_sched_barrier(0);
;     const bf16_t* As = smem + buf * L::STAGE + (wm * 16 * MI + l15) * LDT + quad * 8;
;     const bf16_t* Bs = smem + buf * L::STAGE + L::A_ELEMS + (wn * 16 * NJ + l15) * LDT + quad * 8;
; #pragma unroll
;     for (int ks = 0; ks < 2; ++ks) {
;       if (MI * NJ >= 32 && ks == 1) asm volatile("" ::: "memory");
;       bf16x8 b[NJ];
; #pragma unroll
;       for (int j = 0; j < NJ; ++j) b[j] = *(const bf16x8*)(Bs + j * 16 * LDT + ks * 32);
; #pragma unroll
;       for (int i = 0; i < MI; ++i) {
;         const bf16x8 a = *(const bf16x8*)(As + i * 16 * LDT + ks * 32);
; #pragma unroll
;         for (int j = 0; j < NJ; ++j) acc[i][j] = SWAP ? mfma16(b[j], a, acc[i][j]) : mfma16(a, b[j], acc[i][j]);
;       }
;     }
;     __syncthreads();
;   }
.Lgm0_main:
	ds_read_b128 v[242:245], v176 offset:4608
	s_waitcnt lgkmcnt(4)
	v_mfma_f32_16x16x32_bf16 v[124:127], v[178:181], v[212:215], v[124:127]
	s_waitcnt lgkmcnt(3)
	v_mfma_f32_16x16x32_bf16 v[120:123], v[200:203], v[212:215], v[120:123]
	s_waitcnt lgkmcnt(2)
	v_mfma_f32_16x16x32_bf16 v[116:119], v[204:207], v[212:215], v[116:119]
	s_and_b32 s5, s4, 1
	s_min_u32 s6, s4, 13
	s_xor_b32 s7, s5, 1
	s_mul_i32 s7, s7, 0x12000
	v_add3_u32 v250, s7, v171, v169
	s_waitcnt vmcnt(7)
	ds_write_b128 v250, v[128:131]
	s_waitcnt lgkmcnt(2)
	v_mfma_f32_16x16x32_bf16 v[112:115], v[208:211], v[212:215], v[112:115]
	ds_read_b128 v[246:249], v176 offset:6912
	v_mfma_f32_16x16x32_bf16 v[108:111], v[178:181], v[216:219], v[108:111]
	s_lshl_b32 s33, s6, 7
	s_add_u32 s6, s0, s33
	v_add3_u32 v251, s7, v173, v169
	v_add3_u32 v252, s7, v174, v169
	v_add3_u32 v253, s7, v175, v169
	s_addc_u32 s7, s1, 0
	v_lshl_add_u64 v[128:129], s[6:7], 0, v[160:161]
	s_nop 0
	global_load_dwordx4 v[128:131], v[128:129], off offset:256
	v_mfma_f32_16x16x32_bf16 v[104:107], v[200:203], v[216:219], v[104:107]
	v_mfma_f32_16x16x32_bf16 v[100:103], v[204:207], v[216:219], v[100:103]
	v_mfma_f32_16x16x32_bf16 v[96:99], v[208:211], v[216:219], v[96:99]
	ds_read_b128 v[212:215], v176 offset:9216
	s_waitcnt lgkmcnt(3)
	v_mfma_f32_16x16x32_bf16 v[92:95], v[178:181], v[242:245], v[92:95]
	s_waitcnt vmcnt(7)
	ds_write_b128 v251, v[132:135]
	v_mfma_f32_16x16x32_bf16 v[88:91], v[200:203], v[242:245], v[88:91]
	v_mfma_f32_16x16x32_bf16 v[84:87], v[204:207], v[242:245], v[84:87]
	v_lshl_add_u64 v[132:133], s[6:7], 0, v[162:163]
	s_nop 0
	global_load_dwordx4 v[132:135], v[132:133], off offset:256
	v_mfma_f32_16x16x32_bf16 v[80:83], v[208:211], v[242:245], v[80:83]
	ds_read_b128 v[216:219], v176 offset:11520
	s_waitcnt lgkmcnt(3)
	v_mfma_f32_16x16x32_bf16 v[76:79], v[178:181], v[246:249], v[76:79]
	v_mfma_f32_16x16x32_bf16 v[72:75], v[200:203], v[246:249], v[72:75]
	v_mfma_f32_16x16x32_bf16 v[68:71], v[204:207], v[246:249], v[68:71]
	s_waitcnt vmcnt(7)
	ds_write_b128 v252, v[136:139]
	v_mfma_f32_16x16x32_bf16 v[64:67], v[208:211], v[246:249], v[64:67]
	ds_read_b128 v[242:245], v176 offset:13824
	s_waitcnt lgkmcnt(4)
	v_mfma_f32_16x16x32_bf16 v[60:63], v[178:181], v[212:215], v[60:63]
	v_lshl_add_u64 v[136:137], s[6:7], 0, v[164:165]
	s_nop 0
	global_load_dwordx4 v[136:139], v[136:137], off offset:256
	v_mfma_f32_16x16x32_bf16 v[56:59], v[200:203], v[212:215], v[56:59]
	v_mfma_f32_16x16x32_bf16 v[52:55], v[204:207], v[212:215], v[52:55]
	v_mfma_f32_16x16x32_bf16 v[48:51], v[208:211], v[212:215], v[48:51]
	ds_read_b128 v[246:249], v176 offset:16128
	s_waitcnt lgkmcnt(3)
	v_mfma_f32_16x16x32_bf16 v[44:47], v[178:181], v[216:219], v[44:47]
	s_waitcnt vmcnt(7)
	ds_write_b128 v253, v[140:143]
	v_mfma_f32_16x16x32_bf16 v[40:43], v[200:203], v[216:219], v[40:43]
	v_mfma_f32_16x16x32_bf16 v[36:39], v[204:207], v[216:219], v[36:39]
	v_lshl_add_u64 v[140:141], s[6:7], 0, v[166:167]
	s_nop 0
	global_load_dwordx4 v[140:143], v[140:141], off offset:256
	v_mfma_f32_16x16x32_bf16 v[32:35], v[208:211], v[216:219], v[32:35]
	ds_read_b128 v[212:215], v176 offset:64
	s_waitcnt lgkmcnt(3)
	v_mfma_f32_16x16x32_bf16 v[28:31], v[178:181], v[242:245], v[28:31]
	v_mfma_f32_16x16x32_bf16 v[24:27], v[200:203], v[242:245], v[24:27]
	v_mfma_f32_16x16x32_bf16 v[20:23], v[204:207], v[242:245], v[20:23]
	s_waitcnt vmcnt(7)
	ds_write_b128 v250, v[144:147] offset:36864
	v_mfma_f32_16x16x32_bf16 v[16:19], v[208:211], v[242:245], v[16:19]
	ds_read_b128 v[216:219], v176 offset:2368
	s_waitcnt lgkmcnt(4)
	v_mfma_f32_16x16x32_bf16 v[12:15], v[178:181], v[246:249], v[12:15]
	ds_read_b128 v[178:181], v182 offset:36928
	s_add_u32 s6, s2, s33
	s_addc_u32 s7, s3, 0
	v_lshl_add_u64 v[144:145], s[6:7], 0, v[160:161]
	s_nop 0
	global_load_dwordx4 v[144:147], v[144:145], off offset:256
	v_mfma_f32_16x16x32_bf16 v[8:11], v[200:203], v[246:249], v[8:11]
	ds_read_b128 v[200:203], v182 offset:39232
	v_mfma_f32_16x16x32_bf16 v[0:3], v[204:207], v[246:249], v[0:3]
	ds_read_b128 v[204:207], v182 offset:41536
	v_mfma_f32_16x16x32_bf16 v[4:7], v[208:211], v[246:249], v[4:7]
	ds_read_b128 v[208:211], v182 offset:43840
	ds_read_b128 v[242:245], v176 offset:4672
	s_waitcnt lgkmcnt(4)
	v_mfma_f32_16x16x32_bf16 v[124:127], v[178:181], v[212:215], v[124:127]
	s_waitcnt vmcnt(7)
	ds_write_b128 v251, v[148:151] offset:36864
	s_waitcnt lgkmcnt(4)
	v_mfma_f32_16x16x32_bf16 v[120:123], v[200:203], v[212:215], v[120:123]
	s_waitcnt lgkmcnt(3)
	v_mfma_f32_16x16x32_bf16 v[116:119], v[204:207], v[212:215], v[116:119]
	v_lshl_add_u64 v[148:149], s[6:7], 0, v[162:163]
	s_nop 0
	global_load_dwordx4 v[148:151], v[148:149], off offset:256
	s_waitcnt lgkmcnt(2)
	v_mfma_f32_16x16x32_bf16 v[112:115], v[208:211], v[212:215], v[112:115]
	ds_read_b128 v[246:249], v176 offset:6976
	v_mfma_f32_16x16x32_bf16 v[108:111], v[178:181], v[216:219], v[108:111]
	v_mfma_f32_16x16x32_bf16 v[104:107], v[200:203], v[216:219], v[104:107]
	v_mfma_f32_16x16x32_bf16 v[100:103], v[204:207], v[216:219], v[100:103]
	s_waitcnt vmcnt(7)
	ds_write_b128 v252, v[152:155] offset:36864
	v_mfma_f32_16x16x32_bf16 v[96:99], v[208:211], v[216:219], v[96:99]
	ds_read_b128 v[212:215], v176 offset:9280
	s_waitcnt lgkmcnt(4)
	v_mfma_f32_16x16x32_bf16 v[92:95], v[178:181], v[242:245], v[92:95]
	v_lshl_add_u64 v[152:153], s[6:7], 0, v[164:165]
	s_nop 0
	global_load_dwordx4 v[152:155], v[152:153], off offset:256
	v_mfma_f32_16x16x32_bf16 v[88:91], v[200:203], v[242:245], v[88:91]
	v_mfma_f32_16x16x32_bf16 v[84:87], v[204:207], v[242:245], v[84:87]
	v_mfma_f32_16x16x32_bf16 v[80:83], v[208:211], v[242:245], v[80:83]
	ds_read_b128 v[216:219], v176 offset:11584
	s_waitcnt lgkmcnt(3)
	v_mfma_f32_16x16x32_bf16 v[76:79], v[178:181], v[246:249], v[76:79]
	s_waitcnt vmcnt(7)
	ds_write_b128 v253, v[156:159] offset:36864
	v_mfma_f32_16x16x32_bf16 v[72:75], v[200:203], v[246:249], v[72:75]
	v_mfma_f32_16x16x32_bf16 v[68:71], v[204:207], v[246:249], v[68:71]
	v_lshl_add_u64 v[156:157], s[6:7], 0, v[166:167]
	s_nop 0
	global_load_dwordx4 v[156:159], v[156:157], off offset:256
	v_mfma_f32_16x16x32_bf16 v[64:67], v[208:211], v[246:249], v[64:67]
	ds_read_b128 v[242:245], v176 offset:13888
	s_waitcnt lgkmcnt(3)
	v_mfma_f32_16x16x32_bf16 v[60:63], v[178:181], v[212:215], v[60:63]
	v_mfma_f32_16x16x32_bf16 v[56:59], v[200:203], v[212:215], v[56:59]
	v_mfma_f32_16x16x32_bf16 v[52:55], v[204:207], v[212:215], v[52:55]
	v_mfma_f32_16x16x32_bf16 v[48:51], v[208:211], v[212:215], v[48:51]
	ds_read_b128 v[246:249], v176 offset:16192
	s_waitcnt lgkmcnt(3)
	v_mfma_f32_16x16x32_bf16 v[44:47], v[178:181], v[216:219], v[44:47]
	v_mfma_f32_16x16x32_bf16 v[40:43], v[200:203], v[216:219], v[40:43]
	v_mfma_f32_16x16x32_bf16 v[36:39], v[204:207], v[216:219], v[36:39]
	v_mfma_f32_16x16x32_bf16 v[32:35], v[208:211], v[216:219], v[32:35]
	s_waitcnt lgkmcnt(0)
	s_barrier
; DI f32x4 mfma16(bf16x8 a, bf16x8 b, f32x4 c) { return __builtin_amdgcn_mfma_f32_16x16x32_bf16(a, b, c, 0, 0, 0); }
; template <int MI, int NJ, bool SWAP, class AP, class BP>
; DI void gemm_main(f32x4 (&acc)[MI][NJ], const AP& ap, int a_kstep, const BP& bp, int b_kstep, int nk, bf16_t* smem) {
;     ...
;   for (int kt = 0; kt < nk; ++kt) {
;     const int buf = kt & 1;
;     sstore(buf ^ 1);
;     gload(kt + 2 < nk ? kt + 2 : nk - 1);
;     __builtin_amdgcn_sched_barrier(0);
;     const bf16_t* As = smem + buf * L::STAGE + (wm * 16 * MI + l15) * LDT + quad * 8;
;     const bf16_t* Bs = smem + buf * L::STAGE + L::A_ELEMS + (wn * 16 * NJ + l15) * LDT + quad * 8;
; #pragma unroll
;     for (int ks = 0; ks < 2; ++ks) {
;       if (MI * NJ >= 32 && ks == 1) asm volatile("" ::: "memory");
;       bf16x8 b[NJ];
; #pragma unroll
;       for (int j = 0; j < NJ; ++j) b[j] = *(const bf16x8*)(Bs + j * 16 * LDT + ks * 32);
; #pragma unroll
;       for (int i = 0; i < MI; ++i) {
;         const bf16x8 a = *(const bf16x8*)(As + i * 16 * LDT + ks * 32);
; #pragma unroll
;         for (int j = 0; j < NJ; ++j) acc[i][j] = SWAP ? mfma16(b[j], a, acc[i][j]) : mfma16(a, b[j], acc[i][j]);
;       }
;     }
;     __syncthreads();
;   }
	s_add_i32 s4, s4, 1
	s_cmp_lg_u32 s4, 16
	s_cbranch_scc0 .Lgm0_exit
	s_and_b32 s98, s4, 1
	s_mul_i32 s98, s98, 0x12000
	v_add3_u32 v182, s98, v168, v172
	v_add3_u32 v176, s98, v170, v172
	ds_read_b128 v[212:215], v176
	ds_read_b128 v[216:219], v176 offset:2304
	v_mfma_f32_16x16x32_bf16 v[28:31], v[178:181], v[242:245], v[28:31]
	v_mfma_f32_16x16x32_bf16 v[12:15], v[178:181], v[246:249], v[12:15]
	ds_read_b128 v[178:181], v182 offset:36864
	v_mfma_f32_16x16x32_bf16 v[24:27], v[200:203], v[242:245], v[24:27]
	v_mfma_f32_16x16x32_bf16 v[8:11], v[200:203], v[246:249], v[8:11]
	ds_read_b128 v[200:203], v182 offset:39168
	v_mfma_f32_16x16x32_bf16 v[20:23], v[204:207], v[242:245], v[20:23]
	v_mfma_f32_16x16x32_bf16 v[0:3], v[204:207], v[246:249], v[0:3]
	ds_read_b128 v[204:207], v182 offset:41472
	v_mfma_f32_16x16x32_bf16 v[16:19], v[208:211], v[242:245], v[16:19]
	v_mfma_f32_16x16x32_bf16 v[4:7], v[208:211], v[246:249], v[4:7]
	ds_read_b128 v[208:211], v182 offset:43776
	s_branch .Lgm0_main

; DI f32x4 mfma16(bf16x8 a, bf16x8 b, f32x4 c) { return __builtin_amdgcn_mfma_f32_16x16x32_bf16(a, b, c, 0, 0, 0); }
; template <int MI, int NJ, bool SWAP, class AP, class BP>
; DI void gemm_main(f32x4 (&acc)[MI][NJ], const AP& ap, int a_kstep, const BP& bp, int b_kstep, int nk, bf16_t* smem) {
;     ...
;   auto gload = [&](int kt) {
;     const bf16_t* ab = ap.base + (size_t)kt * a_kstep; const bf16_t* bb = bp.base + (size_t)kt * b_kstep;
; #pragma unroll
;     for (int i = 0; i < CA; ++i) ra[i] = *(const u32x4*)(ab + pa[i]);
; #pragma unroll
;     for (int i = 0; i < CB; ++i) rb[i] = *(const u32x4*)(bb + pb[i]);
;   };
;   auto sstore = [&](int buf) {
;     bf16_t* As = smem + buf * L::STAGE; bf16_t* Bs = As + L::A_ELEMS;
; #pragma unroll
;     for (int i = 0; i < CA; ++i) { const int c = tid + NTHR * i; *(u32x4*)(As + (c >> 3) * LDT + (c & 7) * 8) = oka[i] ? ra[i] : (u32x4){0u, 0u, 0u, 0u}; }
; #pragma unroll
;     for (int i = 0; i < CB; ++i) { const int c = tid + NTHR * i; *(u32x4*)(Bs + (c >> 3) * LDT + (c & 7) * 8) = rb[i]; }
;   };
;   gload(0); sstore(0); gload(nk > 1 ? 1 : 0); __syncthreads();
; #pragma unroll 1
;   for (int kt = 0; kt < nk; ++kt) {
;     const int buf = kt & 1;
;     sstore(buf ^ 1);
;     gload(kt + 2 < nk ? kt + 2 : nk - 1);
;     __builtin_amdgcn_sched_barrier(0);
;     const bf16_t* As = smem + buf * L::STAGE + (wm * 16 * MI + l15) * LDT + quad * 8;
;     const bf16_t* Bs = smem + buf * L::STAGE + L::A_ELEMS + (wn * 16 * NJ + l15) * LDT + quad * 8;
; #pragma unroll
;     for (int ks = 0; ks < 2; ++ks) {
;       if (MI * NJ >= 32 && ks == 1) asm volatile("" ::: "memory");
;       bf16x8 b[NJ];
; #pragma unroll
;       for (int j = 0; j < NJ; ++j) b[j] = *(const bf16x8*)(Bs + j * 16 * LDT + ks * 32);
; #pragma unroll
;       for (int i = 0; i < MI; ++i) {
;         const bf16x8 a = *(const bf16x8*)(As + i * 16 * LDT + ks * 32);
; #pragma unroll
;         for (int j = 0; j < NJ; ++j) acc[i][j] = SWAP ? mfma16(b[j], a, acc[i][j]) : mfma16(a, b[j], acc[i][j]);
;       }
;     }
;     __syncthreads();
;   }
.Lgm1_main:
	ds_read_b128 v[242:245], v176 offset:4608
	s_waitcnt lgkmcnt(4)
	v_mfma_f32_16x16x32_bf16 v[124:127], v[212:215], v[178:181], v[124:127]
	s_waitcnt lgkmcnt(3)
	v_mfma_f32_16x16x32_bf16 v[120:123], v[212:215], v[200:203], v[120:123]
	s_waitcnt lgkmcnt(2)
	v_mfma_f32_16x16x32_bf16 v[116:119], v[212:215], v[204:207], v[116:119]
	v_lshlrev_b32_e32 v250, 1, v168
	s_and_b32 s5, s4, 1
	s_min_u32 s6, s4, 13
	s_xor_b32 s7, s5, 1
	s_mul_i32 s7, s7, 0x12000
	v_add3_u32 v250, s7, v250, v170
	s_waitcnt vmcnt(7)
	ds_write_b128 v250, v[128:131]
	s_waitcnt lgkmcnt(2)
	v_mfma_f32_16x16x32_bf16 v[112:115], v[212:215], v[208:211], v[112:115]
	ds_read_b128 v[246:249], v176 offset:6912
	v_mfma_f32_16x16x32_bf16 v[108:111], v[216:219], v[178:181], v[108:111]
	s_lshl_b32 s33, s6, 7
	s_add_u32 s6, s0, s33
	v_lshlrev_b32_e32 v251, 1, v171
	v_add3_u32 v251, s7, v251, v170
	v_lshlrev_b32_e32 v252, 1, v172
	v_add3_u32 v252, s7, v252, v170
	v_lshlrev_b32_e32 v253, 1, v173
	v_add3_u32 v253, s7, v253, v170
	s_addc_u32 s7, s1, 0
	v_lshl_add_u64 v[128:129], s[6:7], 0, v[160:161]
	s_nop 0
	global_load_dwordx4 v[128:131], v[128:129], off offset:256
	v_mfma_f32_16x16x32_bf16 v[104:107], v[216:219], v[200:203], v[104:107]
	v_mfma_f32_16x16x32_bf16 v[100:103], v[216:219], v[204:207], v[100:103]
	v_mfma_f32_16x16x32_bf16 v[96:99], v[216:219], v[208:211], v[96:99]
	ds_read_b128 v[212:215], v176 offset:9216
	s_waitcnt lgkmcnt(3)
	v_mfma_f32_16x16x32_bf16 v[92:95], v[242:245], v[178:181], v[92:95]
	s_waitcnt vmcnt(7)
	ds_write_b128 v251, v[132:135]
	v_mfma_f32_16x16x32_bf16 v[88:91], v[242:245], v[200:203], v[88:91]
	v_mfma_f32_16x16x32_bf16 v[84:87], v[242:245], v[204:207], v[84:87]
	v_lshl_add_u64 v[132:133], s[6:7], 0, v[162:163]
	s_nop 0
	global_load_dwordx4 v[132:135], v[132:133], off offset:256
	v_mfma_f32_16x16x32_bf16 v[80:83], v[242:245], v[208:211], v[80:83]
	ds_read_b128 v[216:219], v176 offset:11520
	s_waitcnt lgkmcnt(3)
	v_mfma_f32_16x16x32_bf16 v[76:79], v[246:249], v[178:181], v[76:79]
	v_mfma_f32_16x16x32_bf16 v[72:75], v[246:249], v[200:203], v[72:75]
	v_mfma_f32_16x16x32_bf16 v[68:71], v[246:249], v[204:207], v[68:71]
	s_waitcnt vmcnt(7)
	ds_write_b128 v252, v[136:139]
	v_mfma_f32_16x16x32_bf16 v[64:67], v[246:249], v[208:211], v[64:67]
	ds_read_b128 v[242:245], v176 offset:13824
	s_waitcnt lgkmcnt(4)
	v_mfma_f32_16x16x32_bf16 v[60:63], v[212:215], v[178:181], v[60:63]
	v_lshl_add_u64 v[136:137], s[6:7], 0, v[164:165]
	s_nop 0
	global_load_dwordx4 v[136:139], v[136:137], off offset:256
	v_mfma_f32_16x16x32_bf16 v[56:59], v[212:215], v[200:203], v[56:59]
	v_mfma_f32_16x16x32_bf16 v[52:55], v[212:215], v[204:207], v[52:55]
	v_mfma_f32_16x16x32_bf16 v[48:51], v[212:215], v[208:211], v[48:51]
	ds_read_b128 v[246:249], v176 offset:16128
	s_waitcnt lgkmcnt(3)
	v_mfma_f32_16x16x32_bf16 v[44:47], v[216:219], v[178:181], v[44:47]
	s_waitcnt vmcnt(7)
	ds_write_b128 v253, v[140:143]
	v_mfma_f32_16x16x32_bf16 v[40:43], v[216:219], v[200:203], v[40:43]
	v_mfma_f32_16x16x32_bf16 v[36:39], v[216:219], v[204:207], v[36:39]
	v_lshl_add_u64 v[140:141], s[6:7], 0, v[166:167]
	s_nop 0
	global_load_dwordx4 v[140:143], v[140:141], off offset:256
	v_mfma_f32_16x16x32_bf16 v[32:35], v[216:219], v[208:211], v[32:35]
	ds_read_b128 v[212:215], v176 offset:64
	s_waitcnt lgkmcnt(3)
	v_mfma_f32_16x16x32_bf16 v[28:31], v[242:245], v[178:181], v[28:31]
	v_mfma_f32_16x16x32_bf16 v[24:27], v[242:245], v[200:203], v[24:27]
	v_mfma_f32_16x16x32_bf16 v[20:23], v[242:245], v[204:207], v[20:23]
	s_waitcnt vmcnt(7)
	ds_write_b128 v250, v[144:147] offset:36864
	v_mfma_f32_16x16x32_bf16 v[16:19], v[242:245], v[208:211], v[16:19]
	ds_read_b128 v[216:219], v176 offset:2368
	s_waitcnt lgkmcnt(4)
	v_mfma_f32_16x16x32_bf16 v[8:11], v[246:249], v[178:181], v[8:11]
	ds_read_b128 v[178:181], v182 offset:36928
	s_add_u32 s6, s2, s33
	s_addc_u32 s7, s3, 0
	v_lshl_add_u64 v[144:145], s[6:7], 0, v[160:161]
	s_nop 0
	global_load_dwordx4 v[144:147], v[144:145], off offset:256
	v_mfma_f32_16x16x32_bf16 v[4:7], v[246:249], v[200:203], v[4:7]
	ds_read_b128 v[200:203], v182 offset:39232
	v_mfma_f32_16x16x32_bf16 v[0:3], v[246:249], v[204:207], v[0:3]
	ds_read_b128 v[204:207], v182 offset:41536
	v_mfma_f32_16x16x32_bf16 v[12:15], v[246:249], v[208:211], v[12:15]
	ds_read_b128 v[208:211], v182 offset:43840
	ds_read_b128 v[242:245], v176 offset:4672
	s_waitcnt lgkmcnt(4)
	v_mfma_f32_16x16x32_bf16 v[124:127], v[212:215], v[178:181], v[124:127]
	s_waitcnt vmcnt(7)
	ds_write_b128 v251, v[148:151] offset:36864
	s_waitcnt lgkmcnt(4)
	v_mfma_f32_16x16x32_bf16 v[120:123], v[212:215], v[200:203], v[120:123]
	s_waitcnt lgkmcnt(3)
	v_mfma_f32_16x16x32_bf16 v[116:119], v[212:215], v[204:207], v[116:119]
	v_lshl_add_u64 v[148:149], s[6:7], 0, v[162:163]
	s_nop 0
	global_load_dwordx4 v[148:151], v[148:149], off offset:256
	s_waitcnt lgkmcnt(2)
	v_mfma_f32_16x16x32_bf16 v[112:115], v[212:215], v[208:211], v[112:115]
	ds_read_b128 v[246:249], v176 offset:6976
	v_mfma_f32_16x16x32_bf16 v[108:111], v[216:219], v[178:181], v[108:111]
	v_mfma_f32_16x16x32_bf16 v[104:107], v[216:219], v[200:203], v[104:107]
	v_mfma_f32_16x16x32_bf16 v[100:103], v[216:219], v[204:207], v[100:103]
	s_waitcnt vmcnt(7)
	ds_write_b128 v252, v[152:155] offset:36864
	v_mfma_f32_16x16x32_bf16 v[96:99], v[216:219], v[208:211], v[96:99]
	ds_read_b128 v[212:215], v176 offset:9280
	s_waitcnt lgkmcnt(4)
	v_mfma_f32_16x16x32_bf16 v[92:95], v[242:245], v[178:181], v[92:95]
	v_lshl_add_u64 v[152:153], s[6:7], 0, v[164:165]
	s_nop 0
	global_load_dwordx4 v[152:155], v[152:153], off offset:256
	v_mfma_f32_16x16x32_bf16 v[88:91], v[242:245], v[200:203], v[88:91]
	v_mfma_f32_16x16x32_bf16 v[84:87], v[242:245], v[204:207], v[84:87]
	v_mfma_f32_16x16x32_bf16 v[80:83], v[242:245], v[208:211], v[80:83]
	ds_read_b128 v[216:219], v176 offset:11584
	s_waitcnt lgkmcnt(3)
	v_mfma_f32_16x16x32_bf16 v[76:79], v[246:249], v[178:181], v[76:79]
	s_waitcnt vmcnt(7)
	ds_write_b128 v253, v[156:159] offset:36864
	v_mfma_f32_16x16x32_bf16 v[72:75], v[246:249], v[200:203], v[72:75]
	v_mfma_f32_16x16x32_bf16 v[68:71], v[246:249], v[204:207], v[68:71]
	v_lshl_add_u64 v[156:157], s[6:7], 0, v[166:167]
	s_nop 0
	global_load_dwordx4 v[156:159], v[156:157], off offset:256
	v_mfma_f32_16x16x32_bf16 v[64:67], v[246:249], v[208:211], v[64:67]
	ds_read_b128 v[242:245], v176 offset:13888
	s_waitcnt lgkmcnt(3)
	v_mfma_f32_16x16x32_bf16 v[60:63], v[212:215], v[178:181], v[60:63]
	v_mfma_f32_16x16x32_bf16 v[56:59], v[212:215], v[200:203], v[56:59]
	v_mfma_f32_16x16x32_bf16 v[52:55], v[212:215], v[204:207], v[52:55]
	v_mfma_f32_16x16x32_bf16 v[48:51], v[212:215], v[208:211], v[48:51]
	ds_read_b128 v[246:249], v176 offset:16192
	s_waitcnt lgkmcnt(3)
	v_mfma_f32_16x16x32_bf16 v[44:47], v[216:219], v[178:181], v[44:47]
	v_mfma_f32_16x16x32_bf16 v[40:43], v[216:219], v[200:203], v[40:43]
	v_mfma_f32_16x16x32_bf16 v[36:39], v[216:219], v[204:207], v[36:39]
	v_mfma_f32_16x16x32_bf16 v[32:35], v[216:219], v[208:211], v[32:35]
	s_waitcnt lgkmcnt(0)
	s_barrier
; DI f32x4 mfma16(bf16x8 a, bf16x8 b, f32x4 c) { return __builtin_amdgcn_mfma_f32_16x16x32_bf16(a, b, c, 0, 0, 0); }
; template <int MI, int NJ, bool SWAP, class AP, class BP>
; DI void gemm_main(f32x4 (&acc)[MI][NJ], const AP& ap, int a_kstep, const BP& bp, int b_kstep, int nk, bf16_t* smem) {
;     ...
;   for (int kt = 0; kt < nk; ++kt) {
;     const int buf = kt & 1;
;     sstore(buf ^ 1);
;     gload(kt + 2 < nk ? kt + 2 : nk - 1);
;     __builtin_amdgcn_sched_barrier(0);
;     const bf16_t* As = smem + buf * L::STAGE + (wm * 16 * MI + l15) * LDT + quad * 8;
;     const bf16_t* Bs = smem + buf * L::STAGE + L::A_ELEMS + (wn * 16 * NJ + l15) * LDT + quad * 8;
; #pragma unroll
;     for (int ks = 0; ks < 2; ++ks) {
;       if (MI * NJ >= 32 && ks == 1) asm volatile("" ::: "memory");
;       bf16x8 b[NJ];
; #pragma unroll
;       for (int j = 0; j < NJ; ++j) b[j] = *(const bf16x8*)(Bs + j * 16 * LDT + ks * 32);
; #pragma unroll
;       for (int i = 0; i < MI; ++i) {
;         const bf16x8 a = *(const bf16x8*)(As + i * 16 * LDT + ks * 32);
; #pragma unroll
;         for (int j = 0; j < NJ; ++j) acc[i][j] = SWAP ? mfma16(b[j], a, acc[i][j]) : mfma16(a, b[j], acc[i][j]);
;       }
;     }
;     __syncthreads();
;   }
	s_add_i32 s4, s4, 1
	s_cmp_lg_u32 s4, 16
	s_cbranch_scc0 .Lgm1_exit
	s_and_b32 s98, s4, 1
	s_mul_i32 s98, s98, 0x12000
	v_add3_u32 v176, s98, v174, v175
	v_add3_u32 v182, s98, v169, v175
	ds_read_b128 v[212:215], v176
	ds_read_b128 v[216:219], v176 offset:2304
	v_mfma_f32_16x16x32_bf16 v[28:31], v[242:245], v[178:181], v[28:31]
	v_mfma_f32_16x16x32_bf16 v[8:11], v[246:249], v[178:181], v[8:11]
	ds_read_b128 v[178:181], v182 offset:36864
	v_mfma_f32_16x16x32_bf16 v[24:27], v[242:245], v[200:203], v[24:27]
	v_mfma_f32_16x16x32_bf16 v[4:7], v[246:249], v[200:203], v[4:7]
	ds_read_b128 v[200:203], v182 offset:39168
	v_mfma_f32_16x16x32_bf16 v[20:23], v[242:245], v[204:207], v[20:23]
	v_mfma_f32_16x16x32_bf16 v[0:3], v[246:249], v[204:207], v[0:3]
	ds_read_b128 v[204:207], v182 offset:41472
	v_mfma_f32_16x16x32_bf16 v[16:19], v[242:245], v[208:211], v[16:19]
	v_mfma_f32_16x16x32_bf16 v[12:15], v[246:249], v[208:211], v[12:15]
	ds_read_b128 v[208:211], v182 offset:43776
	s_branch .Lgm1_main

; DI f32x4 mfma16(bf16x8 a, bf16x8 b, f32x4 c) { return __builtin_amdgcn_mfma_f32_16x16x32_bf16(a, b, c, 0, 0, 0); }
; template <int MI, int NJ, bool SWAP, class AP, class BP>
; DI void gemm_main(f32x4 (&acc)[MI][NJ], const AP& ap, int a_kstep, const BP& bp, int b_kstep, int nk, bf16_t* smem) {
;     ...
;   auto gload = [&](int kt) {
;     const bf16_t* ab = ap.base + (size_t)kt * a_kstep; const bf16_t* bb = bp.base + (size_t)kt * b_kstep;
; #pragma unroll
;     for (int i = 0; i < CA; ++i) ra[i] = *(const u32x4*)(ab + pa[i]);
; #pragma unroll
;     for (int i = 0; i < CB; ++i) rb[i] = *(const u32x4*)(bb + pb[i]);
;   };
;   auto sstore = [&](int buf) {
;     bf16_t* As = smem + buf * L::STAGE; bf16_t* Bs = As + L::A_ELEMS;
; #pragma unroll
;     for (int i = 0; i < CA; ++i) { const int c = tid + NTHR * i; *(u32x4*)(As + (c >> 3) * LDT + (c & 7) * 8) = oka[i] ? ra[i] : (u32x4){0u, 0u, 0u, 0u}; }
; #pragma unroll
;     for (int i = 0; i < CB; ++i) { const int c = tid + NTHR * i; *(u32x4*)(Bs + (c >> 3) * LDT + (c & 7) * 8) = rb[i]; }
;   };
;   gload(0); sstore(0); gload(nk > 1 ? 1 : 0); __syncthreads();
; #pragma unroll 1
;   for (int kt = 0; kt < nk; ++kt) {
;     const int buf = kt & 1;
;     sstore(buf ^ 1);
;     gload(kt + 2 < nk ? kt + 2 : nk - 1);
;     __builtin_amdgcn_sched_barrier(0);
;     const bf16_t* As = smem + buf * L::STAGE + (wm * 16 * MI + l15) * LDT + quad * 8;
;     const bf16_t* Bs = smem + buf * L::STAGE + L::A_ELEMS + (wn * 16 * NJ + l15) * LDT + quad * 8;
; #pragma unroll
;     for (int ks = 0; ks < 2; ++ks) {
;       if (MI * NJ >= 32 && ks == 1) asm volatile("" ::: "memory");
;       bf16x8 b[NJ];
; #pragma unroll
;       for (int j = 0; j < NJ; ++j) b[j] = *(const bf16x8*)(Bs + j * 16 * LDT + ks * 32);
; #pragma unroll
;       for (int i = 0; i < MI; ++i) {
;         const bf16x8 a = *(const bf16x8*)(As + i * 16 * LDT + ks * 32);
; #pragma unroll
;         for (int j = 0; j < NJ; ++j) acc[i][j] = SWAP ? mfma16(b[j], a, acc[i][j]) : mfma16(a, b[j], acc[i][j]);
;       }
;     }
;     __syncthreads();
;   }
.Lgm2_main:
	ds_read_b128 v[242:245], v182 offset:4608
	s_waitcnt lgkmcnt(4)
	v_mfma_f32_16x16x32_bf16 v[156:159], v[178:181], v[198:201], v[156:159]
	s_waitcnt lgkmcnt(3)
	v_mfma_f32_16x16x32_bf16 v[152:155], v[186:189], v[198:201], v[152:155]
	s_waitcnt lgkmcnt(2)
	v_mfma_f32_16x16x32_bf16 v[148:151], v[190:193], v[198:201], v[148:151]
	s_and_b32 s33, s16, 1
	s_min_u32 s52, s16, 3
	s_xor_b32 s53, s33, 1
	s_mul_i32 s53, s53, 0x12000
	v_add3_u32 v250, s53, v173, v171
	s_waitcnt vmcnt(7)
	ds_write_b128 v250, v[112:115]
	s_waitcnt lgkmcnt(2)
	v_mfma_f32_16x16x32_bf16 v[144:147], v[194:197], v[198:201], v[144:147]
	ds_read_b128 v[246:249], v182 offset:6912
	v_mfma_f32_16x16x32_bf16 v[108:111], v[178:181], v[202:205], v[108:111]
	s_lshl_b32 s54, s52, 7
	s_add_u32 s52, s0, s54
	v_add3_u32 v251, s53, v174, v171
	v_add3_u32 v252, s53, v175, v171
	v_add3_u32 v253, s53, v176, v171
	s_addc_u32 s53, s1, 0
	v_lshl_add_u64 v[112:113], s[52:53], 0, v[162:163]
	s_nop 0
	global_load_dwordx4 v[112:115], v[112:113], off offset:256
	v_mfma_f32_16x16x32_bf16 v[104:107], v[186:189], v[202:205], v[104:107]
	v_mfma_f32_16x16x32_bf16 v[100:103], v[190:193], v[202:205], v[100:103]
	v_mfma_f32_16x16x32_bf16 v[96:99], v[194:197], v[202:205], v[96:99]
	ds_read_b128 v[198:201], v182 offset:9216
	s_waitcnt lgkmcnt(3)
	v_mfma_f32_16x16x32_bf16 v[92:95], v[178:181], v[242:245], v[92:95]
	s_waitcnt vmcnt(6)
	ds_write_b128 v251, v[116:119]
	v_mfma_f32_16x16x32_bf16 v[88:91], v[186:189], v[242:245], v[88:91]
	v_mfma_f32_16x16x32_bf16 v[84:87], v[190:193], v[242:245], v[84:87]
	v_lshl_add_u64 v[116:117], s[52:53], 0, v[164:165]
	s_nop 0
	global_load_dwordx4 v[116:119], v[116:117], off offset:256
	v_mfma_f32_16x16x32_bf16 v[80:83], v[194:197], v[242:245], v[80:83]
	ds_read_b128 v[202:205], v182 offset:11520
	s_waitcnt lgkmcnt(3)
	v_mfma_f32_16x16x32_bf16 v[76:79], v[178:181], v[246:249], v[76:79]
	v_mfma_f32_16x16x32_bf16 v[72:75], v[186:189], v[246:249], v[72:75]
	v_mfma_f32_16x16x32_bf16 v[68:71], v[190:193], v[246:249], v[68:71]
	s_waitcnt vmcnt(6)
	ds_write_b128 v252, v[120:123]
	v_mfma_f32_16x16x32_bf16 v[64:67], v[194:197], v[246:249], v[64:67]
	ds_read_b128 v[242:245], v182 offset:13824
	s_waitcnt lgkmcnt(4)
	v_mfma_f32_16x16x32_bf16 v[60:63], v[178:181], v[198:201], v[60:63]
	v_lshl_add_u64 v[120:121], s[52:53], 0, v[166:167]
	s_nop 0
	global_load_dwordx4 v[120:123], v[120:121], off offset:256
	v_mfma_f32_16x16x32_bf16 v[56:59], v[186:189], v[198:201], v[56:59]
	v_mfma_f32_16x16x32_bf16 v[52:55], v[190:193], v[198:201], v[52:55]
	v_mfma_f32_16x16x32_bf16 v[48:51], v[194:197], v[198:201], v[48:51]
	ds_read_b128 v[246:249], v182 offset:16128
	s_waitcnt lgkmcnt(3)
	v_mfma_f32_16x16x32_bf16 v[44:47], v[178:181], v[202:205], v[44:47]
	s_waitcnt vmcnt(6)
	ds_write_b128 v253, v[124:127]
	v_mfma_f32_16x16x32_bf16 v[40:43], v[186:189], v[202:205], v[40:43]
	v_mfma_f32_16x16x32_bf16 v[36:39], v[190:193], v[202:205], v[36:39]
	v_lshl_add_u64 v[124:125], s[52:53], 0, v[168:169]
	s_nop 0
	global_load_dwordx4 v[124:127], v[124:125], off offset:256
	v_mfma_f32_16x16x32_bf16 v[32:35], v[194:197], v[202:205], v[32:35]
	ds_read_b128 v[198:201], v182 offset:64
	s_waitcnt lgkmcnt(3)
	v_mfma_f32_16x16x32_bf16 v[28:31], v[178:181], v[242:245], v[28:31]
	v_mfma_f32_16x16x32_bf16 v[24:27], v[186:189], v[242:245], v[24:27]
	v_mfma_f32_16x16x32_bf16 v[20:23], v[190:193], v[242:245], v[20:23]
	ds_write_b128 v250, v[128:131] offset:36864
	v_mfma_f32_16x16x32_bf16 v[16:19], v[194:197], v[242:245], v[16:19]
	ds_read_b128 v[202:205], v182 offset:2368
	s_waitcnt lgkmcnt(4)
	v_mfma_f32_16x16x32_bf16 v[8:11], v[178:181], v[246:249], v[8:11]
	ds_read_b128 v[178:181], v183 offset:36928
	s_add_u32 s52, s2, s54
	s_addc_u32 s53, s3, 0
	v_lshl_add_u64 v[128:129], s[52:53], 0, v[162:163]
	s_nop 0
	global_load_dwordx4 v[128:131], v[128:129], off offset:256
	v_mfma_f32_16x16x32_bf16 v[4:7], v[186:189], v[246:249], v[4:7]
	ds_read_b128 v[186:189], v183 offset:39232
	v_mfma_f32_16x16x32_bf16 v[0:3], v[190:193], v[246:249], v[0:3]
	ds_read_b128 v[190:193], v183 offset:41536
	v_mfma_f32_16x16x32_bf16 v[12:15], v[194:197], v[246:249], v[12:15]
	ds_read_b128 v[194:197], v183 offset:43840
	ds_read_b128 v[242:245], v182 offset:4672
	s_waitcnt lgkmcnt(4)
	v_mfma_f32_16x16x32_bf16 v[156:159], v[178:181], v[198:201], v[156:159]
	s_waitcnt vmcnt(7)
	ds_write_b128 v251, v[132:135] offset:36864
	s_waitcnt lgkmcnt(4)
	v_mfma_f32_16x16x32_bf16 v[152:155], v[186:189], v[198:201], v[152:155]
	s_waitcnt lgkmcnt(3)
	v_mfma_f32_16x16x32_bf16 v[148:151], v[190:193], v[198:201], v[148:151]
	v_lshl_add_u64 v[132:133], s[52:53], 0, v[164:165]
	s_nop 0
	global_load_dwordx4 v[132:135], v[132:133], off offset:256
	s_waitcnt lgkmcnt(2)
	v_mfma_f32_16x16x32_bf16 v[144:147], v[194:197], v[198:201], v[144:147]
	ds_read_b128 v[246:249], v182 offset:6976
	v_mfma_f32_16x16x32_bf16 v[108:111], v[178:181], v[202:205], v[108:111]
	v_mfma_f32_16x16x32_bf16 v[104:107], v[186:189], v[202:205], v[104:107]
	v_mfma_f32_16x16x32_bf16 v[100:103], v[190:193], v[202:205], v[100:103]
	s_waitcnt vmcnt(7)
	ds_write_b128 v252, v[136:139] offset:36864
	v_mfma_f32_16x16x32_bf16 v[96:99], v[194:197], v[202:205], v[96:99]
	ds_read_b128 v[198:201], v182 offset:9280
	s_waitcnt lgkmcnt(4)
	v_mfma_f32_16x16x32_bf16 v[92:95], v[178:181], v[242:245], v[92:95]
	v_lshl_add_u64 v[136:137], s[52:53], 0, v[166:167]
	s_nop 0
	global_load_dwordx4 v[136:139], v[136:137], off offset:256
	v_mfma_f32_16x16x32_bf16 v[88:91], v[186:189], v[242:245], v[88:91]
	v_mfma_f32_16x16x32_bf16 v[84:87], v[190:193], v[242:245], v[84:87]
	v_mfma_f32_16x16x32_bf16 v[80:83], v[194:197], v[242:245], v[80:83]
	ds_read_b128 v[202:205], v182 offset:11584
	s_waitcnt lgkmcnt(3)
	v_mfma_f32_16x16x32_bf16 v[76:79], v[178:181], v[246:249], v[76:79]
	s_waitcnt vmcnt(7)
	ds_write_b128 v253, v[140:143] offset:36864
	v_mfma_f32_16x16x32_bf16 v[72:75], v[186:189], v[246:249], v[72:75]
	v_mfma_f32_16x16x32_bf16 v[68:71], v[190:193], v[246:249], v[68:71]
	v_lshl_add_u64 v[140:141], s[52:53], 0, v[168:169]
	s_nop 0
	global_load_dwordx4 v[140:143], v[140:141], off offset:256
	v_mfma_f32_16x16x32_bf16 v[64:67], v[194:197], v[246:249], v[64:67]
	ds_read_b128 v[242:245], v182 offset:13888
	s_waitcnt lgkmcnt(3)
	v_mfma_f32_16x16x32_bf16 v[60:63], v[178:181], v[198:201], v[60:63]
	v_mfma_f32_16x16x32_bf16 v[56:59], v[186:189], v[198:201], v[56:59]
	v_mfma_f32_16x16x32_bf16 v[52:55], v[190:193], v[198:201], v[52:55]
	v_mfma_f32_16x16x32_bf16 v[48:51], v[194:197], v[198:201], v[48:51]
	ds_read_b128 v[246:249], v182 offset:16192
	s_waitcnt lgkmcnt(3)
	v_mfma_f32_16x16x32_bf16 v[44:47], v[178:181], v[202:205], v[44:47]
	v_mfma_f32_16x16x32_bf16 v[40:43], v[186:189], v[202:205], v[40:43]
	v_mfma_f32_16x16x32_bf16 v[36:39], v[190:193], v[202:205], v[36:39]
	v_mfma_f32_16x16x32_bf16 v[32:35], v[194:197], v[202:205], v[32:35]
	s_waitcnt lgkmcnt(0)
	s_barrier
; DI f32x4 mfma16(bf16x8 a, bf16x8 b, f32x4 c) { return __builtin_amdgcn_mfma_f32_16x16x32_bf16(a, b, c, 0, 0, 0); }
; template <int MI, int NJ, bool SWAP, class AP, class BP>
; DI void gemm_main(f32x4 (&acc)[MI][NJ], const AP& ap, int a_kstep, const BP& bp, int b_kstep, int nk, bf16_t* smem) {
;     ...
;   for (int kt = 0; kt < nk; ++kt) {
;     const int buf = kt & 1;
;     sstore(buf ^ 1);
;     gload(kt + 2 < nk ? kt + 2 : nk - 1);
;     __builtin_amdgcn_sched_barrier(0);
;     const bf16_t* As = smem + buf * L::STAGE + (wm * 16 * MI + l15) * LDT + quad * 8;
;     const bf16_t* Bs = smem + buf * L::STAGE + L::A_ELEMS + (wn * 16 * NJ + l15) * LDT + quad * 8;
; #pragma unroll
;     for (int ks = 0; ks < 2; ++ks) {
;       if (MI * NJ >= 32 && ks == 1) asm volatile("" ::: "memory");
;       bf16x8 b[NJ];
; #pragma unroll
;       for (int j = 0; j < NJ; ++j) b[j] = *(const bf16x8*)(Bs + j * 16 * LDT + ks * 32);
; #pragma unroll
;       for (int i = 0; i < MI; ++i) {
;         const bf16x8 a = *(const bf16x8*)(As + i * 16 * LDT + ks * 32);
; #pragma unroll
;         for (int j = 0; j < NJ; ++j) acc[i][j] = SWAP ? mfma16(b[j], a, acc[i][j]) : mfma16(a, b[j], acc[i][j]);
;       }
;     }
;     __syncthreads();
;   }
	s_add_i32 s16, s16, 1
	s_cmp_lg_u32 s16, 6
	s_cbranch_scc0 .Lgm2_exit
	s_and_b32 s98, s16, 1
	s_mul_i32 s98, s98, 0x12000
	v_add3_u32 v183, s98, v160, v177
	v_add3_u32 v182, s98, v172, v177
	ds_read_b128 v[198:201], v182
	ds_read_b128 v[202:205], v182 offset:2304
	v_mfma_f32_16x16x32_bf16 v[28:31], v[178:181], v[242:245], v[28:31]
	v_mfma_f32_16x16x32_bf16 v[8:11], v[178:181], v[246:249], v[8:11]
	ds_read_b128 v[178:181], v183 offset:36864
	v_mfma_f32_16x16x32_bf16 v[24:27], v[186:189], v[242:245], v[24:27]
	v_mfma_f32_16x16x32_bf16 v[4:7], v[186:189], v[246:249], v[4:7]
	ds_read_b128 v[186:189], v183 offset:39168
	v_mfma_f32_16x16x32_bf16 v[20:23], v[190:193], v[242:245], v[20:23]
	v_mfma_f32_16x16x32_bf16 v[0:3], v[190:193], v[246:249], v[0:3]
	ds_read_b128 v[190:193], v183 offset:41472
	v_mfma_f32_16x16x32_bf16 v[16:19], v[194:197], v[242:245], v[16:19]
	v_mfma_f32_16x16x32_bf16 v[12:15], v[194:197], v[246:249], v[12:15]
	ds_read_b128 v[194:197], v183 offset:43776
	s_branch .Lgm2_main

; DI f32x4 mfma16(bf16x8 a, bf16x8 b, f32x4 c) { return __builtin_amdgcn_mfma_f32_16x16x32_bf16(a, b, c, 0, 0, 0); }
; template <int MI, int NJ, bool SWAP, class AP, class BP>
; DI void gemm_main(f32x4 (&acc)[MI][NJ], const AP& ap, int a_kstep, const BP& bp, int b_kstep, int nk, bf16_t* smem) {
;     ...
;   auto gload = [&](int kt) {
;     const bf16_t* ab = ap.base + (size_t)kt * a_kstep; const bf16_t* bb = bp.base + (size_t)kt * b_kstep;
; #pragma unroll
;     for (int i = 0; i < CA; ++i) ra[i] = *(const u32x4*)(ab + pa[i]);
; #pragma unroll
;     for (int i = 0; i < CB; ++i) rb[i] = *(const u32x4*)(bb + pb[i]);
;   };
;   auto sstore = [&](int buf) {
;     bf16_t* As = smem + buf * L::STAGE; bf16_t* Bs = As + L::A_ELEMS;
; #pragma unroll
;     for (int i = 0; i < CA; ++i) { const int c = tid + NTHR * i; *(u32x4*)(As + (c >> 3) * LDT + (c & 7) * 8) = oka[i] ? ra[i] : (u32x4){0u, 0u, 0u, 0u}; }
; #pragma unroll
;     for (int i = 0; i < CB; ++i) { const int c = tid + NTHR * i; *(u32x4*)(Bs + (c >> 3) * LDT + (c & 7) * 8) = rb[i]; }
;   };
;   gload(0); sstore(0); gload(nk > 1 ? 1 : 0); __syncthreads();
; #pragma unroll 1
;   for (int kt = 0; kt < nk; ++kt) {
;     const int buf = kt & 1;
;     sstore(buf ^ 1);
;     gload(kt + 2 < nk ? kt + 2 : nk - 1);
;     __builtin_amdgcn_sched_barrier(0);
;     const bf16_t* As = smem + buf * L::STAGE + (wm * 16 * MI + l15) * LDT + quad * 8;
;     const bf16_t* Bs = smem + buf * L::STAGE + L::A_ELEMS + (wn * 16 * NJ + l15) * LDT + quad * 8;
; #pragma unroll
;     for (int ks = 0; ks < 2; ++ks) {
;       if (MI * NJ >= 32 && ks == 1) asm volatile("" ::: "memory");
;       bf16x8 b[NJ];
; #pragma unroll
;       for (int j = 0; j < NJ; ++j) b[j] = *(const bf16x8*)(Bs + j * 16 * LDT + ks * 32);
; #pragma unroll
;       for (int i = 0; i < MI; ++i) {
;         const bf16x8 a = *(const bf16x8*)(As + i * 16 * LDT + ks * 32);
; #pragma unroll
;         for (int j = 0; j < NJ; ++j) acc[i][j] = SWAP ? mfma16(b[j], a, acc[i][j]) : mfma16(a, b[j], acc[i][j]);
;       }
;     }
;     __syncthreads();
;   }
.Lgm3_main:
	ds_read_b128 v[242:245], v182 offset:4608
	s_waitcnt lgkmcnt(4)
	v_mfma_f32_16x16x32_bf16 v[156:159], v[178:181], v[198:201], v[156:159]
	s_waitcnt lgkmcnt(3)
	v_mfma_f32_16x16x32_bf16 v[152:155], v[186:189], v[198:201], v[152:155]
	s_waitcnt lgkmcnt(2)
	v_mfma_f32_16x16x32_bf16 v[148:151], v[190:193], v[198:201], v[148:151]
	v_lshlrev_b32_e32 v250, 1, v160
	s_and_b32 s54, s33, 1
	s_xor_b32 s52, s54, 1
	s_mul_i32 s52, s52, 0x12000
	v_add3_u32 v250, s52, v250, v172
	s_waitcnt vmcnt(7)
	ds_write_b128 v250, v[112:115]
	s_waitcnt lgkmcnt(2)
	v_mfma_f32_16x16x32_bf16 v[144:147], v[194:197], v[198:201], v[144:147]
	ds_read_b128 v[246:249], v182 offset:6912
	v_mfma_f32_16x16x32_bf16 v[108:111], v[178:181], v[202:205], v[108:111]
	s_cmp_eq_u32 s33, 0
	s_cselect_b32 s55, s48, 0x180
	v_lshlrev_b32_e32 v251, 1, v173
	v_add3_u32 v251, s52, v251, v172
	v_lshlrev_b32_e32 v252, 1, v174
	v_add3_u32 v252, s52, v252, v172
	v_lshlrev_b32_e32 v253, 1, v175
	v_add3_u32 v253, s52, v253, v172
	s_add_u32 s52, s0, s55
	s_addc_u32 s53, s1, 0
	v_lshl_add_u64 v[112:113], s[52:53], 0, v[162:163]
	s_nop 0
	global_load_dwordx4 v[112:115], v[112:113], off
	v_mfma_f32_16x16x32_bf16 v[104:107], v[186:189], v[202:205], v[104:107]
	v_mfma_f32_16x16x32_bf16 v[100:103], v[190:193], v[202:205], v[100:103]
	v_mfma_f32_16x16x32_bf16 v[96:99], v[194:197], v[202:205], v[96:99]
	ds_read_b128 v[198:201], v182 offset:9216
	s_waitcnt lgkmcnt(3)
	v_mfma_f32_16x16x32_bf16 v[92:95], v[178:181], v[242:245], v[92:95]
	s_waitcnt vmcnt(7)
	ds_write_b128 v251, v[116:119]
	v_mfma_f32_16x16x32_bf16 v[88:91], v[186:189], v[242:245], v[88:91]
	v_mfma_f32_16x16x32_bf16 v[84:87], v[190:193], v[242:245], v[84:87]
	v_lshl_add_u64 v[116:117], s[52:53], 0, v[164:165]
	s_nop 0
	global_load_dwordx4 v[116:119], v[116:117], off
	v_mfma_f32_16x16x32_bf16 v[80:83], v[194:197], v[242:245], v[80:83]
	ds_read_b128 v[202:205], v182 offset:11520
	s_waitcnt lgkmcnt(3)
	v_mfma_f32_16x16x32_bf16 v[76:79], v[178:181], v[246:249], v[76:79]
	v_mfma_f32_16x16x32_bf16 v[72:75], v[186:189], v[246:249], v[72:75]
	v_mfma_f32_16x16x32_bf16 v[68:71], v[190:193], v[246:249], v[68:71]
	s_waitcnt vmcnt(7)
	ds_write_b128 v252, v[120:123]
	v_mfma_f32_16x16x32_bf16 v[64:67], v[194:197], v[246:249], v[64:67]
	ds_read_b128 v[242:245], v182 offset:13824
	s_waitcnt lgkmcnt(4)
	v_mfma_f32_16x16x32_bf16 v[60:63], v[178:181], v[198:201], v[60:63]
	v_lshl_add_u64 v[120:121], s[52:53], 0, v[166:167]
	s_nop 0
	global_load_dwordx4 v[120:123], v[120:121], off
	v_mfma_f32_16x16x32_bf16 v[56:59], v[186:189], v[198:201], v[56:59]
	v_mfma_f32_16x16x32_bf16 v[52:55], v[190:193], v[198:201], v[52:55]
	v_mfma_f32_16x16x32_bf16 v[48:51], v[194:197], v[198:201], v[48:51]
	ds_read_b128 v[246:249], v182 offset:16128
	s_waitcnt lgkmcnt(3)
	v_mfma_f32_16x16x32_bf16 v[44:47], v[178:181], v[202:205], v[44:47]
	s_waitcnt vmcnt(7)
	ds_write_b128 v253, v[124:127]
	v_mfma_f32_16x16x32_bf16 v[40:43], v[186:189], v[202:205], v[40:43]
	v_mfma_f32_16x16x32_bf16 v[36:39], v[190:193], v[202:205], v[36:39]
	v_lshl_add_u64 v[124:125], s[52:53], 0, v[168:169]
	s_nop 0
	global_load_dwordx4 v[124:127], v[124:125], off
	v_mfma_f32_16x16x32_bf16 v[32:35], v[194:197], v[202:205], v[32:35]
	ds_read_b128 v[198:201], v182 offset:64
	s_waitcnt lgkmcnt(3)
	v_mfma_f32_16x16x32_bf16 v[28:31], v[178:181], v[242:245], v[28:31]
	v_mfma_f32_16x16x32_bf16 v[24:27], v[186:189], v[242:245], v[24:27]
	v_mfma_f32_16x16x32_bf16 v[20:23], v[190:193], v[242:245], v[20:23]
	s_waitcnt vmcnt(7)
	ds_write_b128 v250, v[128:131] offset:36864
	v_mfma_f32_16x16x32_bf16 v[16:19], v[194:197], v[242:245], v[16:19]
	ds_read_b128 v[202:205], v182 offset:2368
	s_waitcnt lgkmcnt(4)
	v_mfma_f32_16x16x32_bf16 v[8:11], v[178:181], v[246:249], v[8:11]
	ds_read_b128 v[178:181], v183 offset:36928
	s_add_u32 s52, s2, s55
	s_addc_u32 s53, s3, 0
	v_lshl_add_u64 v[128:129], s[52:53], 0, v[162:163]
	s_nop 0
	global_load_dwordx4 v[128:131], v[128:129], off
	v_mfma_f32_16x16x32_bf16 v[4:7], v[186:189], v[246:249], v[4:7]
	ds_read_b128 v[186:189], v183 offset:39232
	v_mfma_f32_16x16x32_bf16 v[0:3], v[190:193], v[246:249], v[0:3]
	ds_read_b128 v[190:193], v183 offset:41536
	v_mfma_f32_16x16x32_bf16 v[12:15], v[194:197], v[246:249], v[12:15]
	ds_read_b128 v[194:197], v183 offset:43840
	ds_read_b128 v[242:245], v182 offset:4672
	s_waitcnt lgkmcnt(4)
	v_mfma_f32_16x16x32_bf16 v[156:159], v[178:181], v[198:201], v[156:159]
	s_waitcnt vmcnt(7)
	ds_write_b128 v251, v[132:135] offset:36864
	s_waitcnt lgkmcnt(4)
	v_mfma_f32_16x16x32_bf16 v[152:155], v[186:189], v[198:201], v[152:155]
	s_waitcnt lgkmcnt(3)
	v_mfma_f32_16x16x32_bf16 v[148:151], v[190:193], v[198:201], v[148:151]
	v_lshl_add_u64 v[132:133], s[52:53], 0, v[164:165]
	s_nop 0
	global_load_dwordx4 v[132:135], v[132:133], off
	s_waitcnt lgkmcnt(2)
	v_mfma_f32_16x16x32_bf16 v[144:147], v[194:197], v[198:201], v[144:147]
	ds_read_b128 v[246:249], v182 offset:6976
	v_mfma_f32_16x16x32_bf16 v[108:111], v[178:181], v[202:205], v[108:111]
	v_mfma_f32_16x16x32_bf16 v[104:107], v[186:189], v[202:205], v[104:107]
	v_mfma_f32_16x16x32_bf16 v[100:103], v[190:193], v[202:205], v[100:103]
	s_waitcnt vmcnt(7)
	ds_write_b128 v252, v[136:139] offset:36864
	v_mfma_f32_16x16x32_bf16 v[96:99], v[194:197], v[202:205], v[96:99]
	ds_read_b128 v[198:201], v182 offset:9280
	s_waitcnt lgkmcnt(4)
	v_mfma_f32_16x16x32_bf16 v[92:95], v[178:181], v[242:245], v[92:95]
	v_lshl_add_u64 v[136:137], s[52:53], 0, v[166:167]
	s_nop 0
	global_load_dwordx4 v[136:139], v[136:137], off
	v_mfma_f32_16x16x32_bf16 v[88:91], v[186:189], v[242:245], v[88:91]
	v_mfma_f32_16x16x32_bf16 v[84:87], v[190:193], v[242:245], v[84:87]
	v_mfma_f32_16x16x32_bf16 v[80:83], v[194:197], v[242:245], v[80:83]
	ds_read_b128 v[202:205], v182 offset:11584
	s_waitcnt lgkmcnt(3)
	v_mfma_f32_16x16x32_bf16 v[76:79], v[178:181], v[246:249], v[76:79]
	s_waitcnt vmcnt(7)
	ds_write_b128 v253, v[140:143] offset:36864
	v_mfma_f32_16x16x32_bf16 v[72:75], v[186:189], v[246:249], v[72:75]
	v_mfma_f32_16x16x32_bf16 v[68:71], v[190:193], v[246:249], v[68:71]
	v_lshl_add_u64 v[140:141], s[52:53], 0, v[168:169]
	s_nop 0
	global_load_dwordx4 v[140:143], v[140:141], off
	v_mfma_f32_16x16x32_bf16 v[64:67], v[194:197], v[246:249], v[64:67]
	ds_read_b128 v[242:245], v182 offset:13888
	s_waitcnt lgkmcnt(3)
	v_mfma_f32_16x16x32_bf16 v[60:63], v[178:181], v[198:201], v[60:63]
	v_mfma_f32_16x16x32_bf16 v[56:59], v[186:189], v[198:201], v[56:59]
	v_mfma_f32_16x16x32_bf16 v[52:55], v[190:193], v[198:201], v[52:55]
	v_mfma_f32_16x16x32_bf16 v[48:51], v[194:197], v[198:201], v[48:51]
	ds_read_b128 v[246:249], v182 offset:16192
	s_waitcnt lgkmcnt(3)
	v_mfma_f32_16x16x32_bf16 v[44:47], v[178:181], v[202:205], v[44:47]
	v_mfma_f32_16x16x32_bf16 v[40:43], v[186:189], v[202:205], v[40:43]
	v_mfma_f32_16x16x32_bf16 v[36:39], v[190:193], v[202:205], v[36:39]
	v_mfma_f32_16x16x32_bf16 v[32:35], v[194:197], v[202:205], v[32:35]
	s_waitcnt lgkmcnt(0)
	s_barrier
; DI f32x4 mfma16(bf16x8 a, bf16x8 b, f32x4 c) { return __builtin_amdgcn_mfma_f32_16x16x32_bf16(a, b, c, 0, 0, 0); }
; template <int MI, int NJ, bool SWAP, class AP, class BP>
; DI void gemm_main(f32x4 (&acc)[MI][NJ], const AP& ap, int a_kstep, const BP& bp, int b_kstep, int nk, bf16_t* smem) {
;     ...
;   for (int kt = 0; kt < nk; ++kt) {
;     const int buf = kt & 1;
;     sstore(buf ^ 1);
;     gload(kt + 2 < nk ? kt + 2 : nk - 1);
;     __builtin_amdgcn_sched_barrier(0);
;     const bf16_t* As = smem + buf * L::STAGE + (wm * 16 * MI + l15) * LDT + quad * 8;
;     const bf16_t* Bs = smem + buf * L::STAGE + L::A_ELEMS + (wn * 16 * NJ + l15) * LDT + quad * 8;
; #pragma unroll
;     for (int ks = 0; ks < 2; ++ks) {
;       if (MI * NJ >= 32 && ks == 1) asm volatile("" ::: "memory");
;       bf16x8 b[NJ];
; #pragma unroll
;       for (int j = 0; j < NJ; ++j) b[j] = *(const bf16x8*)(Bs + j * 16 * LDT + ks * 32);
; #pragma unroll
;       for (int i = 0; i < MI; ++i) {
;         const bf16x8 a = *(const bf16x8*)(As + i * 16 * LDT + ks * 32);
; #pragma unroll
;         for (int j = 0; j < NJ; ++j) acc[i][j] = SWAP ? mfma16(b[j], a, acc[i][j]) : mfma16(a, b[j], acc[i][j]);
;       }
;     }
;     __syncthreads();
;   }
	s_add_i32 s33, s33, 1
	s_cmp_lg_u32 s33, 4
	s_cbranch_scc0 .Lgm3_exit
	s_and_b32 s98, s33, 1
	s_mul_i32 s98, s98, 0x12000
	v_add3_u32 v183, s98, v171, v177
	v_add3_u32 v182, s98, v176, v177
	ds_read_b128 v[198:201], v182
	ds_read_b128 v[202:205], v182 offset:2304
	v_mfma_f32_16x16x32_bf16 v[28:31], v[178:181], v[242:245], v[28:31]
	v_mfma_f32_16x16x32_bf16 v[8:11], v[178:181], v[246:249], v[8:11]
	ds_read_b128 v[178:181], v183 offset:36864
	v_mfma_f32_16x16x32_bf16 v[24:27], v[186:189], v[242:245], v[24:27]
	v_mfma_f32_16x16x32_bf16 v[4:7], v[186:189], v[246:249], v[4:7]
	ds_read_b128 v[186:189], v183 offset:39168
	v_mfma_f32_16x16x32_bf16 v[20:23], v[190:193], v[242:245], v[20:23]
	v_mfma_f32_16x16x32_bf16 v[0:3], v[190:193], v[246:249], v[0:3]
	ds_read_b128 v[190:193], v183 offset:41472
	v_mfma_f32_16x16x32_bf16 v[16:19], v[194:197], v[242:245], v[16:19]
	v_mfma_f32_16x16x32_bf16 v[12:15], v[194:197], v[246:249], v[12:15]
	ds_read_b128 v[194:197], v183 offset:43776
	s_branch .Lgm3_main

; DI f32x4 mfma16(bf16x8 a, bf16x8 b, f32x4 c) { return __builtin_amdgcn_mfma_f32_16x16x32_bf16(a, b, c, 0, 0, 0); }
; template <int MI, int NJ, bool SWAP, class AP, class BP>
; DI void gemm_main(f32x4 (&acc)[MI][NJ], const AP& ap, int a_kstep, const BP& bp, int b_kstep, int nk, bf16_t* smem) {
;     ...
;   auto gload = [&](int kt) {
;     const bf16_t* ab = ap.base + (size_t)kt * a_kstep; const bf16_t* bb = bp.base + (size_t)kt * b_kstep;
; #pragma unroll
;     for (int i = 0; i < CA; ++i) ra[i] = *(const u32x4*)(ab + pa[i]);
; #pragma unroll
;     for (int i = 0; i < CB; ++i) rb[i] = *(const u32x4*)(bb + pb[i]);
;   };
;   auto sstore = [&](int buf) {
;     bf16_t* As = smem + buf * L::STAGE; bf16_t* Bs = As + L::A_ELEMS;
; #pragma unroll
;     for (int i = 0; i < CA; ++i) { const int c = tid + NTHR * i; *(u32x4*)(As + (c >> 3) * LDT + (c & 7) * 8) = oka[i] ? ra[i] : (u32x4){0u, 0u, 0u, 0u}; }
; #pragma unroll
;     for (int i = 0; i < CB; ++i) { const int c = tid + NTHR * i; *(u32x4*)(Bs + (c >> 3) * LDT + (c & 7) * 8) = rb[i]; }
;   };
;   gload(0); sstore(0); gload(nk > 1 ? 1 : 0); __syncthreads();
; #pragma unroll 1
;   for (int kt = 0; kt < nk; ++kt) {
;     const int buf = kt & 1;
;     sstore(buf ^ 1);
;     gload(kt + 2 < nk ? kt + 2 : nk - 1);
;     __builtin_amdgcn_sched_barrier(0);
;     const bf16_t* As = smem + buf * L::STAGE + (wm * 16 * MI + l15) * LDT + quad * 8;
;     const bf16_t* Bs = smem + buf * L::STAGE + L::A_ELEMS + (wn * 16 * NJ + l15) * LDT + quad * 8;
; #pragma unroll
;     for (int ks = 0; ks < 2; ++ks) {
;       if (MI * NJ >= 32 && ks == 1) asm volatile("" ::: "memory");
;       bf16x8 b[NJ];
; #pragma unroll
;       for (int j = 0; j < NJ; ++j) b[j] = *(const bf16x8*)(Bs + j * 16 * LDT + ks * 32);
; #pragma unroll
;       for (int i = 0; i < MI; ++i) {
;         const bf16x8 a = *(const bf16x8*)(As + i * 16 * LDT + ks * 32);
; #pragma unroll
;         for (int j = 0; j < NJ; ++j) acc[i][j] = SWAP ? mfma16(b[j], a, acc[i][j]) : mfma16(a, b[j], acc[i][j]);
;       }
;     }
;     __syncthreads();
;   }
.Lgm4_main:
	ds_read_b128 v[242:245], v182 offset:4608
	s_waitcnt lgkmcnt(4)
	v_mfma_f32_16x16x32_bf16 v[140:143], v[198:201], v[178:181], v[140:143]
	s_waitcnt lgkmcnt(3)
	v_mfma_f32_16x16x32_bf16 v[120:123], v[198:201], v[186:189], v[120:123]
	s_waitcnt lgkmcnt(2)
	v_mfma_f32_16x16x32_bf16 v[116:119], v[198:201], v[190:193], v[116:119]
	v_lshlrev_b32_e32 v250, 1, v160
	s_and_b32 s16, s5, 1
	s_xor_b32 s33, s16, 1
	s_mul_i32 s33, s33, 0x12000
	v_add3_u32 v250, s33, v250, v172
	s_waitcnt vmcnt(7)
	ds_write_b128 v250, v[124:127]
	s_waitcnt lgkmcnt(2)
	v_mfma_f32_16x16x32_bf16 v[112:115], v[198:201], v[194:197], v[112:115]
	ds_read_b128 v[246:249], v182 offset:6912
	v_mfma_f32_16x16x32_bf16 v[108:111], v[202:205], v[178:181], v[108:111]
	s_cmp_eq_u32 s5, 0
	v_lshlrev_b32_e32 v251, 1, v173
	v_add3_u32 v251, s33, v251, v172
	v_lshlrev_b32_e32 v252, 1, v174
	v_add3_u32 v252, s33, v252, v172
	v_lshlrev_b32_e32 v253, 1, v175
	v_add3_u32 v253, s33, v253, v172
	s_cselect_b32 s33, s48, 0x180
	s_add_u32 s52, s0, s33
	s_addc_u32 s53, s1, 0
	v_lshl_add_u64 v[124:125], s[52:53], 0, v[162:163]
	s_nop 0
	global_load_dwordx4 v[124:127], v[124:125], off
	v_mfma_f32_16x16x32_bf16 v[104:107], v[202:205], v[186:189], v[104:107]
	v_mfma_f32_16x16x32_bf16 v[100:103], v[202:205], v[190:193], v[100:103]
	v_mfma_f32_16x16x32_bf16 v[96:99], v[202:205], v[194:197], v[96:99]
	ds_read_b128 v[198:201], v182 offset:9216
	s_waitcnt lgkmcnt(3)
	v_mfma_f32_16x16x32_bf16 v[92:95], v[242:245], v[178:181], v[92:95]
	s_waitcnt vmcnt(7)
	ds_write_b128 v251, v[128:131]
	v_mfma_f32_16x16x32_bf16 v[88:91], v[242:245], v[186:189], v[88:91]
	v_mfma_f32_16x16x32_bf16 v[84:87], v[242:245], v[190:193], v[84:87]
	v_lshl_add_u64 v[128:129], s[52:53], 0, v[164:165]
	s_nop 0
	global_load_dwordx4 v[128:131], v[128:129], off
	v_mfma_f32_16x16x32_bf16 v[80:83], v[242:245], v[194:197], v[80:83]
	ds_read_b128 v[202:205], v182 offset:11520
	s_waitcnt lgkmcnt(3)
	v_mfma_f32_16x16x32_bf16 v[76:79], v[246:249], v[178:181], v[76:79]
	v_mfma_f32_16x16x32_bf16 v[72:75], v[246:249], v[186:189], v[72:75]
	v_mfma_f32_16x16x32_bf16 v[68:71], v[246:249], v[190:193], v[68:71]
	s_waitcnt vmcnt(7)
	ds_write_b128 v252, v[132:135]
	v_mfma_f32_16x16x32_bf16 v[64:67], v[246:249], v[194:197], v[64:67]
	ds_read_b128 v[242:245], v182 offset:13824
	s_waitcnt lgkmcnt(4)
	v_mfma_f32_16x16x32_bf16 v[60:63], v[198:201], v[178:181], v[60:63]
	v_lshl_add_u64 v[132:133], s[52:53], 0, v[166:167]
	s_nop 0
	global_load_dwordx4 v[132:135], v[132:133], off
	v_mfma_f32_16x16x32_bf16 v[56:59], v[198:201], v[186:189], v[56:59]
	v_mfma_f32_16x16x32_bf16 v[52:55], v[198:201], v[190:193], v[52:55]
	v_mfma_f32_16x16x32_bf16 v[48:51], v[198:201], v[194:197], v[48:51]
	ds_read_b128 v[246:249], v182 offset:16128
	s_waitcnt lgkmcnt(3)
	v_mfma_f32_16x16x32_bf16 v[44:47], v[202:205], v[178:181], v[44:47]
	s_waitcnt vmcnt(7)
	ds_write_b128 v253, v[136:139]
	v_mfma_f32_16x16x32_bf16 v[40:43], v[202:205], v[186:189], v[40:43]
	v_mfma_f32_16x16x32_bf16 v[36:39], v[202:205], v[190:193], v[36:39]
	v_lshl_add_u64 v[136:137], s[52:53], 0, v[168:169]
	s_nop 0
	global_load_dwordx4 v[136:139], v[136:137], off
	v_mfma_f32_16x16x32_bf16 v[32:35], v[202:205], v[194:197], v[32:35]
	ds_read_b128 v[198:201], v182 offset:64
	s_waitcnt lgkmcnt(3)
	v_mfma_f32_16x16x32_bf16 v[28:31], v[242:245], v[178:181], v[28:31]
	v_mfma_f32_16x16x32_bf16 v[24:27], v[242:245], v[186:189], v[24:27]
	v_mfma_f32_16x16x32_bf16 v[20:23], v[242:245], v[190:193], v[20:23]
	s_waitcnt vmcnt(7)
	ds_write_b128 v250, v[144:147] offset:36864
	v_mfma_f32_16x16x32_bf16 v[16:19], v[242:245], v[194:197], v[16:19]
	ds_read_b128 v[202:205], v182 offset:2368
	s_waitcnt lgkmcnt(4)
	v_mfma_f32_16x16x32_bf16 v[8:11], v[246:249], v[178:181], v[8:11]
	ds_read_b128 v[178:181], v183 offset:36928
	s_add_u32 s52, s2, s33
	s_addc_u32 s53, s3, 0
	v_lshl_add_u64 v[144:145], s[52:53], 0, v[162:163]
	s_nop 0
	global_load_dwordx4 v[144:147], v[144:145], off
	v_mfma_f32_16x16x32_bf16 v[4:7], v[246:249], v[186:189], v[4:7]
	ds_read_b128 v[186:189], v183 offset:39232
	v_mfma_f32_16x16x32_bf16 v[0:3], v[246:249], v[190:193], v[0:3]
	ds_read_b128 v[190:193], v183 offset:41536
	v_mfma_f32_16x16x32_bf16 v[12:15], v[246:249], v[194:197], v[12:15]
	ds_read_b128 v[194:197], v183 offset:43840
	ds_read_b128 v[242:245], v182 offset:4672
	s_waitcnt lgkmcnt(4)
	v_mfma_f32_16x16x32_bf16 v[140:143], v[198:201], v[178:181], v[140:143]
	s_waitcnt vmcnt(7)
	ds_write_b128 v251, v[148:151] offset:36864
	s_waitcnt lgkmcnt(4)
	v_mfma_f32_16x16x32_bf16 v[120:123], v[198:201], v[186:189], v[120:123]
	s_waitcnt lgkmcnt(3)
	v_mfma_f32_16x16x32_bf16 v[116:119], v[198:201], v[190:193], v[116:119]
	v_lshl_add_u64 v[148:149], s[52:53], 0, v[164:165]
	s_nop 0
	global_load_dwordx4 v[148:151], v[148:149], off
	s_waitcnt lgkmcnt(2)
	v_mfma_f32_16x16x32_bf16 v[112:115], v[198:201], v[194:197], v[112:115]
	ds_read_b128 v[246:249], v182 offset:6976
	v_mfma_f32_16x16x32_bf16 v[108:111], v[202:205], v[178:181], v[108:111]
	v_mfma_f32_16x16x32_bf16 v[104:107], v[202:205], v[186:189], v[104:107]
	v_mfma_f32_16x16x32_bf16 v[100:103], v[202:205], v[190:193], v[100:103]
	s_waitcnt vmcnt(7)
	ds_write_b128 v252, v[152:155] offset:36864
	v_mfma_f32_16x16x32_bf16 v[96:99], v[202:205], v[194:197], v[96:99]
	ds_read_b128 v[198:201], v182 offset:9280
	s_waitcnt lgkmcnt(4)
	v_mfma_f32_16x16x32_bf16 v[92:95], v[242:245], v[178:181], v[92:95]
	v_lshl_add_u64 v[152:153], s[52:53], 0, v[166:167]
	s_nop 0
	global_load_dwordx4 v[152:155], v[152:153], off
	v_mfma_f32_16x16x32_bf16 v[88:91], v[242:245], v[186:189], v[88:91]
	v_mfma_f32_16x16x32_bf16 v[84:87], v[242:245], v[190:193], v[84:87]
	v_mfma_f32_16x16x32_bf16 v[80:83], v[242:245], v[194:197], v[80:83]
	ds_read_b128 v[202:205], v182 offset:11584
	s_waitcnt lgkmcnt(3)
	v_mfma_f32_16x16x32_bf16 v[76:79], v[246:249], v[178:181], v[76:79]
	s_waitcnt vmcnt(7)
	ds_write_b128 v253, v[156:159] offset:36864
	v_mfma_f32_16x16x32_bf16 v[72:75], v[246:249], v[186:189], v[72:75]
	v_mfma_f32_16x16x32_bf16 v[68:71], v[246:249], v[190:193], v[68:71]
	v_lshl_add_u64 v[156:157], s[52:53], 0, v[168:169]
	s_nop 0
	global_load_dwordx4 v[156:159], v[156:157], off
	v_mfma_f32_16x16x32_bf16 v[64:67], v[246:249], v[194:197], v[64:67]
	ds_read_b128 v[242:245], v182 offset:13888
	s_waitcnt lgkmcnt(3)
	v_mfma_f32_16x16x32_bf16 v[60:63], v[198:201], v[178:181], v[60:63]
	v_mfma_f32_16x16x32_bf16 v[56:59], v[198:201], v[186:189], v[56:59]
	v_mfma_f32_16x16x32_bf16 v[52:55], v[198:201], v[190:193], v[52:55]
	v_mfma_f32_16x16x32_bf16 v[48:51], v[198:201], v[194:197], v[48:51]
	ds_read_b128 v[246:249], v182 offset:16192
	s_waitcnt lgkmcnt(3)
	v_mfma_f32_16x16x32_bf16 v[44:47], v[202:205], v[178:181], v[44:47]
	v_mfma_f32_16x16x32_bf16 v[40:43], v[202:205], v[186:189], v[40:43]
	v_mfma_f32_16x16x32_bf16 v[36:39], v[202:205], v[190:193], v[36:39]
	v_mfma_f32_16x16x32_bf16 v[32:35], v[202:205], v[194:197], v[32:35]
	s_waitcnt lgkmcnt(0)
	s_barrier
; DI f32x4 mfma16(bf16x8 a, bf16x8 b, f32x4 c) { return __builtin_amdgcn_mfma_f32_16x16x32_bf16(a, b, c, 0, 0, 0); }
; template <int MI, int NJ, bool SWAP, class AP, class BP>
; DI void gemm_main(f32x4 (&acc)[MI][NJ], const AP& ap, int a_kstep, const BP& bp, int b_kstep, int nk, bf16_t* smem) {
;     ...
;   for (int kt = 0; kt < nk; ++kt) {
;     const int buf = kt & 1;
;     sstore(buf ^ 1);
;     gload(kt + 2 < nk ? kt + 2 : nk - 1);
;     __builtin_amdgcn_sched_barrier(0);
;     const bf16_t* As = smem + buf * L::STAGE + (wm * 16 * MI + l15) * LDT + quad * 8;
;     const bf16_t* Bs = smem + buf * L::STAGE + L::A_ELEMS + (wn * 16 * NJ + l15) * LDT + quad * 8;
; #pragma unroll
;     for (int ks = 0; ks < 2; ++ks) {
;       if (MI * NJ >= 32 && ks == 1) asm volatile("" ::: "memory");
;       bf16x8 b[NJ];
; #pragma unroll
;       for (int j = 0; j < NJ; ++j) b[j] = *(const bf16x8*)(Bs + j * 16 * LDT + ks * 32);
; #pragma unroll
;       for (int i = 0; i < MI; ++i) {
;         const bf16x8 a = *(const bf16x8*)(As + i * 16 * LDT + ks * 32);
; #pragma unroll
;         for (int j = 0; j < NJ; ++j) acc[i][j] = SWAP ? mfma16(b[j], a, acc[i][j]) : mfma16(a, b[j], acc[i][j]);
;       }
;     }
;     __syncthreads();
;   }
	s_add_i32 s5, s5, 1
	s_cmp_lg_u32 s5, 4
	s_cbranch_scc0 .Lgm4_exit
	s_and_b32 s98, s5, 1
	s_mul_i32 s98, s98, 0x12000
	v_add3_u32 v182, s98, v176, v177
	v_add3_u32 v183, s98, v171, v177
	ds_read_b128 v[198:201], v182
	ds_read_b128 v[202:205], v182 offset:2304
	v_mfma_f32_16x16x32_bf16 v[28:31], v[242:245], v[178:181], v[28:31]
	v_mfma_f32_16x16x32_bf16 v[8:11], v[246:249], v[178:181], v[8:11]
	ds_read_b128 v[178:181], v183 offset:36864
	v_mfma_f32_16x16x32_bf16 v[24:27], v[242:245], v[186:189], v[24:27]
	v_mfma_f32_16x16x32_bf16 v[4:7], v[246:249], v[186:189], v[4:7]
	ds_read_b128 v[186:189], v183 offset:39168
	v_mfma_f32_16x16x32_bf16 v[20:23], v[242:245], v[190:193], v[20:23]
	v_mfma_f32_16x16x32_bf16 v[0:3], v[246:249], v[190:193], v[0:3]
	ds_read_b128 v[190:193], v183 offset:41472
	v_mfma_f32_16x16x32_bf16 v[16:19], v[242:245], v[194:197], v[16:19]
	v_mfma_f32_16x16x32_bf16 v[12:15], v[246:249], v[194:197], v[12:15]
	ds_read_b128 v[194:197], v183 offset:43776
	s_branch .Lgm4_main

; template <int MODE>
; DI void flash_pass(AState& st, const bf16x8* qf, u64 tmask, u64 wmask,
;                    const bf16_t* kbase, size_t kld, const bf16_t* kpe, const bf16_t* vtbase, const float* fbias,
;                    int tq, u64 mysel, bf16_t* smem) {
;     ...
;     constexpr int S = decltype(setc)::value;
;     bf16_t* Ks = smem + stg * C::STAGE; bf16_t* Vs = Ks + C::K_ELEMS;
; #pragma unroll
;     for (int i = 0; i < C::KCH; ++i) {
;       const int c = tid + NTHR * i;
;       if (c < C::NKC) {
;         if constexpr (MODE == M_MLA) { const int key = c / 12, dc = c % 12; *(u32x4*)(Ks + key * C::KLD + dc * 8) = rk[S][i]; }
;         else { const int key = c >> 3, dc = c & 7; *(u32x4*)(Ks + key * C::KLD + dc * 8) = rk[S][i]; }
;       }
;     }
;     {
;       const int d = tid >> 3, kc = tid & 7, cgp = kc >> 1, a = kc & 1;
;       bf16_t* dst = Vs + d * 72 + cgp * 16 + 4 * a;
;       *(u32x2*)dst = (u32x2){rv[S][0], rv[S][1]}; *(u32x2*)(dst + 8) = (u32x2){rv[S][2], rv[S][3]};
;     }
;     if constexpr (MODE == M_FOX) { if (tid < 64) ((float*)(Vs + C::V_ELEMS))[tid] = rf[S]; }
;   };
;   const int tmin = __builtin_amdgcn_readfirstlane(tq - l31), tmax = tmin + 31;
;   auto compute = [&](int j, int stg) {
;     bool active = (wmask >> j) & 1;
;     if constexpr (MODE == M_SLC) active = active && __any((mysel >> j) & 1);
;     if (active) {
;       const bf16_t* Ks = smem + stg * C::STAGE; const bf16_t* Vs = Ks + C::K_ELEMS;
;       f32x16 s0 = st.mr, s1 = st.mr;
;       const bf16_t* kr = Ks + l31 * C::KLD + half * 8;
; #pragma unroll
;       for (int ks = 0; ks < C::DQK / 16; ++ks) {
;         s0 = mfma32(*(const bf16x8*)(kr + ks * 16), qf[ks], s0);
;         s1 = mfma32(*(const bf16x8*)(kr + 32 * C::KLD + ks * 16), qf[ks], s1);
;       }
;       const int k0 = j * 64;
;       if constexpr (MODE == M_FOX) {
;         const float* fb = (const float*)(Vs + C::V_ELEMS) + 4 * half;
; #pragma unroll
;         for (int g4 = 0; g4 < 4; ++g4) {
;           const f32x4 b0 = *(const f32x4*)(fb + 8 * g4), b1 = *(const f32x4*)(fb + 32 + 8 * g4);
; #pragma unroll
;           for (int r = 0; r < 4; ++r) { s0[4 * g4 + r] += b0[r]; s1[4 * g4 + r] += b1[r]; }
;         }
;       }
;       bool need = k0 + 63 > tmin;
;       if constexpr (MODE == M_WIN) need = need || (k0 <= tmax - 512);
;       if constexpr (MODE == M_SLC) {
;         if (!need) {
.LBB0_607:
	s_mul_i32 s4, s14, 0x2480
	s_xor_b32 s2, s14, 2
	s_mul_i32 s2, s2, 0x2480
	s_nop 0
	s_lshl_b32 s5, s2, 1
	s_and_saveexec_b64 s[2:3], s[0:1]
	s_cbranch_execz .LBB0_609
	v_add3_u32 v0, s5, v126, v114
	s_waitcnt vmcnt(3)
	ds_write_b128 v0, v[100:103]
.LBB0_609:
	s_or_b64 exec, exec, s[2:3]
	s_cmp_eq_u64 s[10:11], 0
	s_cselect_b64 s[8:9], -1, 0
	s_ff1_i32_b64 s25, s[10:11]
	s_and_b64 s[2:3], s[8:9], exec
	s_cselect_b32 s2, s15, s25
	s_lshl_b32 s68, s2, 6
	v_lshl_add_u32 v0, v125, 1, s5
	v_add_u32_e32 v2, s68, v124
	v_add3_u32 v0, v0, v127, v144
	v_ashrrev_i32_e32 v3, 31, v2
	v_add_u32_e32 v0, 0x2000, v0
	v_lshlrev_b64 v[2:3], 8, v[2:3]
	s_waitcnt vmcnt(2)
	ds_write2_b64 v0, v[96:97], v[98:99] offset0:128 offset1:130
	v_lshl_add_u64 v[2:3], v[118:119], 0, v[2:3]
	v_lshl_add_u64 v[4:5], s[68:69], 1, v[120:121]
	global_load_dwordx4 v[100:103], v[2:3], off
	global_load_dwordx4 v[96:99], v[4:5], off
	v_lshrrev_b64 v[2:3], s15, v[116:117]
	v_and_b32_e32 v0, 1, v2
	v_cmp_eq_u32_e32 vcc, 1, v0
	s_and_saveexec_b64 s[12:13], vcc
	s_cbranch_execz .LBB0_616
	v_lshl_add_u32 v0, s4, 1, v145
	ds_read_b128 v[2:5], v0
	ds_read_b128 v[6:9], v0 offset:32
	s_lshl_b32 s2, s15, 6
	s_or_b32 s3, s2, 63
	s_cmp_le_i32 s3, s21
	s_waitcnt lgkmcnt(1)
	v_mfma_f32_32x32x16_bf16 v[80:95], v[2:5], v[140:143], v[48:63]
	ds_read_b128 v[2:5], v0 offset:4608
	s_cselect_b64 s[4:5], -1, 0
	s_cmp_gt_i32 s2, s24
	s_cselect_b64 s[28:29], -1, 0
	s_and_b64 s[4:5], s[4:5], s[28:29]
	s_and_b64 vcc, exec, s[4:5]
	s_waitcnt lgkmcnt(1)
	v_mfma_f32_32x32x16_bf16 v[80:95], v[6:9], v[128:131], v[80:95]
	s_waitcnt lgkmcnt(0)
	v_mfma_f32_32x32x16_bf16 v[64:79], v[2:5], v[140:143], v[48:63]
	ds_read_b128 v[2:5], v0 offset:4640
	s_waitcnt lgkmcnt(0)
	v_mfma_f32_32x32x16_bf16 v[64:79], v[2:5], v[128:131], v[64:79]
	ds_read_b128 v[2:5], v0 offset:64
	s_waitcnt lgkmcnt(0)
	v_mfma_f32_32x32x16_bf16 v[80:95], v[2:5], v[132:135], v[80:95]
	ds_read_b128 v[2:5], v0 offset:4672
	s_waitcnt lgkmcnt(0)
	v_mfma_f32_32x32x16_bf16 v[64:79], v[2:5], v[132:135], v[64:79]
	ds_read_b128 v[2:5], v0 offset:96
	s_waitcnt lgkmcnt(0)
	v_mfma_f32_32x32x16_bf16 v[80:95], v[2:5], v[136:139], v[80:95]
	ds_read_b128 v[2:5], v0 offset:4704
	s_waitcnt lgkmcnt(0)
	v_mfma_f32_32x32x16_bf16 v[64:79], v[2:5], v[136:139], v[64:79]
	s_cbranch_vccnz .LBB0_612
	v_or_b32_e32 v2, s2, v115
	v_or_b32_e32 v3, 32, v2
	v_cmp_le_i32_e64 s[2:3], v3, v160
	v_sub_u32_e32 v3, v160, v2
	v_cmp_ge_i32_e32 vcc, v160, v2
	v_cmp_gt_i32_e64 s[4:5], s85, v3
	s_and_b64 vcc, vcc, s[4:5]
	v_cmp_gt_i32_e64 s[4:5], s87, v3
	s_and_b64 s[2:3], s[2:3], s[4:5]
	v_or_b32_e32 v3, 33, v2
	s_nop 0
	v_cndmask_b32_e64 v64, v175, v64, s[2:3]
	v_cmp_le_i32_e64 s[2:3], v3, v160
	v_xad_u32 v3, v2, -1, v160
	v_cndmask_b32_e32 v80, v175, v80, vcc
	v_cmp_gt_i32_e32 vcc, v160, v2
	v_cmp_gt_i32_e64 s[4:5], s85, v3
	s_and_b64 vcc, vcc, s[4:5]
	v_cmp_gt_i32_e64 s[4:5], s87, v3
	v_or_b32_e32 v3, 2, v2
	v_cndmask_b32_e32 v81, v175, v81, vcc
	v_cmp_ge_i32_e32 vcc, v160, v3
	v_sub_u32_e32 v3, v160, v3
	s_and_b64 s[2:3], s[2:3], s[4:5]
	v_cmp_gt_i32_e64 s[4:5], s85, v3
	v_or_b32_e32 v4, 34, v2
	s_and_b64 vcc, vcc, s[4:5]
	v_cmp_gt_i32_e64 s[4:5], s87, v3
	v_or_b32_e32 v3, 3, v2
	v_cndmask_b32_e64 v65, v175, v65, s[2:3]
	v_cmp_le_i32_e64 s[2:3], v4, v160
	v_cndmask_b32_e32 v82, v175, v82, vcc
	v_cmp_ge_i32_e32 vcc, v160, v3
	v_sub_u32_e32 v3, v160, v3
	s_and_b64 s[2:3], s[2:3], s[4:5]
	v_cmp_gt_i32_e64 s[4:5], s85, v3
	v_or_b32_e32 v4, 35, v2
	s_and_b64 vcc, vcc, s[4:5]
	v_cmp_gt_i32_e64 s[4:5], s87, v3
	v_or_b32_e32 v3, 8, v2
	v_cndmask_b32_e64 v66, v175, v66, s[2:3]
	v_cmp_le_i32_e64 s[2:3], v4, v160
	v_cndmask_b32_e32 v83, v175, v83, vcc
	v_cmp_ge_i32_e32 vcc, v160, v3
	v_sub_u32_e32 v3, v160, v3
	s_and_b64 s[2:3], s[2:3], s[4:5]
	v_cmp_gt_i32_e64 s[4:5], s85, v3
	v_or_b32_e32 v4, 40, v2
	s_and_b64 vcc, vcc, s[4:5]
	v_cmp_gt_i32_e64 s[4:5], s87, v3
	v_or_b32_e32 v3, 9, v2
	v_cndmask_b32_e64 v67, v175, v67, s[2:3]
	v_cmp_le_i32_e64 s[2:3], v4, v160
	v_cndmask_b32_e32 v84, v175, v84, vcc
	v_cmp_ge_i32_e32 vcc, v160, v3
	v_sub_u32_e32 v3, v160, v3
	s_and_b64 s[2:3], s[2:3], s[4:5]
	v_cmp_gt_i32_e64 s[4:5], s85, v3
	v_or_b32_e32 v4, 41, v2
	s_and_b64 vcc, vcc, s[4:5]
	v_cmp_gt_i32_e64 s[4:5], s87, v3
	v_or_b32_e32 v3, 10, v2
	v_cndmask_b32_e64 v68, v175, v68, s[2:3]
	v_cmp_le_i32_e64 s[2:3], v4, v160
	v_cndmask_b32_e32 v85, v175, v85, vcc
	v_cmp_ge_i32_e32 vcc, v160, v3
	v_sub_u32_e32 v3, v160, v3
	s_and_b64 s[2:3], s[2:3], s[4:5]
	v_cmp_gt_i32_e64 s[4:5], s85, v3
	v_or_b32_e32 v4, 42, v2
	s_and_b64 vcc, vcc, s[4:5]
	v_cmp_gt_i32_e64 s[4:5], s87, v3
	v_or_b32_e32 v3, 11, v2
	v_cndmask_b32_e64 v69, v175, v69, s[2:3]
	v_cmp_le_i32_e64 s[2:3], v4, v160
	v_cndmask_b32_e32 v86, v175, v86, vcc
	v_cmp_ge_i32_e32 vcc, v160, v3
	v_sub_u32_e32 v3, v160, v3
	s_and_b64 s[2:3], s[2:3], s[4:5]
	v_cmp_gt_i32_e64 s[4:5], s85, v3
	v_or_b32_e32 v4, 43, v2
	s_and_b64 vcc, vcc, s[4:5]
	v_cmp_gt_i32_e64 s[4:5], s87, v3
	v_or_b32_e32 v3, 16, v2
	v_cndmask_b32_e64 v70, v175, v70, s[2:3]
	v_cmp_le_i32_e64 s[2:3], v4, v160
	v_cndmask_b32_e32 v87, v175, v87, vcc
	v_cmp_ge_i32_e32 vcc, v160, v3
	v_sub_u32_e32 v3, v160, v3
	s_and_b64 s[2:3], s[2:3], s[4:5]
	v_cmp_gt_i32_e64 s[4:5], s85, v3
	v_or_b32_e32 v4, 48, v2
	s_and_b64 vcc, vcc, s[4:5]
	v_cmp_gt_i32_e64 s[4:5], s87, v3
	v_or_b32_e32 v3, 17, v2
	v_cndmask_b32_e64 v71, v175, v71, s[2:3]
	v_cmp_le_i32_e64 s[2:3], v4, v160
	v_cndmask_b32_e32 v88, v175, v88, vcc
	v_cmp_ge_i32_e32 vcc, v160, v3
	v_sub_u32_e32 v3, v160, v3
	s_and_b64 s[2:3], s[2:3], s[4:5]
	v_cmp_gt_i32_e64 s[4:5], s85, v3
	v_or_b32_e32 v4, 49, v2
	s_and_b64 vcc, vcc, s[4:5]
; DI float ex2(float x) { return __builtin_amdgcn_exp2f(x); }
; template <int MODE>
; DI void flash_pass(AState& st, const bf16x8* qf, u64 tmask, u64 wmask,
;                    const bf16_t* kbase, size_t kld, const bf16_t* kpe, const bf16_t* vtbase, const float* fbias,
;                    int tq, u64 mysel, bf16_t* smem) {
;     ...
;         for (int r = 0; r < 16; ++r) {
;           const int key = k0 + (r & 3) + 8 * (r >> 2) + 4 * half;
;           bool ok0 = rowok && key <= tq, ok1 = rowok && key + 32 <= tq;
;           if constexpr (MODE == M_WIN) { ok0 = ok0 && (tq - key < 512); ok1 = ok1 && (tq - key - 32 < 512); }
;           s0[r] = ok0 ? s0[r] : -INFINITY; s1[r] = ok1 ? s1[r] : -INFINITY;
;         }
;       }
;       int im = (int)0x80000000;
; #pragma unroll
;       for (int r = 0; r < 16; ++r) im = max(im, max(__float_as_int(s0[r]), __float_as_int(s1[r])));
;       im = max(im, __shfl_xor(im, 32));
;       constexpr int TBITS = 0x41800000;
;       f32x16 e0, e1;
; #pragma unroll
;       for (int r = 0; r < 16; ++r) { e0[r] = ex2(s0[r]); e1[r] = ex2(s1[r]); }
;       if (__any(im > TBITS)) {
;         const float d = im > TBITS ? __int_as_float(im) : 0.f;
;         const float a = ex2(-d);
; #pragma unroll
;         for (int r = 0; r < 16; ++r) { e0[r] = ex2(s0[r] - d); e1[r] = ex2(s1[r] - d); st.o[0][r] *= a; st.o[1][r] *= a; }
;         st.l *= a; st.m += d;
; #pragma unroll
;         for (int r = 0; r < 16; ++r) st.mr[r] = -st.m;
;       }
	v_cmp_gt_i32_e64 s[4:5], s87, v3
	v_or_b32_e32 v3, 18, v2
	v_cndmask_b32_e64 v72, v175, v72, s[2:3]
	v_cmp_le_i32_e64 s[2:3], v4, v160
	v_cndmask_b32_e32 v89, v175, v89, vcc
	v_cmp_ge_i32_e32 vcc, v160, v3
	v_sub_u32_e32 v3, v160, v3
	s_and_b64 s[2:3], s[2:3], s[4:5]
	v_cmp_gt_i32_e64 s[4:5], s85, v3
	v_or_b32_e32 v4, 50, v2
	s_and_b64 vcc, vcc, s[4:5]
	v_cmp_gt_i32_e64 s[4:5], s87, v3
	v_or_b32_e32 v3, 19, v2
	v_cndmask_b32_e64 v73, v175, v73, s[2:3]
	v_cmp_le_i32_e64 s[2:3], v4, v160
	v_cndmask_b32_e32 v90, v175, v90, vcc
	v_cmp_ge_i32_e32 vcc, v160, v3
	v_sub_u32_e32 v3, v160, v3
	s_and_b64 s[2:3], s[2:3], s[4:5]
	v_cmp_gt_i32_e64 s[4:5], s85, v3
	v_or_b32_e32 v4, 51, v2
	s_and_b64 vcc, vcc, s[4:5]
	v_cmp_gt_i32_e64 s[4:5], s87, v3
	v_or_b32_e32 v3, 24, v2
	v_cndmask_b32_e64 v74, v175, v74, s[2:3]
	v_cmp_le_i32_e64 s[2:3], v4, v160
	v_cndmask_b32_e32 v91, v175, v91, vcc
	v_cmp_ge_i32_e32 vcc, v160, v3
	v_sub_u32_e32 v3, v160, v3
	s_and_b64 s[2:3], s[2:3], s[4:5]
	v_cmp_gt_i32_e64 s[4:5], s85, v3
	v_or_b32_e32 v4, 56, v2
	s_and_b64 vcc, vcc, s[4:5]
	v_cmp_gt_i32_e64 s[4:5], s87, v3
	v_or_b32_e32 v3, 25, v2
	v_cndmask_b32_e64 v75, v175, v75, s[2:3]
	v_cmp_le_i32_e64 s[2:3], v4, v160
	v_cndmask_b32_e32 v92, v175, v92, vcc
	v_cmp_ge_i32_e32 vcc, v160, v3
	v_sub_u32_e32 v3, v160, v3
	s_and_b64 s[2:3], s[2:3], s[4:5]
	v_cmp_gt_i32_e64 s[4:5], s85, v3
	v_or_b32_e32 v4, 57, v2
	s_and_b64 vcc, vcc, s[4:5]
	v_cmp_gt_i32_e64 s[4:5], s87, v3
	v_or_b32_e32 v3, 26, v2
	v_cndmask_b32_e64 v76, v175, v76, s[2:3]
	v_cmp_le_i32_e64 s[2:3], v4, v160
	v_cndmask_b32_e32 v93, v175, v93, vcc
	v_cmp_ge_i32_e32 vcc, v160, v3
	v_sub_u32_e32 v3, v160, v3
	s_and_b64 s[2:3], s[2:3], s[4:5]
	v_or_b32_e32 v4, 58, v2
	v_cmp_gt_i32_e64 s[4:5], s85, v3
	v_cndmask_b32_e64 v77, v175, v77, s[2:3]
	v_cmp_le_i32_e64 s[2:3], v4, v160
	s_and_b64 vcc, vcc, s[4:5]
	v_cmp_gt_i32_e64 s[4:5], s87, v3
	s_and_b64 s[2:3], s[2:3], s[4:5]
	v_or_b32_e32 v3, 27, v2
	v_or_b32_e32 v2, 59, v2
	v_cndmask_b32_e64 v78, v175, v78, s[2:3]
	v_cmp_le_i32_e64 s[2:3], v2, v160
	v_sub_u32_e32 v2, v160, v3
	v_cndmask_b32_e32 v94, v175, v94, vcc
	v_cmp_ge_i32_e32 vcc, v160, v3
	v_cmp_gt_i32_e64 s[4:5], s85, v2
	s_and_b64 vcc, vcc, s[4:5]
	v_cmp_gt_i32_e64 s[4:5], s87, v2
	s_and_b64 s[2:3], s[2:3], s[4:5]
	v_cndmask_b32_e32 v95, v175, v95, vcc
	v_cndmask_b32_e64 v79, v175, v79, s[2:3]
.LBB0_612:
	s_nop 10
	v_max_i32_e32 v2, v81, v65
	v_max3_i32 v2, v80, v64, v2
	v_max_i32_e32 v3, v82, v66
	v_max_i32_e32 v4, v83, v67
	v_max3_i32 v2, v2, v3, v4
	v_max_i32_e32 v3, v84, v68
	v_max_i32_e32 v4, v85, v69
	v_max3_i32 v2, v2, v3, v4
	v_max_i32_e32 v3, v86, v70
	v_max_i32_e32 v4, v87, v71
	v_max3_i32 v2, v2, v3, v4
	v_max_i32_e32 v3, v88, v72
	v_max_i32_e32 v4, v89, v73
	v_max3_i32 v2, v2, v3, v4
	v_max_i32_e32 v3, v90, v74
	v_max_i32_e32 v4, v91, v75
	v_max3_i32 v2, v2, v3, v4
	v_max_i32_e32 v3, v92, v76
	v_max_i32_e32 v4, v93, v77
	v_max3_i32 v2, v2, v3, v4
	v_max_i32_e32 v3, v94, v78
	v_max_i32_e32 v4, v95, v79
	v_max3_i32 v2, v2, v3, v4
	v_mov_b32_e32 v3, v2
	s_nop 1
	v_permlane32_swap_b32_e32 v3, v2
	v_max_i32_e32 v2, v2, v3
	v_cmp_lt_i32_e32 vcc, s88, v2
	s_cbranch_vccz .LBB0_614
	s_nop 0
	v_cndmask_b32_e32 v49, 0, v2, vcc
	v_sub_f32_e32 v2, v80, v49
	v_exp_f32_e32 v151, v2
	v_sub_f32_e32 v2, v64, v49
	v_exp_f32_e32 v147, v2
	v_sub_f32_e32 v2, v81, v49
	v_exp_f32_e32 v152, v2
	v_sub_f32_e32 v2, v65, v49
	v_exp_f32_e32 v148, v2
	v_sub_f32_e32 v2, v82, v49
	v_exp_f32_e32 v153, v2
	v_sub_f32_e32 v2, v66, v49
	v_exp_f32_e32 v149, v2
	v_sub_f32_e32 v2, v83, v49
	v_exp_f32_e32 v154, v2
	v_sub_f32_e32 v2, v67, v49
	v_exp_f32_e32 v150, v2
	v_sub_f32_e32 v2, v84, v49
	v_exp_f32_e32 v80, v2
	v_sub_f32_e32 v2, v68, v49
	v_exp_f32_e32 v10, v2
	v_sub_f32_e32 v2, v85, v49
	v_exp_f32_e32 v81, v2
	v_sub_f32_e32 v2, v69, v49
	v_exp_f32_e32 v11, v2
	v_sub_f32_e32 v2, v86, v49
	v_exp_f32_e32 v82, v2
	v_sub_f32_e32 v2, v70, v49
	v_exp_f32_e32 v12, v2
	v_sub_f32_e32 v2, v87, v49
	v_exp_f32_e32 v83, v2
	v_sub_f32_e32 v2, v71, v49
	v_exp_f32_e64 v48, -v49
	v_exp_f32_e32 v13, v2
	v_sub_f32_e32 v2, v88, v49
	v_sub_f32_e32 v3, v89, v49
	v_sub_f32_e32 v4, v90, v49
	v_sub_f32_e32 v5, v91, v49
	v_sub_f32_e32 v6, v92, v49
	v_sub_f32_e32 v7, v93, v49
	v_sub_f32_e32 v8, v94, v49
	v_sub_f32_e32 v9, v95, v49
	v_exp_f32_e32 v14, v2
	v_sub_f32_e32 v2, v72, v49
	v_exp_f32_e32 v15, v3
	v_sub_f32_e32 v3, v73, v49
	v_exp_f32_e32 v64, v4
	v_sub_f32_e32 v4, v74, v49
	v_exp_f32_e32 v65, v5
	v_sub_f32_e32 v5, v75, v49
	v_exp_f32_e32 v66, v6
	v_sub_f32_e32 v6, v76, v49
	v_exp_f32_e32 v67, v7
	v_sub_f32_e32 v7, v77, v49
	v_exp_f32_e32 v68, v8
	v_sub_f32_e32 v8, v78, v49
	v_exp_f32_e32 v69, v9
	v_sub_f32_e32 v9, v79, v49
	v_exp_f32_e32 v2, v2
	v_exp_f32_e32 v3, v3
	v_exp_f32_e32 v4, v4
	v_exp_f32_e32 v5, v5
	v_exp_f32_e32 v6, v6
	v_exp_f32_e32 v7, v7
	v_exp_f32_e32 v8, v8
	v_exp_f32_e32 v9, v9
	v_add_f32_e32 v146, v146, v49
	v_pk_mul_f32 v[46:47], v[46:47], v[48:49] op_sel_hi:[1,0]
	v_pk_mul_f32 v[44:45], v[44:45], v[48:49] op_sel_hi:[1,0]
	v_pk_mul_f32 v[42:43], v[42:43], v[48:49] op_sel_hi:[1,0]
	v_pk_mul_f32 v[40:41], v[40:41], v[48:49] op_sel_hi:[1,0]
	v_pk_mul_f32 v[38:39], v[38:39], v[48:49] op_sel_hi:[1,0]
	v_pk_mul_f32 v[36:37], v[36:37], v[48:49] op_sel_hi:[1,0]
	v_pk_mul_f32 v[34:35], v[34:35], v[48:49] op_sel_hi:[1,0]
	v_pk_mul_f32 v[32:33], v[32:33], v[48:49] op_sel_hi:[1,0]
	v_pk_mul_f32 v[30:31], v[30:31], v[48:49] op_sel_hi:[1,0]
	v_pk_mul_f32 v[28:29], v[28:29], v[48:49] op_sel_hi:[1,0]
	v_pk_mul_f32 v[26:27], v[26:27], v[48:49] op_sel_hi:[1,0]
	v_pk_mul_f32 v[24:25], v[24:25], v[48:49] op_sel_hi:[1,0]
	v_pk_mul_f32 v[22:23], v[22:23], v[48:49] op_sel_hi:[1,0]
	v_pk_mul_f32 v[20:21], v[20:21], v[48:49] op_sel_hi:[1,0]
	v_pk_mul_f32 v[18:19], v[18:19], v[48:49] op_sel_hi:[1,0]
	v_pk_mul_f32 v[16:17], v[16:17], v[48:49] op_sel_hi:[1,0]
	v_mul_f32_e32 v178, v178, v48
	v_xor_b32_e32 v48, 0x80000000, v146
	v_mov_b32_e32 v49, v48
	v_mov_b32_e32 v50, v48
	v_mov_b32_e32 v51, v48
	v_mov_b32_e32 v52, v48
	v_mov_b32_e32 v53, v48
	v_mov_b32_e32 v54, v48
	v_mov_b32_e32 v55, v48
	v_mov_b32_e32 v56, v48
	v_mov_b32_e32 v57, v48
	v_mov_b32_e32 v58, v48
	v_mov_b32_e32 v59, v48
	v_mov_b32_e32 v60, v48
	v_mov_b32_e32 v61, v48
	v_mov_b32_e32 v62, v48
	v_mov_b32_e32 v63, v48
	s_branch .LBB0_615

; DI float ex2(float x) { return __builtin_amdgcn_exp2f(x); }
; template <int MODE>
; DI void flash_pass(AState& st, const bf16x8* qf, u64 tmask, u64 wmask,
;                    const bf16_t* kbase, size_t kld, const bf16_t* kpe, const bf16_t* vtbase, const float* fbias,
;                    int tq, u64 mysel, bf16_t* smem) {
;     ...
;       int im = (int)0x80000000;
; #pragma unroll
;       for (int r = 0; r < 16; ++r) im = max(im, max(__float_as_int(s0[r]), __float_as_int(s1[r])));
;       im = max(im, __shfl_xor(im, 32));
;       constexpr int TBITS = 0x41800000;
;       f32x16 e0, e1;
; #pragma unroll
;       for (int r = 0; r < 16; ++r) { e0[r] = ex2(s0[r]); e1[r] = ex2(s1[r]); }
;       if (__any(im > TBITS)) {
;         const float d = im > TBITS ? __int_as_float(im) : 0.f;
;         const float a = ex2(-d);
; #pragma unroll
;         for (int r = 0; r < 16; ++r) { e0[r] = ex2(s0[r] - d); e1[r] = ex2(s1[r] - d); st.o[0][r] *= a; st.o[1][r] *= a; }
;         st.l *= a; st.m += d;
; #pragma unroll
;         for (int r = 0; r < 16; ++r) st.mr[r] = -st.m;
.LBB0_622:
	s_nop 10
	v_max_i32_e32 v2, v81, v65
	v_max3_i32 v2, v80, v64, v2
	v_max_i32_e32 v3, v82, v66
	v_max_i32_e32 v4, v83, v67
	v_max3_i32 v2, v2, v3, v4
	v_max_i32_e32 v3, v84, v68
	v_max_i32_e32 v4, v85, v69
	v_max3_i32 v2, v2, v3, v4
	v_max_i32_e32 v3, v86, v70
	v_max_i32_e32 v4, v87, v71
	v_max3_i32 v2, v2, v3, v4
	v_max_i32_e32 v3, v88, v72
	v_max_i32_e32 v4, v89, v73
	v_max3_i32 v2, v2, v3, v4
	v_max_i32_e32 v3, v90, v74
	v_max_i32_e32 v4, v91, v75
	v_max3_i32 v2, v2, v3, v4
	v_max_i32_e32 v3, v92, v76
	v_max_i32_e32 v4, v93, v77
	v_max3_i32 v2, v2, v3, v4
	v_max_i32_e32 v3, v94, v78
	v_max_i32_e32 v4, v95, v79
	v_max3_i32 v2, v2, v3, v4
	v_mov_b32_e32 v3, v2
	s_nop 1
	v_permlane32_swap_b32_e32 v3, v2
	v_max_i32_e32 v2, v2, v3
	v_cmp_lt_i32_e32 vcc, s88, v2
	s_cbranch_vccnz .LBB0_603
	v_exp_f32_e32 v151, v80
	v_exp_f32_e32 v147, v64
	v_exp_f32_e32 v152, v81
	v_exp_f32_e32 v148, v65
	v_exp_f32_e32 v153, v82
	v_exp_f32_e32 v149, v66
	v_exp_f32_e32 v154, v83
	v_exp_f32_e32 v150, v67
	v_exp_f32_e32 v80, v84
	v_exp_f32_e32 v10, v68
	v_exp_f32_e32 v81, v85
	v_exp_f32_e32 v11, v69
	v_exp_f32_e32 v82, v86
	v_exp_f32_e32 v12, v70
	v_exp_f32_e32 v83, v87
	v_exp_f32_e32 v13, v71
	v_exp_f32_e32 v14, v88
	v_exp_f32_e32 v2, v72
	v_exp_f32_e32 v15, v89
	v_exp_f32_e32 v3, v73
	v_exp_f32_e32 v64, v90
	v_exp_f32_e32 v4, v74
	v_exp_f32_e32 v65, v91
	v_exp_f32_e32 v5, v75
	v_exp_f32_e32 v66, v92
	v_exp_f32_e32 v6, v76
	v_exp_f32_e32 v67, v93
	v_exp_f32_e32 v7, v77
	v_exp_f32_e32 v68, v94
	v_exp_f32_e32 v8, v78
	v_exp_f32_e32 v69, v95
	v_exp_f32_e32 v9, v79
	s_branch .LBB0_604
.Lxb0:
	s_waitcnt vmcnt(2) lgkmcnt(0)
	s_barrier

; template <int MODE>
; DI void flash_pass(AState& st, const bf16x8* qf, u64 tmask, u64 wmask,
;                    const bf16_t* kbase, size_t kld, const bf16_t* kpe, const bf16_t* vtbase, const float* fbias,
;                    int tq, u64 mysel, bf16_t* smem) {
;     ...
;   auto sstore = [&](int stg, auto setc) {
;     constexpr int S = decltype(setc)::value;
;     bf16_t* Ks = smem + stg * C::STAGE; bf16_t* Vs = Ks + C::K_ELEMS;
; #pragma unroll
;     for (int i = 0; i < C::KCH; ++i) {
;       const int c = tid + NTHR * i;
;       if (c < C::NKC) {
;         if constexpr (MODE == M_MLA) { const int key = c / 12, dc = c % 12; *(u32x4*)(Ks + key * C::KLD + dc * 8) = rk[S][i]; }
;         else { const int key = c >> 3, dc = c & 7; *(u32x4*)(Ks + key * C::KLD + dc * 8) = rk[S][i]; }
;       }
;     }
;     {
;       const int d = tid >> 3, kc = tid & 7, cgp = kc >> 1, a = kc & 1;
;       bf16_t* dst = Vs + d * 72 + cgp * 16 + 4 * a;
;       *(u32x2*)dst = (u32x2){rv[S][0], rv[S][1]}; *(u32x2*)(dst + 8) = (u32x2){rv[S][2], rv[S][3]};
;     }
;     if constexpr (MODE == M_FOX) { if (tid < 64) ((float*)(Vs + C::V_ELEMS))[tid] = rf[S]; }
;   };
;   const int tmin = __builtin_amdgcn_readfirstlane(tq - l31), tmax = tmin + 31;
;   auto compute = [&](int j, int stg) {
;     bool active = (wmask >> j) & 1;
;     if constexpr (MODE == M_SLC) active = active && __any((mysel >> j) & 1);
;     if (active) {
;       const bf16_t* Ks = smem + stg * C::STAGE; const bf16_t* Vs = Ks + C::K_ELEMS;
;       f32x16 s0 = st.mr, s1 = st.mr;
;       const bf16_t* kr = Ks + l31 * C::KLD + half * 8;
; #pragma unroll
;       for (int ks = 0; ks < C::DQK / 16; ++ks) {
;         s0 = mfma32(*(const bf16x8*)(kr + ks * 16), qf[ks], s0);
;         s1 = mfma32(*(const bf16x8*)(kr + 32 * C::KLD + ks * 16), qf[ks], s1);
;       }
;       const int k0 = j * 64;
;       if constexpr (MODE == M_FOX) {
;         const float* fb = (const float*)(Vs + C::V_ELEMS) + 4 * half;
; #pragma unroll
;         for (int g4 = 0; g4 < 4; ++g4) {
;           const f32x4 b0 = *(const f32x4*)(fb + 8 * g4), b1 = *(const f32x4*)(fb + 32 + 8 * g4);
; #pragma unroll
;           for (int r = 0; r < 4; ++r) { s0[4 * g4 + r] += b0[r]; s1[4 * g4 + r] += b1[r]; }
;         }
;       }
;       bool need = k0 + 63 > tmin;
;       if constexpr (MODE == M_WIN) need = need || (k0 <= tmax - 512);
;       if constexpr (MODE == M_SLC) {
.LBB0_632:
	s_mul_i32 s4, s12, 0x2480
	s_xor_b32 s2, s12, 2
	s_mul_i32 s2, s2, 0x2480
	s_nop 0
	s_lshl_b32 s5, s2, 1
	s_and_saveexec_b64 s[2:3], s[0:1]
	s_cbranch_execz .LBB0_634
	v_add3_u32 v0, s5, v183, v168
	s_waitcnt vmcnt(3)
	ds_write_b128 v0, v[148:151]
.LBB0_634:
	s_or_b64 exec, exec, s[2:3]
	s_cmp_eq_u64 s[10:11], 0
	s_cselect_b64 s[8:9], -1, 0
	s_ff1_i32_b64 s17, s[10:11]
	s_and_b64 s[2:3], s[8:9], exec
	s_cselect_b32 s2, s13, s17
	s_lshl_b32 s68, s2, 6
	v_lshl_add_u32 v0, v182, 1, s5
	v_add_u32_e32 v2, s68, v181
	v_add3_u32 v0, v0, v184, v185
	v_ashrrev_i32_e32 v3, 31, v2
	v_add_u32_e32 v0, 0x2000, v0
	v_lshlrev_b64 v[2:3], 8, v[2:3]
	s_waitcnt vmcnt(2)
	ds_write2_b64 v0, v[144:145], v[146:147] offset0:128 offset1:130
	v_lshl_add_u64 v[2:3], v[170:171], 0, v[2:3]
	v_lshl_add_u64 v[4:5], s[68:69], 1, v[172:173]
	global_load_dwordx4 v[148:151], v[2:3], off
	global_load_dwordx4 v[144:147], v[4:5], off
	s_lshl_b64 s[2:3], 1, s13
	s_and_b64 s[20:21], s[2:3], s[6:7]
	s_cmp_eq_u64 s[20:21], 0
	s_cbranch_scc1 .LBB0_645
	v_and_b32_e32 v3, s3, v167
	v_and_b32_e32 v2, s2, v166
	v_cmp_ne_u64_e64 s[2:3], 0, v[2:3]
	s_mov_b64 vcc, s[2:3]
	s_cbranch_vccz .LBB0_645
	v_lshl_add_u32 v0, s4, 1, v187
	ds_read_b128 v[2:5], v0
	s_lshl_b32 s13, s13, 6
	s_or_b32 s4, s13, 63
	s_cmp_gt_i32 s4, s14
	s_cselect_b64 s[4:5], -1, 0
	s_and_b64 vcc, exec, s[4:5]
	s_waitcnt lgkmcnt(0)
	v_mfma_f32_32x32x16_bf16 v[112:127], v[2:5], v[140:143], v[80:95]
	ds_read_b128 v[2:5], v0 offset:4608
	s_waitcnt lgkmcnt(0)
	v_mfma_f32_32x32x16_bf16 v[96:111], v[2:5], v[140:143], v[80:95]
	ds_read_b128 v[2:5], v0 offset:32
	s_waitcnt lgkmcnt(0)
	v_mfma_f32_32x32x16_bf16 v[112:127], v[2:5], v[128:131], v[112:127]
	ds_read_b128 v[2:5], v0 offset:4640
	s_waitcnt lgkmcnt(0)
	v_mfma_f32_32x32x16_bf16 v[96:111], v[2:5], v[128:131], v[96:111]
	ds_read_b128 v[2:5], v0 offset:64
	s_waitcnt lgkmcnt(0)
	v_mfma_f32_32x32x16_bf16 v[112:127], v[2:5], v[132:135], v[112:127]
	ds_read_b128 v[2:5], v0 offset:4672
	s_waitcnt lgkmcnt(0)
	v_mfma_f32_32x32x16_bf16 v[96:111], v[2:5], v[132:135], v[96:111]
	ds_read_b128 v[2:5], v0 offset:96
	s_waitcnt lgkmcnt(0)
	v_mfma_f32_32x32x16_bf16 v[112:127], v[2:5], v[136:139], v[112:127]
	ds_read_b128 v[2:5], v0 offset:4704
	s_waitcnt lgkmcnt(0)
	v_mfma_f32_32x32x16_bf16 v[96:111], v[2:5], v[136:139], v[96:111]
	s_cbranch_vccnz .LBB0_639
	v_cndmask_b32_e64 v2, 0, 1, s[2:3]
	v_cmp_ne_u32_e32 vcc, 0, v2
	s_cmp_eq_u64 vcc, exec
	s_cbranch_scc1 .LBB0_639
	s_nop 3
	v_cndmask_b32_e64 v112, v175, v112, s[2:3]
	s_nop 1
	v_cndmask_b32_e64 v96, v175, v96, s[2:3]
	v_cndmask_b32_e64 v113, v175, v113, s[2:3]
	v_cndmask_b32_e64 v97, v175, v97, s[2:3]
	v_cndmask_b32_e64 v114, v175, v114, s[2:3]
	v_cndmask_b32_e64 v98, v175, v98, s[2:3]
	v_cndmask_b32_e64 v115, v175, v115, s[2:3]
	v_cndmask_b32_e64 v99, v175, v99, s[2:3]
	v_cndmask_b32_e64 v116, v175, v116, s[2:3]
	v_cndmask_b32_e64 v100, v175, v100, s[2:3]
	v_cndmask_b32_e64 v117, v175, v117, s[2:3]
	v_cndmask_b32_e64 v101, v175, v101, s[2:3]
	v_cndmask_b32_e64 v118, v175, v118, s[2:3]
	v_cndmask_b32_e64 v102, v175, v102, s[2:3]
	v_cndmask_b32_e64 v119, v175, v119, s[2:3]
	v_cndmask_b32_e64 v103, v175, v103, s[2:3]
	v_cndmask_b32_e64 v120, v175, v120, s[2:3]
	v_cndmask_b32_e64 v104, v175, v104, s[2:3]
	v_cndmask_b32_e64 v121, v175, v121, s[2:3]
	v_cndmask_b32_e64 v105, v175, v105, s[2:3]
	v_cndmask_b32_e64 v122, v175, v122, s[2:3]
	v_cndmask_b32_e64 v106, v175, v106, s[2:3]
	v_cndmask_b32_e64 v123, v175, v123, s[2:3]
	v_cndmask_b32_e64 v107, v175, v107, s[2:3]
	v_cndmask_b32_e64 v124, v175, v124, s[2:3]
	v_cndmask_b32_e64 v108, v175, v108, s[2:3]
	v_cndmask_b32_e64 v125, v175, v125, s[2:3]
	v_cndmask_b32_e64 v109, v175, v109, s[2:3]
	v_cndmask_b32_e64 v126, v175, v126, s[2:3]
	v_cndmask_b32_e64 v110, v175, v110, s[2:3]
	v_cndmask_b32_e64 v127, v175, v127, s[2:3]
	v_cndmask_b32_e64 v111, v175, v111, s[2:3]

; DI float ex2(float x) { return __builtin_amdgcn_exp2f(x); }
; template <int MODE>
; DI void flash_pass(AState& st, const bf16x8* qf, u64 tmask, u64 wmask,
;                    const bf16_t* kbase, size_t kld, const bf16_t* kpe, const bf16_t* vtbase, const float* fbias,
;                    int tq, u64 mysel, bf16_t* smem) {
;     ...
;       int im = (int)0x80000000;
; #pragma unroll
;       for (int r = 0; r < 16; ++r) im = max(im, max(__float_as_int(s0[r]), __float_as_int(s1[r])));
;       im = max(im, __shfl_xor(im, 32));
;       constexpr int TBITS = 0x41800000;
;       f32x16 e0, e1;
; #pragma unroll
;       for (int r = 0; r < 16; ++r) { e0[r] = ex2(s0[r]); e1[r] = ex2(s1[r]); }
;       if (__any(im > TBITS)) {
;         const float d = im > TBITS ? __int_as_float(im) : 0.f;
;         const float a = ex2(-d);
; #pragma unroll
;         for (int r = 0; r < 16; ++r) { e0[r] = ex2(s0[r] - d); e1[r] = ex2(s1[r] - d); st.o[0][r] *= a; st.o[1][r] *= a; }
;         st.l *= a; st.m += d;
; #pragma unroll
;         for (int r = 0; r < 16; ++r) st.mr[r] = -st.m;
;       }
.LBB0_641:
	s_nop 8
	v_max_i32_e32 v2, v113, v97
	v_max3_i32 v2, v112, v96, v2
	v_max_i32_e32 v3, v114, v98
	v_max_i32_e32 v4, v115, v99
	v_max3_i32 v2, v2, v3, v4
	v_max_i32_e32 v3, v116, v100
	v_max_i32_e32 v4, v117, v101
	v_max3_i32 v2, v2, v3, v4
	v_max_i32_e32 v3, v118, v102
	v_max_i32_e32 v4, v119, v103
	v_max3_i32 v2, v2, v3, v4
	v_max_i32_e32 v3, v120, v104
	v_max_i32_e32 v4, v121, v105
	v_max3_i32 v2, v2, v3, v4
	v_max_i32_e32 v3, v122, v106
	v_max_i32_e32 v4, v123, v107
	v_max3_i32 v2, v2, v3, v4
	v_max_i32_e32 v3, v124, v108
	v_max_i32_e32 v4, v125, v109
	v_max3_i32 v2, v2, v3, v4
	v_max_i32_e32 v3, v126, v110
	v_max_i32_e32 v4, v127, v111
	v_max3_i32 v2, v2, v3, v4
	v_mov_b32_e32 v3, v2
	s_nop 1
	v_permlane32_swap_b32_e32 v3, v2
	v_max_i32_e32 v2, v2, v3
	v_cmp_lt_i32_e32 vcc, s88, v2
	s_cbranch_vccz .LBB0_643
	s_nop 0
	v_cndmask_b32_e32 v81, 0, v2, vcc
	v_sub_f32_e32 v2, v112, v81
	v_exp_f32_e32 v194, v2
	v_sub_f32_e32 v2, v96, v81
	v_exp_f32_e32 v189, v2
	v_sub_f32_e32 v2, v113, v81
	v_exp_f32_e32 v192, v2
	v_sub_f32_e32 v2, v97, v81
	v_exp_f32_e32 v190, v2
	v_sub_f32_e32 v2, v114, v81
	v_exp_f32_e32 v191, v2
	v_sub_f32_e32 v2, v98, v81
	v_sub_f32_e32 v82, v124, v81
	v_exp_f32_e32 v114, v2
	v_sub_f32_e32 v2, v115, v81
	v_exp_f32_e32 v96, v82
	v_sub_f32_e32 v82, v108, v81
	v_exp_f32_e32 v193, v2
	v_sub_f32_e32 v2, v99, v81
	v_exp_f32_e32 v98, v82
	v_sub_f32_e32 v82, v125, v81
	v_exp_f32_e32 v115, v2
	v_sub_f32_e32 v2, v116, v81
	v_exp_f32_e32 v97, v82
	v_sub_f32_e32 v82, v109, v81
	v_exp_f32_e32 v112, v2
	v_sub_f32_e32 v2, v100, v81
	v_exp_f32_e32 v99, v82
	v_sub_f32_e32 v82, v126, v81
	v_exp_f32_e32 v8, v2
	v_sub_f32_e32 v2, v117, v81
	v_sub_f32_e32 v4, v103, v81
	v_exp_f32_e32 v100, v82
	v_sub_f32_e32 v82, v110, v81
	v_exp_f32_e64 v80, -v81
	v_exp_f32_e32 v113, v2
	v_sub_f32_e32 v2, v101, v81
	v_sub_f32_e32 v3, v102, v81
	v_exp_f32_e32 v7, v4
	v_sub_f32_e32 v4, v120, v81
	v_sub_f32_e32 v5, v121, v81
	v_sub_f32_e32 v12, v122, v81
	v_sub_f32_e32 v13, v123, v81
	v_exp_f32_e32 v102, v82
	v_sub_f32_e32 v82, v127, v81
	v_exp_f32_e32 v9, v2
	v_sub_f32_e32 v2, v118, v81
	v_exp_f32_e32 v6, v3
	v_sub_f32_e32 v3, v119, v81
	v_exp_f32_e32 v10, v4
	v_sub_f32_e32 v4, v104, v81
	v_exp_f32_e32 v11, v5
	v_sub_f32_e32 v5, v105, v81
	v_exp_f32_e32 v14, v12
	v_sub_f32_e32 v12, v106, v81
	v_exp_f32_e32 v15, v13
	v_sub_f32_e32 v13, v107, v81
	v_exp_f32_e32 v101, v82
	v_sub_f32_e32 v82, v111, v81
	v_exp_f32_e32 v2, v2
	v_exp_f32_e32 v3, v3
	v_exp_f32_e32 v4, v4
	v_exp_f32_e32 v5, v5
	v_exp_f32_e32 v12, v12
	v_exp_f32_e32 v13, v13
	v_exp_f32_e32 v103, v82
	v_add_f32_e32 v188, v188, v81
	v_pk_mul_f32 v[78:79], v[78:79], v[80:81] op_sel_hi:[1,0]
	v_pk_mul_f32 v[76:77], v[76:77], v[80:81] op_sel_hi:[1,0]
	v_pk_mul_f32 v[74:75], v[74:75], v[80:81] op_sel_hi:[1,0]
	v_pk_mul_f32 v[72:73], v[72:73], v[80:81] op_sel_hi:[1,0]
	v_pk_mul_f32 v[70:71], v[70:71], v[80:81] op_sel_hi:[1,0]
	v_pk_mul_f32 v[68:69], v[68:69], v[80:81] op_sel_hi:[1,0]
	v_pk_mul_f32 v[66:67], v[66:67], v[80:81] op_sel_hi:[1,0]
	v_pk_mul_f32 v[64:65], v[64:65], v[80:81] op_sel_hi:[1,0]
	v_pk_mul_f32 v[62:63], v[62:63], v[80:81] op_sel_hi:[1,0]
	v_pk_mul_f32 v[60:61], v[60:61], v[80:81] op_sel_hi:[1,0]
	v_pk_mul_f32 v[58:59], v[58:59], v[80:81] op_sel_hi:[1,0]
	v_pk_mul_f32 v[56:57], v[56:57], v[80:81] op_sel_hi:[1,0]
	v_pk_mul_f32 v[54:55], v[54:55], v[80:81] op_sel_hi:[1,0]
	v_pk_mul_f32 v[52:53], v[52:53], v[80:81] op_sel_hi:[1,0]
	v_pk_mul_f32 v[50:51], v[50:51], v[80:81] op_sel_hi:[1,0]
	v_pk_mul_f32 v[48:49], v[48:49], v[80:81] op_sel_hi:[1,0]
	v_mul_f32_e32 v169, v169, v80
	v_xor_b32_e32 v80, 0x80000000, v188
	v_mov_b32_e32 v81, v80
	v_mov_b32_e32 v82, v80
	v_mov_b32_e32 v83, v80
	v_mov_b32_e32 v84, v80
	v_mov_b32_e32 v85, v80
	v_mov_b32_e32 v86, v80
	v_mov_b32_e32 v87, v80
	v_mov_b32_e32 v88, v80
	v_mov_b32_e32 v89, v80
	v_mov_b32_e32 v90, v80
	v_mov_b32_e32 v91, v80
	v_mov_b32_e32 v92, v80
	v_mov_b32_e32 v93, v80
	v_mov_b32_e32 v94, v80
	v_mov_b32_e32 v95, v80
	s_branch .LBB0_644

; DI float ex2(float x) { return __builtin_amdgcn_exp2f(x); }
; template <int MODE>
; DI void flash_pass(AState& st, const bf16x8* qf, u64 tmask, u64 wmask,
;                    const bf16_t* kbase, size_t kld, const bf16_t* kpe, const bf16_t* vtbase, const float* fbias,
;                    int tq, u64 mysel, bf16_t* smem) {
;     ...
;       int im = (int)0x80000000;
; #pragma unroll
;       for (int r = 0; r < 16; ++r) im = max(im, max(__float_as_int(s0[r]), __float_as_int(s1[r])));
;       im = max(im, __shfl_xor(im, 32));
;       constexpr int TBITS = 0x41800000;
;       f32x16 e0, e1;
; #pragma unroll
;       for (int r = 0; r < 16; ++r) { e0[r] = ex2(s0[r]); e1[r] = ex2(s1[r]); }
;       if (__any(im > TBITS)) {
;         const float d = im > TBITS ? __int_as_float(im) : 0.f;
;         const float a = ex2(-d);
; #pragma unroll
;         for (int r = 0; r < 16; ++r) { e0[r] = ex2(s0[r] - d); e1[r] = ex2(s1[r] - d); st.o[0][r] *= a; st.o[1][r] *= a; }
;         st.l *= a; st.m += d;
; #pragma unroll
;         for (int r = 0; r < 16; ++r) st.mr[r] = -st.m;
;       }
.LBB0_675:
	v_max_i32_e32 v90, v157, v161
	v_max3_i32 v90, v156, v160, v90
	v_max_i32_e32 v91, v158, v96
	v_max_i32_e32 v92, v159, v97
	v_max3_i32 v90, v90, v91, v92
	v_max_i32_e32 v91, v14, v10
	v_max_i32_e32 v92, v15, v11
	v_max3_i32 v90, v90, v91, v92
	v_max_i32_e32 v91, v84, v80
	v_max_i32_e32 v92, v85, v81
	v_max3_i32 v90, v90, v91, v92
	v_max_i32_e32 v91, v88, v86
	v_max_i32_e32 v92, v89, v87
	v_max3_i32 v90, v90, v91, v92
	v_max_i32_e32 v91, v82, v12
	v_max_i32_e32 v92, v83, v13
	v_max3_i32 v90, v90, v91, v92
	v_max_i32_e32 v91, v8, v6
	v_max_i32_e32 v92, v9, v7
	v_max3_i32 v90, v90, v91, v92
	v_max_i32_e32 v91, v2, v4
	v_max_i32_e32 v92, v3, v5
	v_max3_i32 v90, v90, v91, v92
	v_mov_b32_e32 v91, v90
	s_nop 1
	v_permlane32_swap_b32_e32 v91, v90
	v_max_i32_e32 v90, v90, v91
	v_cmp_lt_i32_e32 vcc, s88, v90
	s_cbranch_vccz .LBB0_704
	s_nop 0
	v_cndmask_b32_e32 v65, 0, v90, vcc
	v_sub_f32_e32 v66, v156, v65
	v_exp_f32_e32 v98, v66
	v_sub_f32_e32 v66, v160, v65
	v_sub_f32_e32 v14, v14, v65
	v_sub_f32_e32 v10, v10, v65
	v_exp_f32_e32 v94, v66
	v_sub_f32_e32 v66, v157, v65
	v_exp_f32_e32 v90, v14
	v_exp_f32_e32 v14, v10
	v_sub_f32_e32 v10, v15, v65
	v_exp_f32_e32 v99, v66
	v_sub_f32_e32 v66, v161, v65
	v_exp_f32_e32 v91, v10
	v_sub_f32_e32 v10, v11, v65
	v_exp_f32_e32 v95, v66
	v_sub_f32_e32 v66, v158, v65
	v_exp_f32_e32 v15, v10
	v_sub_f32_e32 v10, v84, v65
	v_exp_f32_e32 v100, v66
	v_sub_f32_e32 v66, v96, v65
	v_exp_f32_e32 v92, v10
	v_sub_f32_e32 v10, v80, v65
	v_exp_f32_e32 v96, v66
	v_sub_f32_e32 v66, v159, v65
	v_exp_f32_e32 v80, v10
	v_sub_f32_e32 v10, v85, v65
	v_exp_f32_e32 v101, v66
	v_sub_f32_e32 v66, v97, v65
	v_exp_f32_e32 v93, v10
	v_sub_f32_e32 v10, v81, v65
	v_exp_f32_e64 v64, -v65
	v_exp_f32_e32 v97, v66
	v_exp_f32_e32 v81, v10
	v_sub_f32_e32 v10, v88, v65
	v_sub_f32_e32 v11, v89, v65
	v_sub_f32_e32 v66, v82, v65
	v_sub_f32_e32 v2, v2, v65
	v_sub_f32_e32 v3, v3, v65
	v_exp_f32_e32 v84, v10
	v_sub_f32_e32 v10, v86, v65
	v_exp_f32_e32 v85, v11
	v_sub_f32_e32 v11, v87, v65
	v_exp_f32_e32 v82, v66
	v_sub_f32_e32 v12, v12, v65
	v_sub_f32_e32 v66, v83, v65
	v_sub_f32_e32 v13, v13, v65
	v_sub_f32_e32 v8, v8, v65
	v_sub_f32_e32 v6, v6, v65
	v_sub_f32_e32 v9, v9, v65
	v_sub_f32_e32 v7, v7, v65
	v_exp_f32_e32 v86, v2
	v_sub_f32_e32 v2, v4, v65
	v_exp_f32_e32 v87, v3
	v_sub_f32_e32 v3, v5, v65
	v_exp_f32_e32 v10, v10
	v_exp_f32_e32 v11, v11
	v_exp_f32_e32 v12, v12
	v_exp_f32_e32 v83, v66
	v_exp_f32_e32 v13, v13
	v_exp_f32_e32 v8, v8
	v_exp_f32_e32 v6, v6
	v_exp_f32_e32 v9, v9
	v_exp_f32_e32 v7, v7
	v_exp_f32_e32 v2, v2
	v_exp_f32_e32 v3, v3
	v_add_f32_e32 v177, v177, v65
	v_pk_mul_f32 v[46:47], v[46:47], v[64:65] op_sel_hi:[1,0]
	v_pk_mul_f32 v[44:45], v[44:45], v[64:65] op_sel_hi:[1,0]
	v_pk_mul_f32 v[42:43], v[42:43], v[64:65] op_sel_hi:[1,0]
	v_pk_mul_f32 v[40:41], v[40:41], v[64:65] op_sel_hi:[1,0]
	v_pk_mul_f32 v[38:39], v[38:39], v[64:65] op_sel_hi:[1,0]
	v_pk_mul_f32 v[36:37], v[36:37], v[64:65] op_sel_hi:[1,0]
	v_pk_mul_f32 v[34:35], v[34:35], v[64:65] op_sel_hi:[1,0]
	v_pk_mul_f32 v[32:33], v[32:33], v[64:65] op_sel_hi:[1,0]
	v_pk_mul_f32 v[30:31], v[30:31], v[64:65] op_sel_hi:[1,0]
	v_pk_mul_f32 v[28:29], v[28:29], v[64:65] op_sel_hi:[1,0]
	v_pk_mul_f32 v[26:27], v[26:27], v[64:65] op_sel_hi:[1,0]
	v_pk_mul_f32 v[24:25], v[24:25], v[64:65] op_sel_hi:[1,0]
	v_pk_mul_f32 v[22:23], v[22:23], v[64:65] op_sel_hi:[1,0]
	v_pk_mul_f32 v[20:21], v[20:21], v[64:65] op_sel_hi:[1,0]
	v_pk_mul_f32 v[18:19], v[18:19], v[64:65] op_sel_hi:[1,0]
	v_pk_mul_f32 v[16:17], v[16:17], v[64:65] op_sel_hi:[1,0]
	v_mul_f32_e32 v176, v176, v64
	v_xor_b32_e32 v64, 0x80000000, v177
	v_mov_b32_e32 v65, v64
	v_mov_b32_e32 v66, v64
	v_mov_b32_e32 v67, v64
	v_mov_b32_e32 v68, v64
	v_mov_b32_e32 v69, v64
	v_mov_b32_e32 v70, v64
	v_mov_b32_e32 v71, v64
	v_mov_b32_e32 v72, v64
	v_mov_b32_e32 v73, v64
	v_mov_b32_e32 v74, v64
	v_mov_b32_e32 v75, v64
	v_mov_b32_e32 v76, v64
	v_mov_b32_e32 v77, v64
	v_mov_b32_e32 v78, v64
	v_mov_b32_e32 v79, v64

; template <int MODE>
; DI void flash_pass(AState& st, const bf16x8* qf, u64 tmask, u64 wmask,
;                    const bf16_t* kbase, size_t kld, const bf16_t* kpe, const bf16_t* vtbase, const float* fbias,
;                    int tq, u64 mysel, bf16_t* smem) {
;     ...
;   auto sstore = [&](int stg, auto setc) {
;     constexpr int S = decltype(setc)::value;
;     bf16_t* Ks = smem + stg * C::STAGE; bf16_t* Vs = Ks + C::K_ELEMS;
; #pragma unroll
;     for (int i = 0; i < C::KCH; ++i) {
;       const int c = tid + NTHR * i;
;       if (c < C::NKC) {
;         if constexpr (MODE == M_MLA) { const int key = c / 12, dc = c % 12; *(u32x4*)(Ks + key * C::KLD + dc * 8) = rk[S][i]; }
;         else { const int key = c >> 3, dc = c & 7; *(u32x4*)(Ks + key * C::KLD + dc * 8) = rk[S][i]; }
;       }
;     }
;     {
;       const int d = tid >> 3, kc = tid & 7, cgp = kc >> 1, a = kc & 1;
;       bf16_t* dst = Vs + d * 72 + cgp * 16 + 4 * a;
;       *(u32x2*)dst = (u32x2){rv[S][0], rv[S][1]}; *(u32x2*)(dst + 8) = (u32x2){rv[S][2], rv[S][3]};
;     }
;     if constexpr (MODE == M_FOX) { if (tid < 64) ((float*)(Vs + C::V_ELEMS))[tid] = rf[S]; }
;   };
.LBB0_680:
	s_mul_i32 s6, s82, 0x2480
	s_xor_b32 s4, s82, 2
	s_mul_i32 s4, s4, 0x2480
	s_nop 0
	s_lshl_b32 s7, s4, 1
	s_and_saveexec_b64 s[4:5], s[0:1]
	s_cbranch_execz .LBB0_682
	v_add3_u32 v0, s7, v167, v148
	s_waitcnt vmcnt(5)
	ds_write_b128 v0, v[128:131]
.LBB0_682:
	s_or_b64 exec, exec, s[4:5]
	v_lshl_add_u32 v0, v166, 1, s7
	v_add3_u32 v0, v0, v168, v169
	v_add_u32_e32 v0, 0x2000, v0
	s_waitcnt vmcnt(4)
	ds_write2_b64 v0, v[132:133], v[134:135] offset0:128 offset1:130
	s_and_saveexec_b64 s[4:5], s[2:3]
	s_cbranch_execz .LBB0_684
	v_lshl_add_u32 v0, v163, 2, s7
	s_waitcnt vmcnt(3)
	ds_write_b32 v0, v170 offset:18432

; DI float ex2(float x) { return __builtin_amdgcn_exp2f(x); }
; template <int MODE>
; DI void flash_pass(AState& st, const bf16x8* qf, u64 tmask, u64 wmask,
;                    const bf16_t* kbase, size_t kld, const bf16_t* kpe, const bf16_t* vtbase, const float* fbias,
;                    int tq, u64 mysel, bf16_t* smem) {
;     ...
;       int im = (int)0x80000000;
; #pragma unroll
;       for (int r = 0; r < 16; ++r) im = max(im, max(__float_as_int(s0[r]), __float_as_int(s1[r])));
;       im = max(im, __shfl_xor(im, 32));
;       constexpr int TBITS = 0x41800000;
;       f32x16 e0, e1;
; #pragma unroll
;       for (int r = 0; r < 16; ++r) { e0[r] = ex2(s0[r]); e1[r] = ex2(s1[r]); }
;       if (__any(im > TBITS)) {
;         const float d = im > TBITS ? __int_as_float(im) : 0.f;
;         const float a = ex2(-d);
; #pragma unroll
;         for (int r = 0; r < 16; ++r) { e0[r] = ex2(s0[r] - d); e1[r] = ex2(s1[r] - d); st.o[0][r] *= a; st.o[1][r] *= a; }
;         st.l *= a; st.m += d;
; #pragma unroll
;         for (int r = 0; r < 16; ++r) st.mr[r] = -st.m;
;       }
.LBB0_689:
	v_max_i32_e32 v90, v157, v161
	v_max3_i32 v90, v156, v160, v90
	v_max_i32_e32 v91, v158, v96
	v_max_i32_e32 v92, v159, v97
	v_max3_i32 v90, v90, v91, v92
	v_max_i32_e32 v91, v14, v10
	v_max_i32_e32 v92, v15, v11
	v_max3_i32 v90, v90, v91, v92
	v_max_i32_e32 v91, v84, v80
	v_max_i32_e32 v92, v85, v81
	v_max3_i32 v90, v90, v91, v92
	v_max_i32_e32 v91, v88, v86
	v_max_i32_e32 v92, v89, v87
	v_max3_i32 v90, v90, v91, v92
	v_max_i32_e32 v91, v82, v12
	v_max_i32_e32 v92, v83, v13
	v_max3_i32 v90, v90, v91, v92
	v_max_i32_e32 v91, v8, v6
	v_max_i32_e32 v92, v9, v7
	v_max3_i32 v90, v90, v91, v92
	v_max_i32_e32 v91, v2, v4
	v_max_i32_e32 v92, v3, v5
	v_max3_i32 v90, v90, v91, v92
	v_mov_b32_e32 v91, v90
	s_nop 1
	v_permlane32_swap_b32_e32 v91, v90
	v_max_i32_e32 v90, v90, v91
	v_cmp_lt_i32_e32 vcc, s88, v90
	s_cbranch_vccz .LBB0_691
	s_nop 0
	v_cndmask_b32_e32 v65, 0, v90, vcc
	v_sub_f32_e32 v66, v156, v65
	v_exp_f32_e32 v98, v66
	v_sub_f32_e32 v66, v160, v65
	v_sub_f32_e32 v14, v14, v65
	v_sub_f32_e32 v10, v10, v65
	v_exp_f32_e32 v94, v66
	v_sub_f32_e32 v66, v157, v65
	v_exp_f32_e32 v90, v14
	v_exp_f32_e32 v14, v10
	v_sub_f32_e32 v10, v15, v65
	v_exp_f32_e32 v99, v66
	v_sub_f32_e32 v66, v161, v65
	v_exp_f32_e32 v91, v10
	v_sub_f32_e32 v10, v11, v65
	v_exp_f32_e32 v95, v66
	v_sub_f32_e32 v66, v158, v65
	v_exp_f32_e32 v15, v10
	v_sub_f32_e32 v10, v84, v65
	v_exp_f32_e32 v100, v66
	v_sub_f32_e32 v66, v96, v65
	v_exp_f32_e32 v92, v10
	v_sub_f32_e32 v10, v80, v65
	v_exp_f32_e32 v96, v66
	v_sub_f32_e32 v66, v159, v65
	v_exp_f32_e32 v80, v10
	v_sub_f32_e32 v10, v85, v65
	v_exp_f32_e32 v101, v66
	v_sub_f32_e32 v66, v97, v65
	v_exp_f32_e32 v93, v10
	v_sub_f32_e32 v10, v81, v65
	v_exp_f32_e64 v64, -v65
	v_exp_f32_e32 v97, v66
	v_exp_f32_e32 v81, v10
	v_sub_f32_e32 v10, v88, v65
	v_sub_f32_e32 v11, v89, v65
	v_sub_f32_e32 v66, v82, v65
	v_sub_f32_e32 v2, v2, v65
	v_sub_f32_e32 v3, v3, v65
	v_exp_f32_e32 v84, v10
	v_sub_f32_e32 v10, v86, v65
	v_exp_f32_e32 v85, v11
	v_sub_f32_e32 v11, v87, v65
	v_exp_f32_e32 v82, v66
	v_sub_f32_e32 v12, v12, v65
	v_sub_f32_e32 v66, v83, v65
	v_sub_f32_e32 v13, v13, v65
	v_sub_f32_e32 v8, v8, v65
	v_sub_f32_e32 v6, v6, v65
	v_sub_f32_e32 v9, v9, v65
	v_sub_f32_e32 v7, v7, v65
	v_exp_f32_e32 v86, v2
	v_sub_f32_e32 v2, v4, v65
	v_exp_f32_e32 v87, v3
	v_sub_f32_e32 v3, v5, v65
	v_exp_f32_e32 v10, v10
	v_exp_f32_e32 v11, v11
	v_exp_f32_e32 v12, v12
	v_exp_f32_e32 v83, v66
	v_exp_f32_e32 v13, v13
	v_exp_f32_e32 v8, v8
	v_exp_f32_e32 v6, v6
	v_exp_f32_e32 v9, v9
	v_exp_f32_e32 v7, v7
	v_exp_f32_e32 v2, v2
	v_exp_f32_e32 v3, v3
	v_add_f32_e32 v177, v177, v65
	v_pk_mul_f32 v[46:47], v[46:47], v[64:65] op_sel_hi:[1,0]
	v_pk_mul_f32 v[44:45], v[44:45], v[64:65] op_sel_hi:[1,0]
	v_pk_mul_f32 v[42:43], v[42:43], v[64:65] op_sel_hi:[1,0]
	v_pk_mul_f32 v[40:41], v[40:41], v[64:65] op_sel_hi:[1,0]
	v_pk_mul_f32 v[38:39], v[38:39], v[64:65] op_sel_hi:[1,0]
	v_pk_mul_f32 v[36:37], v[36:37], v[64:65] op_sel_hi:[1,0]
	v_pk_mul_f32 v[34:35], v[34:35], v[64:65] op_sel_hi:[1,0]
	v_pk_mul_f32 v[32:33], v[32:33], v[64:65] op_sel_hi:[1,0]
	v_pk_mul_f32 v[30:31], v[30:31], v[64:65] op_sel_hi:[1,0]
	v_pk_mul_f32 v[28:29], v[28:29], v[64:65] op_sel_hi:[1,0]
	v_pk_mul_f32 v[26:27], v[26:27], v[64:65] op_sel_hi:[1,0]
	v_pk_mul_f32 v[24:25], v[24:25], v[64:65] op_sel_hi:[1,0]
	v_pk_mul_f32 v[22:23], v[22:23], v[64:65] op_sel_hi:[1,0]
	v_pk_mul_f32 v[20:21], v[20:21], v[64:65] op_sel_hi:[1,0]
	v_pk_mul_f32 v[18:19], v[18:19], v[64:65] op_sel_hi:[1,0]
	v_pk_mul_f32 v[16:17], v[16:17], v[64:65] op_sel_hi:[1,0]
	v_mul_f32_e32 v176, v176, v64
	v_xor_b32_e32 v64, 0x80000000, v177
	v_mov_b32_e32 v65, v64
	v_mov_b32_e32 v66, v64
	v_mov_b32_e32 v67, v64
	v_mov_b32_e32 v68, v64
	v_mov_b32_e32 v69, v64
	v_mov_b32_e32 v70, v64
	v_mov_b32_e32 v71, v64
	v_mov_b32_e32 v72, v64
	v_mov_b32_e32 v73, v64
	v_mov_b32_e32 v74, v64
	v_mov_b32_e32 v75, v64
	v_mov_b32_e32 v76, v64
	v_mov_b32_e32 v77, v64
	v_mov_b32_e32 v78, v64
	v_mov_b32_e32 v79, v64
	s_branch .LBB0_692

; template <int MODE>
; DI void flash_pass(AState& st, const bf16x8* qf, u64 tmask, u64 wmask,
;                    const bf16_t* kbase, size_t kld, const bf16_t* kpe, const bf16_t* vtbase, const float* fbias,
;                    int tq, u64 mysel, bf16_t* smem) {
;     ...
;     __syncthreads();
.Lxb2:
	s_waitcnt vmcnt(3) lgkmcnt(0)
	s_barrier

; template <int MODE>
; DI void flash_pass(AState& st, const bf16x8* qf, u64 tmask, u64 wmask,
;                    const bf16_t* kbase, size_t kld, const bf16_t* kpe, const bf16_t* vtbase, const float* fbias,
;                    int tq, u64 mysel, bf16_t* smem) {
;     ...
;     for (int i = 0; i < C::KCH; ++i) {
;       const int c0 = tid + NTHR * i, c = c0 < C::NKC ? c0 : C::NKC - 1;
;       if constexpr (MODE == M_MLA) {
;         const int key = c / 12, dc = c % 12;
;         const bf16_t* src = dc < 8 ? kbase + (size_t)(k0 + key) * kld + dc * 8 : kpe + (size_t)(k0 + key) * 32 + (dc - 8) * 8;
;         rk[S][i] = *(const u32x4*)src;
;       } else { const int key = c >> 3, dc = c & 7; rk[S][i] = *(const u32x4*)(kbase + (size_t)(k0 + key) * kld + dc * 8); }
;     }
;     { const int d = tid >> 3, kc = tid & 7; rv[S] = *(const u32x4*)(vtbase + (size_t)d * S_ + k0 + kc * 8); }
;     if constexpr (MODE == M_FOX) rf[S] = fbias[k0 + (tid & 63)];
;   };
;   auto sstore = [&](int stg, auto setc) {
;     constexpr int S = decltype(setc)::value;
;     bf16_t* Ks = smem + stg * C::STAGE; bf16_t* Vs = Ks + C::K_ELEMS;
; #pragma unroll
;     for (int i = 0; i < C::KCH; ++i) {
;       const int c = tid + NTHR * i;
;       if (c < C::NKC) {
;         if constexpr (MODE == M_MLA) { const int key = c / 12, dc = c % 12; *(u32x4*)(Ks + key * C::KLD + dc * 8) = rk[S][i]; }
;         else { const int key = c >> 3, dc = c & 7; *(u32x4*)(Ks + key * C::KLD + dc * 8) = rk[S][i]; }
;       }
;     }
;     {
;       const int d = tid >> 3, kc = tid & 7, cgp = kc >> 1, a = kc & 1;
;       bf16_t* dst = Vs + d * 72 + cgp * 16 + 4 * a;
;       *(u32x2*)dst = (u32x2){rv[S][0], rv[S][1]}; *(u32x2*)(dst + 8) = (u32x2){rv[S][2], rv[S][3]};
;     }
;     if constexpr (MODE == M_FOX) { if (tid < 64) ((float*)(Vs + C::V_ELEMS))[tid] = rf[S]; }
;   };
;     ...
;       const bf16_t* Ks = smem + stg * C::STAGE; const bf16_t* Vs = Ks + C::K_ELEMS;
;       f32x16 s0 = st.mr, s1 = st.mr;
;       const bf16_t* kr = Ks + l31 * C::KLD + half * 8;
; #pragma unroll
;       for (int ks = 0; ks < C::DQK / 16; ++ks) {
;         s0 = mfma32(*(const bf16x8*)(kr + ks * 16), qf[ks], s0);
;         s1 = mfma32(*(const bf16x8*)(kr + 32 * C::KLD + ks * 16), qf[ks], s1);
;       }
;       const int k0 = j * 64;
;       if constexpr (MODE == M_FOX) {
;         const float* fb = (const float*)(Vs + C::V_ELEMS) + 4 * half;
.LBB0_750:
	s_mul_i32 s14, s18, 0x2c80
	s_xor_b32 s8, s18, 2
	s_mul_i32 s8, s8, 0x2c80
	s_nop 0
	s_lshl_b32 s12, s8, 1
	s_and_saveexec_b64 s[8:9], s[4:5]
	s_cbranch_execz .LBB0_752
	v_lshlrev_b32_e32 v2, 1, v165
	v_lshlrev_b32_e32 v3, 1, v166
	v_add3_u32 v2, s12, v2, v3
	s_waitcnt vmcnt(5)
	ds_write_b128 v2, v[120:123]
.LBB0_752:
	s_or_b64 exec, exec, s[8:9]
	s_and_saveexec_b64 s[8:9], s[6:7]
	s_cbranch_execz .LBB0_754
	v_lshlrev_b32_e32 v2, 1, v167
	v_lshlrev_b32_e32 v3, 1, v168
	v_add3_u32 v2, s12, v2, v3
	s_waitcnt vmcnt(4)
	ds_write_b128 v2, v[128:131]
.LBB0_754:
	s_or_b64 exec, exec, s[8:9]
	s_cmp_eq_u64 s[10:11], 0
	s_cselect_b64 s[8:9], -1, 0
	s_ff1_i32_b64 s19, s[10:11]
	v_lshl_add_u32 v2, v162, 1, s12
	v_lshlrev_b32_e32 v176, 1, v164
	s_and_b64 s[12:13], s[8:9], exec
	v_add3_u32 v2, v2, v163, v176
	s_cselect_b32 s12, s25, s19
	v_add_u32_e32 v2, 0x3000, v2
	s_lshl_b32 s68, s12, 6
	s_waitcnt vmcnt(3)
	ds_write2_b64 v2, v[124:125], v[126:127] offset0:128 offset1:130
	v_add_u32_e32 v2, s68, v147
	v_ashrrev_i32_e32 v3, 31, v2
	v_lshlrev_b64 v[4:5], 10, v[2:3]
	v_lshlrev_b64 v[2:3], 6, v[2:3]
	v_lshl_add_u64 v[2:3], v[152:153], 0, v[2:3]
	v_lshl_add_u64 v[4:5], v[154:155], 0, v[4:5]
	v_lshl_add_u64 v[2:3], v[2:3], 0, s[70:71]
	v_cndmask_b32_e64 v3, v3, v5, s[0:1]
	v_cndmask_b32_e64 v2, v2, v4, s[0:1]
	global_load_dwordx4 v[120:123], v[2:3], off
	v_add_u32_e32 v2, s68, v161
	v_ashrrev_i32_e32 v3, 31, v2
	v_lshlrev_b64 v[4:5], 10, v[2:3]
	v_lshlrev_b64 v[2:3], 6, v[2:3]
	v_lshl_add_u64 v[2:3], v[156:157], 0, v[2:3]
	v_lshl_add_u64 v[4:5], v[158:159], 0, v[4:5]
	v_lshl_add_u64 v[2:3], v[2:3], 0, s[70:71]
	v_cndmask_b32_e64 v3, v3, v5, s[2:3]
	v_cndmask_b32_e64 v2, v2, v4, s[2:3]
	global_load_dwordx4 v[128:131], v[2:3], off
	v_lshl_add_u64 v[2:3], s[68:69], 1, v[150:151]
	global_load_dwordx4 v[124:127], v[2:3], off
	v_lshrrev_b64 v[2:3], s25, v[148:149]
	v_and_b32_e32 v2, 1, v2
	v_cmp_eq_u32_e32 vcc, 1, v2
	s_and_saveexec_b64 s[12:13], vcc
	s_cbranch_execz .LBB0_761
	v_lshl_add_u32 v177, s14, 1, v172
	v_lshl_add_u32 v6, v169, 1, v177
	ds_read_b128 v[2:5], v6
	s_lshl_b32 s14, s25, 6
	s_or_b32 s15, s14, 63
	s_cmp_le_i32 s15, s24
	s_waitcnt lgkmcnt(0)
	v_mfma_f32_32x32x16_bf16 v[80:95], v[2:5], v[96:99], v[48:63]
	ds_read_b128 v[2:5], v6 offset:6656
	s_waitcnt lgkmcnt(0)
	v_mfma_f32_32x32x16_bf16 v[64:79], v[2:5], v[96:99], v[48:63]
	ds_read_b128 v[2:5], v6 offset:32
	s_waitcnt lgkmcnt(0)
	v_mfma_f32_32x32x16_bf16 v[80:95], v[2:5], v[100:103], v[80:95]
	ds_read_b128 v[2:5], v6 offset:6688
	s_waitcnt lgkmcnt(0)
	v_mfma_f32_32x32x16_bf16 v[64:79], v[2:5], v[100:103], v[64:79]
	ds_read_b128 v[2:5], v6 offset:64
	s_waitcnt lgkmcnt(0)
	v_mfma_f32_32x32x16_bf16 v[80:95], v[2:5], v[104:107], v[80:95]
	ds_read_b128 v[2:5], v6 offset:6720
	s_waitcnt lgkmcnt(0)
	v_mfma_f32_32x32x16_bf16 v[64:79], v[2:5], v[104:107], v[64:79]
	ds_read_b128 v[2:5], v6 offset:96
	s_waitcnt lgkmcnt(0)
	v_mfma_f32_32x32x16_bf16 v[80:95], v[2:5], v[108:111], v[80:95]
	ds_read_b128 v[2:5], v6 offset:6752
	s_waitcnt lgkmcnt(0)
	v_mfma_f32_32x32x16_bf16 v[64:79], v[2:5], v[108:111], v[64:79]
	ds_read_b128 v[2:5], v6 offset:128
	s_waitcnt lgkmcnt(0)
	v_mfma_f32_32x32x16_bf16 v[80:95], v[2:5], v[112:115], v[80:95]
	ds_read_b128 v[2:5], v6 offset:6784
	s_waitcnt lgkmcnt(0)
	v_mfma_f32_32x32x16_bf16 v[64:79], v[2:5], v[112:115], v[64:79]
	ds_read_b128 v[2:5], v6 offset:160
	s_waitcnt lgkmcnt(0)
	v_mfma_f32_32x32x16_bf16 v[80:95], v[2:5], v[116:119], v[80:95]
	ds_read_b128 v[2:5], v6 offset:6816
	s_waitcnt lgkmcnt(0)
	v_mfma_f32_32x32x16_bf16 v[64:79], v[2:5], v[116:119], v[64:79]
	s_cbranch_scc1 .LBB0_757
	v_or_b32_e32 v2, s14, v170
	v_or_b32_e32 v3, 32, v2
	v_cmp_le_i32_e32 vcc, v2, v146
	v_or_b32_e32 v4, 34, v2
	s_nop 3
	v_cndmask_b32_e32 v80, v175, v80, vcc
	v_cmp_le_i32_e32 vcc, v3, v146
	v_or_b32_e32 v3, 33, v2
	s_nop 0
	v_cndmask_b32_e32 v64, v175, v64, vcc
	v_cmp_lt_i32_e32 vcc, v2, v146
	s_nop 1
	v_cndmask_b32_e32 v81, v175, v81, vcc
	v_cmp_le_i32_e32 vcc, v3, v146
	v_or_b32_e32 v3, 2, v2
	s_nop 0
	v_cndmask_b32_e32 v65, v175, v65, vcc
	v_cmp_le_i32_e32 vcc, v3, v146
	v_or_b32_e32 v3, 3, v2
	s_nop 0
	v_cndmask_b32_e32 v82, v175, v82, vcc
	v_cmp_le_i32_e32 vcc, v4, v146
	v_or_b32_e32 v4, 35, v2
	s_nop 0
	v_cndmask_b32_e32 v66, v175, v66, vcc
	v_cmp_le_i32_e32 vcc, v3, v146
	v_or_b32_e32 v3, 8, v2
	s_nop 0
	v_cndmask_b32_e32 v83, v175, v83, vcc
	v_cmp_le_i32_e32 vcc, v4, v146
	v_or_b32_e32 v4, 40, v2
	s_nop 0
	v_cndmask_b32_e32 v67, v175, v67, vcc
	v_cmp_le_i32_e32 vcc, v3, v146
	v_or_b32_e32 v3, 9, v2
	s_nop 0
	v_cndmask_b32_e32 v84, v175, v84, vcc
	v_cmp_le_i32_e32 vcc, v4, v146
	v_or_b32_e32 v4, 41, v2
	s_nop 0
	v_cndmask_b32_e32 v68, v175, v68, vcc
	v_cmp_le_i32_e32 vcc, v3, v146
	v_or_b32_e32 v3, 10, v2
	s_nop 0
	v_cndmask_b32_e32 v85, v175, v85, vcc
	v_cmp_le_i32_e32 vcc, v4, v146
	v_or_b32_e32 v4, 42, v2
	s_nop 0
	v_cndmask_b32_e32 v69, v175, v69, vcc
	v_cmp_le_i32_e32 vcc, v3, v146
	v_or_b32_e32 v3, 11, v2
	s_nop 0
	v_cndmask_b32_e32 v86, v175, v86, vcc
	v_cmp_le_i32_e32 vcc, v4, v146
	v_or_b32_e32 v4, 43, v2
	s_nop 0
	v_cndmask_b32_e32 v70, v175, v70, vcc
	v_cmp_le_i32_e32 vcc, v3, v146
	v_or_b32_e32 v3, 16, v2
	s_nop 0
	v_cndmask_b32_e32 v87, v175, v87, vcc
	v_cmp_le_i32_e32 vcc, v4, v146
	v_or_b32_e32 v4, 48, v2
	s_nop 0
	v_cndmask_b32_e32 v71, v175, v71, vcc
	v_cmp_le_i32_e32 vcc, v3, v146
	v_or_b32_e32 v3, 17, v2
	s_nop 0
	v_cndmask_b32_e32 v88, v175, v88, vcc
	v_cmp_le_i32_e32 vcc, v4, v146
	v_or_b32_e32 v4, 49, v2
	s_nop 0
	v_cndmask_b32_e32 v72, v175, v72, vcc
	v_cmp_le_i32_e32 vcc, v3, v146
	v_or_b32_e32 v3, 18, v2
	s_nop 0
	v_cndmask_b32_e32 v89, v175, v89, vcc
	v_cmp_le_i32_e32 vcc, v4, v146
	v_or_b32_e32 v4, 50, v2
	s_nop 0
	v_cndmask_b32_e32 v73, v175, v73, vcc
	v_cmp_le_i32_e32 vcc, v3, v146
	v_or_b32_e32 v3, 19, v2
	s_nop 0
	v_cndmask_b32_e32 v90, v175, v90, vcc
	v_cmp_le_i32_e32 vcc, v4, v146
	v_or_b32_e32 v4, 51, v2
	s_nop 0
	v_cndmask_b32_e32 v74, v175, v74, vcc
	v_cmp_le_i32_e32 vcc, v3, v146
	v_or_b32_e32 v3, 24, v2
	s_nop 0
	v_cndmask_b32_e32 v91, v175, v91, vcc
	v_cmp_le_i32_e32 vcc, v4, v146
	v_or_b32_e32 v4, 56, v2
	s_nop 0
	v_cndmask_b32_e32 v75, v175, v75, vcc
	v_cmp_le_i32_e32 vcc, v3, v146
	v_or_b32_e32 v3, 25, v2
	s_nop 0
	v_cndmask_b32_e32 v92, v175, v92, vcc
	v_cmp_le_i32_e32 vcc, v4, v146
	v_or_b32_e32 v4, 57, v2
	s_nop 0
	v_cndmask_b32_e32 v76, v175, v76, vcc
	v_cmp_le_i32_e32 vcc, v3, v146
	v_or_b32_e32 v3, 26, v2
	s_nop 0
	v_cndmask_b32_e32 v93, v175, v93, vcc
	v_cmp_le_i32_e32 vcc, v4, v146
	v_or_b32_e32 v4, 58, v2
	s_nop 0
	v_cndmask_b32_e32 v77, v175, v77, vcc
	v_cmp_le_i32_e32 vcc, v3, v146
	v_or_b32_e32 v3, 27, v2
	v_or_b32_e32 v2, 59, v2
	v_cndmask_b32_e32 v94, v175, v94, vcc
	v_cmp_le_i32_e32 vcc, v4, v146
	s_nop 1
	v_cndmask_b32_e32 v78, v175, v78, vcc
	v_cmp_le_i32_e32 vcc, v3, v146
	s_nop 1
	v_cndmask_b32_e32 v95, v175, v95, vcc
	v_cmp_le_i32_e32 vcc, v2, v146
	s_nop 1
	v_cndmask_b32_e32 v79, v175, v79, vcc
; DI float ex2(float x) { return __builtin_amdgcn_exp2f(x); }
; template <int MODE>
; DI void flash_pass(AState& st, const bf16x8* qf, u64 tmask, u64 wmask,
;                    const bf16_t* kbase, size_t kld, const bf16_t* kpe, const bf16_t* vtbase, const float* fbias,
;                    int tq, u64 mysel, bf16_t* smem) {
;     ...
;       int im = (int)0x80000000;
; #pragma unroll
;       for (int r = 0; r < 16; ++r) im = max(im, max(__float_as_int(s0[r]), __float_as_int(s1[r])));
;       im = max(im, __shfl_xor(im, 32));
;       constexpr int TBITS = 0x41800000;
;       f32x16 e0, e1;
; #pragma unroll
;       for (int r = 0; r < 16; ++r) { e0[r] = ex2(s0[r]); e1[r] = ex2(s1[r]); }
;       if (__any(im > TBITS)) {
;         const float d = im > TBITS ? __int_as_float(im) : 0.f;
;         const float a = ex2(-d);
; #pragma unroll
;         for (int r = 0; r < 16; ++r) { e0[r] = ex2(s0[r] - d); e1[r] = ex2(s1[r] - d); st.o[0][r] *= a; st.o[1][r] *= a; }
;         st.l *= a; st.m += d;
; #pragma unroll
;         for (int r = 0; r < 16; ++r) st.mr[r] = -st.m;
;       }
.LBB0_757:
	s_nop 10
	v_max_i32_e32 v2, v81, v65
	v_max3_i32 v2, v80, v64, v2
	v_max_i32_e32 v3, v82, v66
	v_max_i32_e32 v4, v83, v67
	v_max3_i32 v2, v2, v3, v4
	v_max_i32_e32 v3, v84, v68
	v_max_i32_e32 v4, v85, v69
	v_max3_i32 v2, v2, v3, v4
	v_max_i32_e32 v3, v86, v70
	v_max_i32_e32 v4, v87, v71
	v_max3_i32 v2, v2, v3, v4
	v_max_i32_e32 v3, v88, v72
	v_max_i32_e32 v4, v89, v73
	v_max3_i32 v2, v2, v3, v4
	v_max_i32_e32 v3, v90, v74
	v_max_i32_e32 v4, v91, v75
	v_max3_i32 v2, v2, v3, v4
	v_max_i32_e32 v3, v92, v76
	v_max_i32_e32 v4, v93, v77
	v_max3_i32 v2, v2, v3, v4
	v_max_i32_e32 v3, v94, v78
	v_max_i32_e32 v4, v95, v79
	v_max3_i32 v2, v2, v3, v4
	v_mov_b32_e32 v3, v2
	s_nop 1
	v_permlane32_swap_b32_e32 v3, v2
	v_max_i32_e32 v2, v2, v3
	v_cmp_lt_i32_e32 vcc, s88, v2
	s_cbranch_vccz .LBB0_759
	s_nop 0
	v_cndmask_b32_e32 v49, 0, v2, vcc
	v_sub_f32_e32 v2, v80, v49
	v_exp_f32_e32 v183, v2
	v_sub_f32_e32 v2, v64, v49
	v_exp_f32_e32 v178, v2
	v_sub_f32_e32 v2, v81, v49
	v_exp_f32_e32 v181, v2
	v_sub_f32_e32 v2, v65, v49
	v_exp_f32_e32 v179, v2
	v_sub_f32_e32 v2, v82, v49
	v_exp_f32_e32 v180, v2
	v_sub_f32_e32 v2, v66, v49
	v_sub_f32_e32 v50, v92, v49
	v_exp_f32_e32 v82, v2
	v_sub_f32_e32 v2, v83, v49
	v_exp_f32_e32 v64, v50
	v_sub_f32_e32 v50, v76, v49
	v_exp_f32_e32 v182, v2
	v_sub_f32_e32 v2, v67, v49
	v_exp_f32_e32 v66, v50
	v_sub_f32_e32 v50, v93, v49
	v_exp_f32_e32 v83, v2
	v_sub_f32_e32 v2, v84, v49
	v_exp_f32_e32 v65, v50
	v_sub_f32_e32 v50, v77, v49
	v_exp_f32_e32 v80, v2
	v_sub_f32_e32 v2, v68, v49
	v_exp_f32_e32 v67, v50
	v_sub_f32_e32 v50, v94, v49
	v_exp_f32_e32 v8, v2
	v_sub_f32_e32 v2, v85, v49
	v_sub_f32_e32 v4, v71, v49
	v_exp_f32_e32 v68, v50
	v_sub_f32_e32 v50, v78, v49
	v_exp_f32_e64 v48, -v49
	v_exp_f32_e32 v81, v2
	v_sub_f32_e32 v2, v69, v49
	v_sub_f32_e32 v3, v70, v49
	v_exp_f32_e32 v7, v4
	v_sub_f32_e32 v4, v88, v49
	v_sub_f32_e32 v5, v89, v49
	v_sub_f32_e32 v12, v90, v49
	v_sub_f32_e32 v13, v91, v49
	v_exp_f32_e32 v70, v50
	v_sub_f32_e32 v50, v95, v49
	v_exp_f32_e32 v9, v2
	v_sub_f32_e32 v2, v86, v49
	v_exp_f32_e32 v6, v3
	v_sub_f32_e32 v3, v87, v49
	v_exp_f32_e32 v10, v4
	v_sub_f32_e32 v4, v72, v49
	v_exp_f32_e32 v11, v5
	v_sub_f32_e32 v5, v73, v49
	v_exp_f32_e32 v14, v12
	v_sub_f32_e32 v12, v74, v49
	v_exp_f32_e32 v15, v13
	v_sub_f32_e32 v13, v75, v49
	v_exp_f32_e32 v69, v50
	v_sub_f32_e32 v50, v79, v49
	v_exp_f32_e32 v2, v2
	v_exp_f32_e32 v3, v3
	v_exp_f32_e32 v4, v4
	v_exp_f32_e32 v5, v5
	v_exp_f32_e32 v12, v12
	v_exp_f32_e32 v13, v13
	v_exp_f32_e32 v71, v50
	v_add_f32_e32 v0, v0, v49
	v_pk_mul_f32 v[46:47], v[46:47], v[48:49] op_sel_hi:[1,0]
	v_pk_mul_f32 v[44:45], v[44:45], v[48:49] op_sel_hi:[1,0]
	v_pk_mul_f32 v[42:43], v[42:43], v[48:49] op_sel_hi:[1,0]
	v_pk_mul_f32 v[40:41], v[40:41], v[48:49] op_sel_hi:[1,0]
	v_pk_mul_f32 v[38:39], v[38:39], v[48:49] op_sel_hi:[1,0]
	v_pk_mul_f32 v[36:37], v[36:37], v[48:49] op_sel_hi:[1,0]
	v_pk_mul_f32 v[34:35], v[34:35], v[48:49] op_sel_hi:[1,0]
	v_pk_mul_f32 v[32:33], v[32:33], v[48:49] op_sel_hi:[1,0]
	v_pk_mul_f32 v[30:31], v[30:31], v[48:49] op_sel_hi:[1,0]
	v_pk_mul_f32 v[28:29], v[28:29], v[48:49] op_sel_hi:[1,0]
	v_pk_mul_f32 v[26:27], v[26:27], v[48:49] op_sel_hi:[1,0]
	v_pk_mul_f32 v[24:25], v[24:25], v[48:49] op_sel_hi:[1,0]
	v_pk_mul_f32 v[22:23], v[22:23], v[48:49] op_sel_hi:[1,0]
	v_pk_mul_f32 v[20:21], v[20:21], v[48:49] op_sel_hi:[1,0]
	v_pk_mul_f32 v[18:19], v[18:19], v[48:49] op_sel_hi:[1,0]
	v_pk_mul_f32 v[16:17], v[16:17], v[48:49] op_sel_hi:[1,0]
	v_mul_f32_e32 v171, v171, v48
	v_xor_b32_e32 v48, 0x80000000, v0
	v_mov_b32_e32 v49, v48
	v_mov_b32_e32 v50, v48
	v_mov_b32_e32 v51, v48
	v_mov_b32_e32 v52, v48
	v_mov_b32_e32 v53, v48
	v_mov_b32_e32 v54, v48
	v_mov_b32_e32 v55, v48
	v_mov_b32_e32 v56, v48
	v_mov_b32_e32 v57, v48
	v_mov_b32_e32 v58, v48
	v_mov_b32_e32 v59, v48
	v_mov_b32_e32 v60, v48
	v_mov_b32_e32 v61, v48
	v_mov_b32_e32 v62, v48
	v_mov_b32_e32 v63, v48
	s_branch .LBB0_760

; DI float ex2(float x) { return __builtin_amdgcn_exp2f(x); }
; template <int MODE>
; DI void flash_pass(AState& st, const bf16x8* qf, u64 tmask, u64 wmask,
;                    const bf16_t* kbase, size_t kld, const bf16_t* kpe, const bf16_t* vtbase, const float* fbias,
;                    int tq, u64 mysel, bf16_t* smem) {
;     ...
;       int im = (int)0x80000000;
; #pragma unroll
;       for (int r = 0; r < 16; ++r) im = max(im, max(__float_as_int(s0[r]), __float_as_int(s1[r])));
;       im = max(im, __shfl_xor(im, 32));
;       constexpr int TBITS = 0x41800000;
;       f32x16 e0, e1;
; #pragma unroll
;       for (int r = 0; r < 16; ++r) { e0[r] = ex2(s0[r]); e1[r] = ex2(s1[r]); }
;       if (__any(im > TBITS)) {
;         const float d = im > TBITS ? __int_as_float(im) : 0.f;
;         const float a = ex2(-d);
; #pragma unroll
;         for (int r = 0; r < 16; ++r) { e0[r] = ex2(s0[r] - d); e1[r] = ex2(s1[r] - d); st.o[0][r] *= a; st.o[1][r] *= a; }
;         st.l *= a; st.m += d;
; #pragma unroll
;         for (int r = 0; r < 16; ++r) st.mr[r] = -st.m;
;       }
.LBB0_769:
	s_nop 10
	v_max_i32_e32 v2, v81, v65
	v_max3_i32 v2, v80, v64, v2
	v_max_i32_e32 v3, v82, v66
	v_max_i32_e32 v4, v83, v67
	v_max3_i32 v2, v2, v3, v4
	v_max_i32_e32 v3, v84, v68
	v_max_i32_e32 v4, v85, v69
	v_max3_i32 v2, v2, v3, v4
	v_max_i32_e32 v3, v86, v70
	v_max_i32_e32 v4, v87, v71
	v_max3_i32 v2, v2, v3, v4
	v_max_i32_e32 v3, v88, v72
	v_max_i32_e32 v4, v89, v73
	v_max3_i32 v2, v2, v3, v4
	v_max_i32_e32 v3, v90, v74
	v_max_i32_e32 v4, v91, v75
	v_max3_i32 v2, v2, v3, v4
	v_max_i32_e32 v3, v92, v76
	v_max_i32_e32 v4, v93, v77
	v_max3_i32 v2, v2, v3, v4
	v_max_i32_e32 v3, v94, v78
	v_max_i32_e32 v4, v95, v79
	v_max3_i32 v2, v2, v3, v4
	v_mov_b32_e32 v3, v2
	s_nop 1
	v_permlane32_swap_b32_e32 v3, v2
	v_max_i32_e32 v2, v2, v3
	v_cmp_lt_i32_e32 vcc, s88, v2
	s_cbranch_vccz .LBB0_771
	s_nop 0
	v_cndmask_b32_e32 v49, 0, v2, vcc
	v_sub_f32_e32 v2, v80, v49
	v_exp_f32_e32 v179, v2
	v_sub_f32_e32 v2, v64, v49
	v_exp_f32_e32 v177, v2
	v_sub_f32_e32 v2, v81, v49
	v_exp_f32_e32 v180, v2
	v_sub_f32_e32 v2, v65, v49
	v_exp_f32_e32 v178, v2
	v_sub_f32_e32 v2, v82, v49
	v_exp_f32_e32 v181, v2
	v_sub_f32_e32 v2, v66, v49
	v_exp_f32_e32 v82, v2
	v_sub_f32_e32 v2, v83, v49
	v_exp_f32_e32 v182, v2
	v_sub_f32_e32 v2, v67, v49
	v_exp_f32_e32 v83, v2
	v_sub_f32_e32 v2, v84, v49
	v_exp_f32_e32 v66, v2
	v_sub_f32_e32 v2, v68, v49
	v_exp_f32_e32 v10, v2
	v_sub_f32_e32 v2, v85, v49
	v_exp_f32_e32 v67, v2
	v_sub_f32_e32 v2, v69, v49
	v_exp_f32_e32 v11, v2
	v_sub_f32_e32 v2, v86, v49
	v_exp_f32_e32 v80, v2
	v_sub_f32_e32 v2, v70, v49
	v_exp_f32_e32 v12, v2
	v_sub_f32_e32 v2, v87, v49
	v_exp_f32_e32 v81, v2
	v_sub_f32_e32 v2, v71, v49
	v_exp_f32_e64 v48, -v49
	v_exp_f32_e32 v13, v2
	v_sub_f32_e32 v2, v88, v49
	v_sub_f32_e32 v3, v89, v49
	v_sub_f32_e32 v4, v90, v49
	v_sub_f32_e32 v5, v91, v49
	v_sub_f32_e32 v6, v92, v49
	v_sub_f32_e32 v7, v93, v49
	v_sub_f32_e32 v8, v94, v49
	v_sub_f32_e32 v9, v95, v49
	v_exp_f32_e32 v14, v2
	v_sub_f32_e32 v2, v72, v49
	v_exp_f32_e32 v15, v3
	v_sub_f32_e32 v3, v73, v49
	v_exp_f32_e32 v64, v4
	v_sub_f32_e32 v4, v74, v49
	v_exp_f32_e32 v65, v5
	v_sub_f32_e32 v5, v75, v49
	v_exp_f32_e32 v68, v6
	v_sub_f32_e32 v6, v76, v49
	v_exp_f32_e32 v69, v7
	v_sub_f32_e32 v7, v77, v49
	v_exp_f32_e32 v70, v8
	v_sub_f32_e32 v8, v78, v49
	v_exp_f32_e32 v71, v9
	v_sub_f32_e32 v9, v79, v49
	v_exp_f32_e32 v2, v2
	v_exp_f32_e32 v3, v3
	v_exp_f32_e32 v4, v4
	v_exp_f32_e32 v5, v5
	v_exp_f32_e32 v6, v6
	v_exp_f32_e32 v7, v7
	v_exp_f32_e32 v8, v8
	v_exp_f32_e32 v9, v9
	v_add_f32_e32 v0, v0, v49
	v_pk_mul_f32 v[46:47], v[46:47], v[48:49] op_sel_hi:[1,0]
	v_pk_mul_f32 v[44:45], v[44:45], v[48:49] op_sel_hi:[1,0]
	v_pk_mul_f32 v[42:43], v[42:43], v[48:49] op_sel_hi:[1,0]
	v_pk_mul_f32 v[40:41], v[40:41], v[48:49] op_sel_hi:[1,0]
	v_pk_mul_f32 v[38:39], v[38:39], v[48:49] op_sel_hi:[1,0]
	v_pk_mul_f32 v[36:37], v[36:37], v[48:49] op_sel_hi:[1,0]
	v_pk_mul_f32 v[34:35], v[34:35], v[48:49] op_sel_hi:[1,0]
	v_pk_mul_f32 v[32:33], v[32:33], v[48:49] op_sel_hi:[1,0]
	v_pk_mul_f32 v[30:31], v[30:31], v[48:49] op_sel_hi:[1,0]
	v_pk_mul_f32 v[28:29], v[28:29], v[48:49] op_sel_hi:[1,0]
	v_pk_mul_f32 v[26:27], v[26:27], v[48:49] op_sel_hi:[1,0]
	v_pk_mul_f32 v[24:25], v[24:25], v[48:49] op_sel_hi:[1,0]
	v_pk_mul_f32 v[22:23], v[22:23], v[48:49] op_sel_hi:[1,0]
	v_pk_mul_f32 v[20:21], v[20:21], v[48:49] op_sel_hi:[1,0]
	v_pk_mul_f32 v[18:19], v[18:19], v[48:49] op_sel_hi:[1,0]
	v_pk_mul_f32 v[16:17], v[16:17], v[48:49] op_sel_hi:[1,0]
	v_mul_f32_e32 v171, v171, v48
	v_xor_b32_e32 v48, 0x80000000, v0
	v_mov_b32_e32 v49, v48
	v_mov_b32_e32 v50, v48
	v_mov_b32_e32 v51, v48
	v_mov_b32_e32 v52, v48
	v_mov_b32_e32 v53, v48
	v_mov_b32_e32 v54, v48
	v_mov_b32_e32 v55, v48
	v_mov_b32_e32 v56, v48
	v_mov_b32_e32 v57, v48
	v_mov_b32_e32 v58, v48
	v_mov_b32_e32 v59, v48
	v_mov_b32_e32 v60, v48
	v_mov_b32_e32 v61, v48
	v_mov_b32_e32 v62, v48
	v_mov_b32_e32 v63, v48
	s_branch .LBB0_772

; DI f32x4 mfma16(bf16x8 a, bf16x8 b, f32x4 c) { return __builtin_amdgcn_mfma_f32_16x16x32_bf16(a, b, c, 0, 0, 0); }
; template <int MI, int NJ, bool SWAP, class AP, class BP>
; DI void gemm_main(f32x4 (&acc)[MI][NJ], const AP& ap, int a_kstep, const BP& bp, int b_kstep, int nk, bf16_t* smem) {
;     ...
;   auto gload = [&](int kt) {
;     const bf16_t* ab = ap.base + (size_t)kt * a_kstep; const bf16_t* bb = bp.base + (size_t)kt * b_kstep;
; #pragma unroll
;     for (int i = 0; i < CA; ++i) ra[i] = *(const u32x4*)(ab + pa[i]);
; #pragma unroll
;     for (int i = 0; i < CB; ++i) rb[i] = *(const u32x4*)(bb + pb[i]);
;   };
;   auto sstore = [&](int buf) {
;     bf16_t* As = smem + buf * L::STAGE; bf16_t* Bs = As + L::A_ELEMS;
; #pragma unroll
;     for (int i = 0; i < CA; ++i) { const int c = tid + NTHR * i; *(u32x4*)(As + (c >> 3) * LDT + (c & 7) * 8) = oka[i] ? ra[i] : (u32x4){0u, 0u, 0u, 0u}; }
; #pragma unroll
;     for (int i = 0; i < CB; ++i) { const int c = tid + NTHR * i; *(u32x4*)(Bs + (c >> 3) * LDT + (c & 7) * 8) = rb[i]; }
;   };
;   gload(0); sstore(0); gload(nk > 1 ? 1 : 0); __syncthreads();
; #pragma unroll 1
;   for (int kt = 0; kt < nk; ++kt) {
;     const int buf = kt & 1;
;     sstore(buf ^ 1);
;     gload(kt + 2 < nk ? kt + 2 : nk - 1);
;     __builtin_amdgcn_sched_barrier(0);
;     const bf16_t* As = smem + buf * L::STAGE + (wm * 16 * MI + l15) * LDT + quad * 8;
;     const bf16_t* Bs = smem + buf * L::STAGE + L::A_ELEMS + (wn * 16 * NJ + l15) * LDT + quad * 8;
; #pragma unroll
;     for (int ks = 0; ks < 2; ++ks) {
;       if (MI * NJ >= 32 && ks == 1) asm volatile("" ::: "memory");
;       bf16x8 b[NJ];
; #pragma unroll
;       for (int j = 0; j < NJ; ++j) b[j] = *(const bf16x8*)(Bs + j * 16 * LDT + ks * 32);
; #pragma unroll
;       for (int i = 0; i < MI; ++i) {
;         const bf16x8 a = *(const bf16x8*)(As + i * 16 * LDT + ks * 32);
; #pragma unroll
;         for (int j = 0; j < NJ; ++j) acc[i][j] = SWAP ? mfma16(b[j], a, acc[i][j]) : mfma16(a, b[j], acc[i][j]);
;       }
;     }
;     __syncthreads();
;   }
.Lgm5_main:
	ds_read_b128 v[242:245], v177 offset:4608
	s_waitcnt lgkmcnt(4)
	v_mfma_f32_16x16x32_bf16 v[156:159], v[178:181], v[194:197], v[156:159]
	s_waitcnt lgkmcnt(3)
	v_mfma_f32_16x16x32_bf16 v[152:155], v[182:185], v[194:197], v[152:155]
	s_waitcnt lgkmcnt(2)
	v_mfma_f32_16x16x32_bf16 v[148:151], v[186:189], v[194:197], v[148:151]
	s_and_b32 s15, s1, 1
	s_min_u32 s16, s1, 13
	s_xor_b32 s17, s15, 1
	s_mul_i32 s17, s17, 0x12000
	v_add3_u32 v250, s17, v172, v170
	s_waitcnt vmcnt(7)
	ds_write_b128 v250, v[112:115]
	s_waitcnt lgkmcnt(2)
	v_mfma_f32_16x16x32_bf16 v[128:131], v[190:193], v[194:197], v[128:131]
	ds_read_b128 v[246:249], v177 offset:6912
	v_mfma_f32_16x16x32_bf16 v[108:111], v[178:181], v[198:201], v[108:111]
	s_lshl_b32 s26, s16, 7
	s_add_u32 s16, s2, s26
	v_add3_u32 v251, s17, v174, v170
	v_add3_u32 v252, s17, v175, v170
	v_add3_u32 v253, s17, v176, v170
	s_addc_u32 s17, s3, 0
	v_lshl_add_u64 v[112:113], s[16:17], 0, v[162:163]
	s_nop 0
	global_load_dwordx4 v[112:115], v[112:113], off offset:256
	v_mfma_f32_16x16x32_bf16 v[104:107], v[182:185], v[198:201], v[104:107]
	v_mfma_f32_16x16x32_bf16 v[100:103], v[186:189], v[198:201], v[100:103]
	v_mfma_f32_16x16x32_bf16 v[96:99], v[190:193], v[198:201], v[96:99]
	ds_read_b128 v[194:197], v177 offset:9216
	s_waitcnt lgkmcnt(3)
	v_mfma_f32_16x16x32_bf16 v[92:95], v[178:181], v[242:245], v[92:95]
	s_waitcnt vmcnt(7)
	ds_write_b128 v251, v[116:119]
	v_mfma_f32_16x16x32_bf16 v[88:91], v[182:185], v[242:245], v[88:91]
	v_mfma_f32_16x16x32_bf16 v[84:87], v[186:189], v[242:245], v[84:87]
	v_lshl_add_u64 v[116:117], s[16:17], 0, v[164:165]
	s_nop 0
	global_load_dwordx4 v[116:119], v[116:117], off offset:256
	v_mfma_f32_16x16x32_bf16 v[80:83], v[190:193], v[242:245], v[80:83]
	ds_read_b128 v[198:201], v177 offset:11520
	s_waitcnt lgkmcnt(3)
	v_mfma_f32_16x16x32_bf16 v[76:79], v[178:181], v[246:249], v[76:79]
	v_mfma_f32_16x16x32_bf16 v[72:75], v[182:185], v[246:249], v[72:75]
	v_mfma_f32_16x16x32_bf16 v[68:71], v[186:189], v[246:249], v[68:71]
	s_waitcnt vmcnt(7)
	ds_write_b128 v252, v[120:123]
	v_mfma_f32_16x16x32_bf16 v[64:67], v[190:193], v[246:249], v[64:67]
	ds_read_b128 v[242:245], v177 offset:13824
	s_waitcnt lgkmcnt(4)
	v_mfma_f32_16x16x32_bf16 v[60:63], v[178:181], v[194:197], v[60:63]
	v_lshl_add_u64 v[120:121], s[16:17], 0, v[166:167]
	s_nop 0
	global_load_dwordx4 v[120:123], v[120:121], off offset:256
	v_mfma_f32_16x16x32_bf16 v[56:59], v[182:185], v[194:197], v[56:59]
	v_mfma_f32_16x16x32_bf16 v[52:55], v[186:189], v[194:197], v[52:55]
	v_mfma_f32_16x16x32_bf16 v[48:51], v[190:193], v[194:197], v[48:51]
	ds_read_b128 v[246:249], v177 offset:16128
	s_waitcnt lgkmcnt(3)
	v_mfma_f32_16x16x32_bf16 v[44:47], v[178:181], v[198:201], v[44:47]
	s_waitcnt vmcnt(7)
	ds_write_b128 v253, v[124:127]
	v_mfma_f32_16x16x32_bf16 v[40:43], v[182:185], v[198:201], v[40:43]
	v_mfma_f32_16x16x32_bf16 v[36:39], v[186:189], v[198:201], v[36:39]
	v_lshl_add_u64 v[124:125], s[16:17], 0, v[168:169]
	s_nop 0
	global_load_dwordx4 v[124:127], v[124:125], off offset:256
	v_mfma_f32_16x16x32_bf16 v[32:35], v[190:193], v[198:201], v[32:35]
	ds_read_b128 v[194:197], v177 offset:64
	s_waitcnt lgkmcnt(3)
	v_mfma_f32_16x16x32_bf16 v[28:31], v[178:181], v[242:245], v[28:31]
	v_mfma_f32_16x16x32_bf16 v[24:27], v[182:185], v[242:245], v[24:27]
	v_mfma_f32_16x16x32_bf16 v[20:23], v[186:189], v[242:245], v[20:23]
	s_waitcnt vmcnt(7)
	ds_write_b128 v250, v[132:135] offset:36864
	v_mfma_f32_16x16x32_bf16 v[16:19], v[190:193], v[242:245], v[16:19]
	ds_read_b128 v[198:201], v177 offset:2368
	s_waitcnt lgkmcnt(4)
	v_mfma_f32_16x16x32_bf16 v[8:11], v[178:181], v[246:249], v[8:11]
	ds_read_b128 v[178:181], v202 offset:36928
	s_add_u32 s16, s12, s26
	s_addc_u32 s17, s13, 0
	v_lshl_add_u64 v[132:133], s[16:17], 0, v[162:163]
	s_nop 0
	global_load_dwordx4 v[132:135], v[132:133], off offset:256
	v_mfma_f32_16x16x32_bf16 v[4:7], v[182:185], v[246:249], v[4:7]
	ds_read_b128 v[182:185], v202 offset:39232
	v_mfma_f32_16x16x32_bf16 v[0:3], v[186:189], v[246:249], v[0:3]
	ds_read_b128 v[186:189], v202 offset:41536
	v_mfma_f32_16x16x32_bf16 v[12:15], v[190:193], v[246:249], v[12:15]
	ds_read_b128 v[190:193], v202 offset:43840
	ds_read_b128 v[242:245], v177 offset:4672
	s_waitcnt lgkmcnt(4)
	v_mfma_f32_16x16x32_bf16 v[156:159], v[178:181], v[194:197], v[156:159]
	s_waitcnt vmcnt(7)
	ds_write_b128 v251, v[136:139] offset:36864
	s_waitcnt lgkmcnt(4)
	v_mfma_f32_16x16x32_bf16 v[152:155], v[182:185], v[194:197], v[152:155]
	s_waitcnt lgkmcnt(3)
	v_mfma_f32_16x16x32_bf16 v[148:151], v[186:189], v[194:197], v[148:151]
	v_lshl_add_u64 v[136:137], s[16:17], 0, v[164:165]
	s_nop 0
	global_load_dwordx4 v[136:139], v[136:137], off offset:256
	s_waitcnt lgkmcnt(2)
	v_mfma_f32_16x16x32_bf16 v[128:131], v[190:193], v[194:197], v[128:131]
	ds_read_b128 v[246:249], v177 offset:6976
	v_mfma_f32_16x16x32_bf16 v[108:111], v[178:181], v[198:201], v[108:111]
	v_mfma_f32_16x16x32_bf16 v[104:107], v[182:185], v[198:201], v[104:107]
	v_mfma_f32_16x16x32_bf16 v[100:103], v[186:189], v[198:201], v[100:103]
	s_waitcnt vmcnt(7)
	ds_write_b128 v252, v[140:143] offset:36864
	v_mfma_f32_16x16x32_bf16 v[96:99], v[190:193], v[198:201], v[96:99]
	ds_read_b128 v[194:197], v177 offset:9280
	s_waitcnt lgkmcnt(4)
	v_mfma_f32_16x16x32_bf16 v[92:95], v[178:181], v[242:245], v[92:95]
	v_lshl_add_u64 v[140:141], s[16:17], 0, v[166:167]
	s_nop 0
	global_load_dwordx4 v[140:143], v[140:141], off offset:256
	v_mfma_f32_16x16x32_bf16 v[88:91], v[182:185], v[242:245], v[88:91]
	v_mfma_f32_16x16x32_bf16 v[84:87], v[186:189], v[242:245], v[84:87]
	v_mfma_f32_16x16x32_bf16 v[80:83], v[190:193], v[242:245], v[80:83]
	ds_read_b128 v[198:201], v177 offset:11584
	s_waitcnt lgkmcnt(3)
	v_mfma_f32_16x16x32_bf16 v[76:79], v[178:181], v[246:249], v[76:79]
	s_waitcnt vmcnt(7)
	ds_write_b128 v253, v[144:147] offset:36864
	v_mfma_f32_16x16x32_bf16 v[72:75], v[182:185], v[246:249], v[72:75]
	v_mfma_f32_16x16x32_bf16 v[68:71], v[186:189], v[246:249], v[68:71]
	v_lshl_add_u64 v[144:145], s[16:17], 0, v[168:169]
	s_nop 0
	global_load_dwordx4 v[144:147], v[144:145], off offset:256
	v_mfma_f32_16x16x32_bf16 v[64:67], v[190:193], v[246:249], v[64:67]
	ds_read_b128 v[242:245], v177 offset:13888
	s_waitcnt lgkmcnt(3)
	v_mfma_f32_16x16x32_bf16 v[60:63], v[178:181], v[194:197], v[60:63]
	v_mfma_f32_16x16x32_bf16 v[56:59], v[182:185], v[194:197], v[56:59]
	v_mfma_f32_16x16x32_bf16 v[52:55], v[186:189], v[194:197], v[52:55]
	v_mfma_f32_16x16x32_bf16 v[48:51], v[190:193], v[194:197], v[48:51]
	ds_read_b128 v[246:249], v177 offset:16192
	s_waitcnt lgkmcnt(3)
	v_mfma_f32_16x16x32_bf16 v[44:47], v[178:181], v[198:201], v[44:47]
	v_mfma_f32_16x16x32_bf16 v[40:43], v[182:185], v[198:201], v[40:43]
	v_mfma_f32_16x16x32_bf16 v[36:39], v[186:189], v[198:201], v[36:39]
	v_mfma_f32_16x16x32_bf16 v[32:35], v[190:193], v[198:201], v[32:35]
	s_waitcnt lgkmcnt(0)
	s_barrier
; DI f32x4 mfma16(bf16x8 a, bf16x8 b, f32x4 c) { return __builtin_amdgcn_mfma_f32_16x16x32_bf16(a, b, c, 0, 0, 0); }
; template <int MI, int NJ, bool SWAP, class AP, class BP>
; DI void gemm_main(f32x4 (&acc)[MI][NJ], const AP& ap, int a_kstep, const BP& bp, int b_kstep, int nk, bf16_t* smem) {
;     ...
;   for (int kt = 0; kt < nk; ++kt) {
;     const int buf = kt & 1;
;     sstore(buf ^ 1);
;     gload(kt + 2 < nk ? kt + 2 : nk - 1);
;     __builtin_amdgcn_sched_barrier(0);
;     const bf16_t* As = smem + buf * L::STAGE + (wm * 16 * MI + l15) * LDT + quad * 8;
;     const bf16_t* Bs = smem + buf * L::STAGE + L::A_ELEMS + (wn * 16 * NJ + l15) * LDT + quad * 8;
; #pragma unroll
;     for (int ks = 0; ks < 2; ++ks) {
;       if (MI * NJ >= 32 && ks == 1) asm volatile("" ::: "memory");
;       bf16x8 b[NJ];
; #pragma unroll
;       for (int j = 0; j < NJ; ++j) b[j] = *(const bf16x8*)(Bs + j * 16 * LDT + ks * 32);
; #pragma unroll
;       for (int i = 0; i < MI; ++i) {
;         const bf16x8 a = *(const bf16x8*)(As + i * 16 * LDT + ks * 32);
; #pragma unroll
;         for (int j = 0; j < NJ; ++j) acc[i][j] = SWAP ? mfma16(b[j], a, acc[i][j]) : mfma16(a, b[j], acc[i][j]);
;       }
;     }
;     __syncthreads();
;   }
	s_add_i32 s1, s1, 1
	s_cmp_lg_u32 s1, 16
	s_cbranch_scc0 .Lgm5_exit
	s_and_b32 s98, s1, 1
	s_mul_i32 s98, s98, 0x12000
	v_add3_u32 v202, s98, v160, v173
	v_add3_u32 v177, s98, v171, v173
	ds_read_b128 v[194:197], v177
	ds_read_b128 v[198:201], v177 offset:2304
	v_mfma_f32_16x16x32_bf16 v[28:31], v[178:181], v[242:245], v[28:31]
	v_mfma_f32_16x16x32_bf16 v[8:11], v[178:181], v[246:249], v[8:11]
	ds_read_b128 v[178:181], v202 offset:36864
	v_mfma_f32_16x16x32_bf16 v[24:27], v[182:185], v[242:245], v[24:27]
	v_mfma_f32_16x16x32_bf16 v[4:7], v[182:185], v[246:249], v[4:7]
	ds_read_b128 v[182:185], v202 offset:39168
	v_mfma_f32_16x16x32_bf16 v[20:23], v[186:189], v[242:245], v[20:23]
	v_mfma_f32_16x16x32_bf16 v[0:3], v[186:189], v[246:249], v[0:3]
	ds_read_b128 v[186:189], v202 offset:41472
	v_mfma_f32_16x16x32_bf16 v[16:19], v[190:193], v[242:245], v[16:19]
	v_mfma_f32_16x16x32_bf16 v[12:15], v[190:193], v[246:249], v[12:15]
	ds_read_b128 v[190:193], v202 offset:43776
	s_branch .Lgm5_main

; DI f32x4 mfma16(bf16x8 a, bf16x8 b, f32x4 c) { return __builtin_amdgcn_mfma_f32_16x16x32_bf16(a, b, c, 0, 0, 0); }
; template <int MI, int NJ, bool SWAP, class AP, class BP>
; DI void gemm_main(f32x4 (&acc)[MI][NJ], const AP& ap, int a_kstep, const BP& bp, int b_kstep, int nk, bf16_t* smem) {
;     ...
;   auto gload = [&](int kt) {
;     const bf16_t* ab = ap.base + (size_t)kt * a_kstep; const bf16_t* bb = bp.base + (size_t)kt * b_kstep;
; #pragma unroll
;     for (int i = 0; i < CA; ++i) ra[i] = *(const u32x4*)(ab + pa[i]);
; #pragma unroll
;     for (int i = 0; i < CB; ++i) rb[i] = *(const u32x4*)(bb + pb[i]);
;   };
;   auto sstore = [&](int buf) {
;     bf16_t* As = smem + buf * L::STAGE; bf16_t* Bs = As + L::A_ELEMS;
; #pragma unroll
;     for (int i = 0; i < CA; ++i) { const int c = tid + NTHR * i; *(u32x4*)(As + (c >> 3) * LDT + (c & 7) * 8) = oka[i] ? ra[i] : (u32x4){0u, 0u, 0u, 0u}; }
; #pragma unroll
;     for (int i = 0; i < CB; ++i) { const int c = tid + NTHR * i; *(u32x4*)(Bs + (c >> 3) * LDT + (c & 7) * 8) = rb[i]; }
;   };
;   gload(0); sstore(0); gload(nk > 1 ? 1 : 0); __syncthreads();
; #pragma unroll 1
;   for (int kt = 0; kt < nk; ++kt) {
;     const int buf = kt & 1;
;     sstore(buf ^ 1);
;     gload(kt + 2 < nk ? kt + 2 : nk - 1);
;     __builtin_amdgcn_sched_barrier(0);
;     const bf16_t* As = smem + buf * L::STAGE + (wm * 16 * MI + l15) * LDT + quad * 8;
;     const bf16_t* Bs = smem + buf * L::STAGE + L::A_ELEMS + (wn * 16 * NJ + l15) * LDT + quad * 8;
; #pragma unroll
;     for (int ks = 0; ks < 2; ++ks) {
;       if (MI * NJ >= 32 && ks == 1) asm volatile("" ::: "memory");
;       bf16x8 b[NJ];
; #pragma unroll
;       for (int j = 0; j < NJ; ++j) b[j] = *(const bf16x8*)(Bs + j * 16 * LDT + ks * 32);
; #pragma unroll
;       for (int i = 0; i < MI; ++i) {
;         const bf16x8 a = *(const bf16x8*)(As + i * 16 * LDT + ks * 32);
; #pragma unroll
;         for (int j = 0; j < NJ; ++j) acc[i][j] = SWAP ? mfma16(b[j], a, acc[i][j]) : mfma16(a, b[j], acc[i][j]);
;       }
;     }
;     __syncthreads();
;   }
.Lgm7_main:
	ds_read_b128 v[242:245], v177 offset:4608
	s_waitcnt lgkmcnt(4)
	v_mfma_f32_16x16x32_bf16 v[156:159], v[178:181], v[194:197], v[156:159]
	s_waitcnt lgkmcnt(3)
	v_mfma_f32_16x16x32_bf16 v[152:155], v[182:185], v[194:197], v[152:155]
	s_waitcnt lgkmcnt(2)
	v_mfma_f32_16x16x32_bf16 v[148:151], v[186:189], v[194:197], v[148:151]
	s_and_b32 s24, s21, 1
	s_min_u32 s22, s21, 41
	s_xor_b32 s23, s24, 1
	s_mul_i32 s23, s23, 0x12000
	v_add3_u32 v250, s23, v172, v170
	s_waitcnt vmcnt(7)
	ds_write_b128 v250, v[112:115]
	s_waitcnt lgkmcnt(2)
	v_mfma_f32_16x16x32_bf16 v[144:147], v[190:193], v[194:197], v[144:147]
	ds_read_b128 v[246:249], v177 offset:6912
	v_mfma_f32_16x16x32_bf16 v[108:111], v[178:181], v[198:201], v[108:111]
	s_lshl_b32 s25, s22, 7
	s_add_u32 s22, s6, s25
	v_add3_u32 v251, s23, v173, v170
	v_add3_u32 v252, s23, v174, v170
	v_add3_u32 v253, s23, v175, v170
	s_addc_u32 s23, s7, 0
	v_lshl_add_u64 v[112:113], s[22:23], 0, v[162:163]
	s_nop 0
	global_load_dwordx4 v[112:115], v[112:113], off offset:256
	v_mfma_f32_16x16x32_bf16 v[104:107], v[182:185], v[198:201], v[104:107]
	v_mfma_f32_16x16x32_bf16 v[100:103], v[186:189], v[198:201], v[100:103]
	v_mfma_f32_16x16x32_bf16 v[96:99], v[190:193], v[198:201], v[96:99]
	ds_read_b128 v[194:197], v177 offset:9216
	s_waitcnt lgkmcnt(3)
	v_mfma_f32_16x16x32_bf16 v[92:95], v[178:181], v[242:245], v[92:95]
	s_waitcnt vmcnt(7)
	ds_write_b128 v251, v[116:119]
	v_mfma_f32_16x16x32_bf16 v[88:91], v[182:185], v[242:245], v[88:91]
	v_mfma_f32_16x16x32_bf16 v[84:87], v[186:189], v[242:245], v[84:87]
	v_lshl_add_u64 v[116:117], s[22:23], 0, v[164:165]
	s_nop 0
	global_load_dwordx4 v[116:119], v[116:117], off offset:256
	v_mfma_f32_16x16x32_bf16 v[80:83], v[190:193], v[242:245], v[80:83]
	ds_read_b128 v[198:201], v177 offset:11520
	s_waitcnt lgkmcnt(3)
	v_mfma_f32_16x16x32_bf16 v[76:79], v[178:181], v[246:249], v[76:79]
	v_mfma_f32_16x16x32_bf16 v[72:75], v[182:185], v[246:249], v[72:75]
	v_mfma_f32_16x16x32_bf16 v[68:71], v[186:189], v[246:249], v[68:71]
	s_waitcnt vmcnt(7)
	ds_write_b128 v252, v[120:123]
	v_mfma_f32_16x16x32_bf16 v[64:67], v[190:193], v[246:249], v[64:67]
	ds_read_b128 v[242:245], v177 offset:13824
	s_waitcnt lgkmcnt(4)
	v_mfma_f32_16x16x32_bf16 v[60:63], v[178:181], v[194:197], v[60:63]
	v_lshl_add_u64 v[120:121], s[22:23], 0, v[166:167]
	s_nop 0
	global_load_dwordx4 v[120:123], v[120:121], off offset:256
	v_mfma_f32_16x16x32_bf16 v[56:59], v[182:185], v[194:197], v[56:59]
	v_mfma_f32_16x16x32_bf16 v[52:55], v[186:189], v[194:197], v[52:55]
	v_mfma_f32_16x16x32_bf16 v[48:51], v[190:193], v[194:197], v[48:51]
	ds_read_b128 v[246:249], v177 offset:16128
	s_waitcnt lgkmcnt(3)
	v_mfma_f32_16x16x32_bf16 v[44:47], v[178:181], v[198:201], v[44:47]
	s_waitcnt vmcnt(7)
	ds_write_b128 v253, v[124:127]
	v_mfma_f32_16x16x32_bf16 v[40:43], v[182:185], v[198:201], v[40:43]
	v_mfma_f32_16x16x32_bf16 v[36:39], v[186:189], v[198:201], v[36:39]
	v_lshl_add_u64 v[124:125], s[22:23], 0, v[168:169]
	s_nop 0
	global_load_dwordx4 v[124:127], v[124:125], off offset:256
	v_mfma_f32_16x16x32_bf16 v[32:35], v[190:193], v[198:201], v[32:35]
	ds_read_b128 v[194:197], v177 offset:64
	s_waitcnt lgkmcnt(3)
	v_mfma_f32_16x16x32_bf16 v[28:31], v[178:181], v[242:245], v[28:31]
	v_mfma_f32_16x16x32_bf16 v[24:27], v[182:185], v[242:245], v[24:27]
	v_mfma_f32_16x16x32_bf16 v[20:23], v[186:189], v[242:245], v[20:23]
	s_waitcnt vmcnt(7)
	ds_write_b128 v250, v[128:131] offset:36864
	v_mfma_f32_16x16x32_bf16 v[16:19], v[190:193], v[242:245], v[16:19]
	ds_read_b128 v[198:201], v177 offset:2368
	s_waitcnt lgkmcnt(4)
	v_mfma_f32_16x16x32_bf16 v[8:11], v[178:181], v[246:249], v[8:11]
	ds_read_b128 v[178:181], v202 offset:36928
	s_add_u32 s22, s8, s25
	s_addc_u32 s23, s9, 0
	v_lshl_add_u64 v[128:129], s[22:23], 0, v[162:163]
	s_nop 0
	global_load_dwordx4 v[128:131], v[128:129], off offset:256
	v_mfma_f32_16x16x32_bf16 v[4:7], v[182:185], v[246:249], v[4:7]
	ds_read_b128 v[182:185], v202 offset:39232
	v_mfma_f32_16x16x32_bf16 v[0:3], v[186:189], v[246:249], v[0:3]
	ds_read_b128 v[186:189], v202 offset:41536
	v_mfma_f32_16x16x32_bf16 v[12:15], v[190:193], v[246:249], v[12:15]
	ds_read_b128 v[190:193], v202 offset:43840
	ds_read_b128 v[242:245], v177 offset:4672
	s_waitcnt lgkmcnt(4)
	v_mfma_f32_16x16x32_bf16 v[156:159], v[178:181], v[194:197], v[156:159]
	s_waitcnt vmcnt(7)
	ds_write_b128 v251, v[132:135] offset:36864
	s_waitcnt lgkmcnt(4)
	v_mfma_f32_16x16x32_bf16 v[152:155], v[182:185], v[194:197], v[152:155]
	s_waitcnt lgkmcnt(3)
	v_mfma_f32_16x16x32_bf16 v[148:151], v[186:189], v[194:197], v[148:151]
	v_lshl_add_u64 v[132:133], s[22:23], 0, v[164:165]
	s_nop 0
	global_load_dwordx4 v[132:135], v[132:133], off offset:256
	s_waitcnt lgkmcnt(2)
	v_mfma_f32_16x16x32_bf16 v[144:147], v[190:193], v[194:197], v[144:147]
	ds_read_b128 v[246:249], v177 offset:6976
	v_mfma_f32_16x16x32_bf16 v[108:111], v[178:181], v[198:201], v[108:111]
	v_mfma_f32_16x16x32_bf16 v[104:107], v[182:185], v[198:201], v[104:107]
	v_mfma_f32_16x16x32_bf16 v[100:103], v[186:189], v[198:201], v[100:103]
	s_waitcnt vmcnt(7)
	ds_write_b128 v252, v[136:139] offset:36864
	v_mfma_f32_16x16x32_bf16 v[96:99], v[190:193], v[198:201], v[96:99]
	ds_read_b128 v[194:197], v177 offset:9280
	s_waitcnt lgkmcnt(4)
	v_mfma_f32_16x16x32_bf16 v[92:95], v[178:181], v[242:245], v[92:95]
	v_lshl_add_u64 v[136:137], s[22:23], 0, v[166:167]
	s_nop 0
	global_load_dwordx4 v[136:139], v[136:137], off offset:256
	v_mfma_f32_16x16x32_bf16 v[88:91], v[182:185], v[242:245], v[88:91]
	v_mfma_f32_16x16x32_bf16 v[84:87], v[186:189], v[242:245], v[84:87]
	v_mfma_f32_16x16x32_bf16 v[80:83], v[190:193], v[242:245], v[80:83]
	ds_read_b128 v[198:201], v177 offset:11584
	s_waitcnt lgkmcnt(3)
	v_mfma_f32_16x16x32_bf16 v[76:79], v[178:181], v[246:249], v[76:79]
	s_waitcnt vmcnt(7)
	ds_write_b128 v253, v[140:143] offset:36864
	v_mfma_f32_16x16x32_bf16 v[72:75], v[182:185], v[246:249], v[72:75]
	v_mfma_f32_16x16x32_bf16 v[68:71], v[186:189], v[246:249], v[68:71]
	v_lshl_add_u64 v[140:141], s[22:23], 0, v[168:169]
	s_nop 0
	global_load_dwordx4 v[140:143], v[140:141], off offset:256
	v_mfma_f32_16x16x32_bf16 v[64:67], v[190:193], v[246:249], v[64:67]
	ds_read_b128 v[242:245], v177 offset:13888
	s_waitcnt lgkmcnt(3)
	v_mfma_f32_16x16x32_bf16 v[60:63], v[178:181], v[194:197], v[60:63]
	v_mfma_f32_16x16x32_bf16 v[56:59], v[182:185], v[194:197], v[56:59]
	v_mfma_f32_16x16x32_bf16 v[52:55], v[186:189], v[194:197], v[52:55]
	v_mfma_f32_16x16x32_bf16 v[48:51], v[190:193], v[194:197], v[48:51]
	ds_read_b128 v[246:249], v177 offset:16192
	s_waitcnt lgkmcnt(3)
	v_mfma_f32_16x16x32_bf16 v[44:47], v[178:181], v[198:201], v[44:47]
	v_mfma_f32_16x16x32_bf16 v[40:43], v[182:185], v[198:201], v[40:43]
	v_mfma_f32_16x16x32_bf16 v[36:39], v[186:189], v[198:201], v[36:39]
	v_mfma_f32_16x16x32_bf16 v[32:35], v[190:193], v[198:201], v[32:35]
	s_waitcnt lgkmcnt(0)
	s_barrier
; DI f32x4 mfma16(bf16x8 a, bf16x8 b, f32x4 c) { return __builtin_amdgcn_mfma_f32_16x16x32_bf16(a, b, c, 0, 0, 0); }
; template <int MI, int NJ, bool SWAP, class AP, class BP>
; DI void gemm_main(f32x4 (&acc)[MI][NJ], const AP& ap, int a_kstep, const BP& bp, int b_kstep, int nk, bf16_t* smem) {
;     ...
;   for (int kt = 0; kt < nk; ++kt) {
;     const int buf = kt & 1;
;     sstore(buf ^ 1);
;     gload(kt + 2 < nk ? kt + 2 : nk - 1);
;     __builtin_amdgcn_sched_barrier(0);
;     const bf16_t* As = smem + buf * L::STAGE + (wm * 16 * MI + l15) * LDT + quad * 8;
;     const bf16_t* Bs = smem + buf * L::STAGE + L::A_ELEMS + (wn * 16 * NJ + l15) * LDT + quad * 8;
; #pragma unroll
;     for (int ks = 0; ks < 2; ++ks) {
;       if (MI * NJ >= 32 && ks == 1) asm volatile("" ::: "memory");
;       bf16x8 b[NJ];
; #pragma unroll
;       for (int j = 0; j < NJ; ++j) b[j] = *(const bf16x8*)(Bs + j * 16 * LDT + ks * 32);
; #pragma unroll
;       for (int i = 0; i < MI; ++i) {
;         const bf16x8 a = *(const bf16x8*)(As + i * 16 * LDT + ks * 32);
; #pragma unroll
;         for (int j = 0; j < NJ; ++j) acc[i][j] = SWAP ? mfma16(b[j], a, acc[i][j]) : mfma16(a, b[j], acc[i][j]);
;       }
;     }
;     __syncthreads();
;   }
	s_add_i32 s21, s21, 1
	s_cmp_lg_u32 s21, 44
	s_cbranch_scc0 .Lgm7_exit
	s_and_b32 s98, s21, 1
	s_mul_i32 s98, s98, 0x12000
	v_add3_u32 v202, s98, v160, v176
	v_add3_u32 v177, s98, v171, v176
	ds_read_b128 v[194:197], v177
	ds_read_b128 v[198:201], v177 offset:2304
	v_mfma_f32_16x16x32_bf16 v[28:31], v[178:181], v[242:245], v[28:31]
	v_mfma_f32_16x16x32_bf16 v[8:11], v[178:181], v[246:249], v[8:11]
	ds_read_b128 v[178:181], v202 offset:36864
	v_mfma_f32_16x16x32_bf16 v[24:27], v[182:185], v[242:245], v[24:27]
	v_mfma_f32_16x16x32_bf16 v[4:7], v[182:185], v[246:249], v[4:7]
	ds_read_b128 v[182:185], v202 offset:39168
	v_mfma_f32_16x16x32_bf16 v[20:23], v[186:189], v[242:245], v[20:23]
	v_mfma_f32_16x16x32_bf16 v[0:3], v[186:189], v[246:249], v[0:3]
	ds_read_b128 v[186:189], v202 offset:41472
	v_mfma_f32_16x16x32_bf16 v[16:19], v[190:193], v[242:245], v[16:19]
	v_mfma_f32_16x16x32_bf16 v[12:15], v[190:193], v[246:249], v[12:15]
	ds_read_b128 v[190:193], v202 offset:43776
	s_branch .Lgm7_main

; DI f32x4 mfma16(bf16x8 a, bf16x8 b, f32x4 c) { return __builtin_amdgcn_mfma_f32_16x16x32_bf16(a, b, c, 0, 0, 0); }
; template <int MI, int NJ, bool SWAP, class AP, class BP>
; DI void gemm_main(f32x4 (&acc)[MI][NJ], const AP& ap, int a_kstep, const BP& bp, int b_kstep, int nk, bf16_t* smem) {
;     ...
;   auto gload = [&](int kt) {
;     const bf16_t* ab = ap.base + (size_t)kt * a_kstep; const bf16_t* bb = bp.base + (size_t)kt * b_kstep;
; #pragma unroll
;     for (int i = 0; i < CA; ++i) ra[i] = *(const u32x4*)(ab + pa[i]);
; #pragma unroll
;     for (int i = 0; i < CB; ++i) rb[i] = *(const u32x4*)(bb + pb[i]);
;   };
;   auto sstore = [&](int buf) {
;     bf16_t* As = smem + buf * L::STAGE; bf16_t* Bs = As + L::A_ELEMS;
; #pragma unroll
;     for (int i = 0; i < CA; ++i) { const int c = tid + NTHR * i; *(u32x4*)(As + (c >> 3) * LDT + (c & 7) * 8) = oka[i] ? ra[i] : (u32x4){0u, 0u, 0u, 0u}; }
; #pragma unroll
;     for (int i = 0; i < CB; ++i) { const int c = tid + NTHR * i; *(u32x4*)(Bs + (c >> 3) * LDT + (c & 7) * 8) = rb[i]; }
;   };
;   gload(0); sstore(0); gload(nk > 1 ? 1 : 0); __syncthreads();
; #pragma unroll 1
;   for (int kt = 0; kt < nk; ++kt) {
;     const int buf = kt & 1;
;     sstore(buf ^ 1);
;     gload(kt + 2 < nk ? kt + 2 : nk - 1);
;     __builtin_amdgcn_sched_barrier(0);
;     const bf16_t* As = smem + buf * L::STAGE + (wm * 16 * MI + l15) * LDT + quad * 8;
;     const bf16_t* Bs = smem + buf * L::STAGE + L::A_ELEMS + (wn * 16 * NJ + l15) * LDT + quad * 8;
; #pragma unroll
;     for (int ks = 0; ks < 2; ++ks) {
;       if (MI * NJ >= 32 && ks == 1) asm volatile("" ::: "memory");
;       bf16x8 b[NJ];
; #pragma unroll
;       for (int j = 0; j < NJ; ++j) b[j] = *(const bf16x8*)(Bs + j * 16 * LDT + ks * 32);
; #pragma unroll
;       for (int i = 0; i < MI; ++i) {
;         const bf16x8 a = *(const bf16x8*)(As + i * 16 * LDT + ks * 32);
; #pragma unroll
;         for (int j = 0; j < NJ; ++j) acc[i][j] = SWAP ? mfma16(b[j], a, acc[i][j]) : mfma16(a, b[j], acc[i][j]);
;       }
;     }
;     __syncthreads();
;   }
.Lgm8_main:
	ds_read_b128 v[246:249], v210 offset:4608
	s_waitcnt lgkmcnt(4)
	v_mfma_f32_16x16x32_bf16 v[124:127], v[190:193], v[206:209], v[124:127]
	s_waitcnt lgkmcnt(3)
	v_mfma_f32_16x16x32_bf16 v[120:123], v[194:197], v[206:209], v[120:123]
	s_waitcnt lgkmcnt(2)
	v_mfma_f32_16x16x32_bf16 v[116:119], v[198:201], v[206:209], v[116:119]
	s_and_b32 s5, s4, 1
	s_xor_b32 s23, s5, 1
	s_mul_i32 s23, s23, 0x12000
	v_add3_u32 v254, s23, v185, v183
	s_waitcnt vmcnt(7)
	ds_write_b128 v254, v[128:131]
	s_waitcnt lgkmcnt(2)
	v_mfma_f32_16x16x32_bf16 v[112:115], v[202:205], v[206:209], v[112:115]
	ds_read_b128 v[250:253], v210 offset:6912
	v_mfma_f32_16x16x32_bf16 v[108:111], v[190:193], v[242:245], v[108:111]
	s_min_u32 s99, s4, 13
	s_lshl_b32 s99, s99, 7
	s_add_u32 s26, s0, s99
	s_addc_u32 s27, s1, 0
	v_lshl_add_u64 v[128:129], s[26:27], 0, v[162:163]
	s_nop 0
	global_load_dwordx4 v[128:131], v[128:129], off offset:256
	v_mfma_f32_16x16x32_bf16 v[104:107], v[194:197], v[242:245], v[104:107]
	v_mfma_f32_16x16x32_bf16 v[100:103], v[198:201], v[242:245], v[100:103]
	v_mfma_f32_16x16x32_bf16 v[96:99], v[202:205], v[242:245], v[96:99]
	ds_read_b128 v[206:209], v210 offset:9216
	s_waitcnt lgkmcnt(3)
	v_mfma_f32_16x16x32_bf16 v[92:95], v[190:193], v[246:249], v[92:95]
	v_add3_u32 v238, s23, v187, v183
	s_waitcnt vmcnt(7)
	ds_write_b128 v238, v[132:135]
	v_mfma_f32_16x16x32_bf16 v[88:91], v[194:197], v[246:249], v[88:91]
	v_mfma_f32_16x16x32_bf16 v[84:87], v[198:201], v[246:249], v[84:87]
	v_lshl_add_u64 v[132:133], s[26:27], 0, v[164:165]
	s_nop 0
	global_load_dwordx4 v[132:135], v[132:133], off offset:256
	v_mfma_f32_16x16x32_bf16 v[80:83], v[202:205], v[246:249], v[80:83]
	ds_read_b128 v[242:245], v210 offset:11520
	s_waitcnt lgkmcnt(3)
	v_mfma_f32_16x16x32_bf16 v[76:79], v[190:193], v[250:253], v[76:79]
	v_mfma_f32_16x16x32_bf16 v[72:75], v[194:197], v[250:253], v[72:75]
	v_mfma_f32_16x16x32_bf16 v[68:71], v[198:201], v[250:253], v[68:71]
	v_add3_u32 v239, s23, v188, v183
	s_waitcnt vmcnt(7)
	ds_write_b128 v239, v[136:139]
	v_mfma_f32_16x16x32_bf16 v[64:67], v[202:205], v[250:253], v[64:67]
	ds_read_b128 v[246:249], v210 offset:13824
	s_waitcnt lgkmcnt(4)
	v_mfma_f32_16x16x32_bf16 v[60:63], v[190:193], v[206:209], v[60:63]
	v_lshl_add_u64 v[136:137], s[26:27], 0, v[166:167]
	s_nop 0
	global_load_dwordx4 v[136:139], v[136:137], off offset:256
	v_mfma_f32_16x16x32_bf16 v[56:59], v[194:197], v[206:209], v[56:59]
	v_mfma_f32_16x16x32_bf16 v[52:55], v[198:201], v[206:209], v[52:55]
	v_mfma_f32_16x16x32_bf16 v[48:51], v[202:205], v[206:209], v[48:51]
	ds_read_b128 v[250:253], v210 offset:16128
	s_waitcnt lgkmcnt(3)
	v_mfma_f32_16x16x32_bf16 v[44:47], v[190:193], v[242:245], v[44:47]
	v_add3_u32 v255, s23, v189, v183
	s_waitcnt vmcnt(7)
	ds_write_b128 v255, v[140:143]
	v_mfma_f32_16x16x32_bf16 v[40:43], v[194:197], v[242:245], v[40:43]
	v_mfma_f32_16x16x32_bf16 v[36:39], v[198:201], v[242:245], v[36:39]
	v_lshl_add_u64 v[140:141], s[26:27], 0, v[168:169]
	s_nop 0
	global_load_dwordx4 v[140:143], v[140:141], off offset:256
	v_mfma_f32_16x16x32_bf16 v[32:35], v[202:205], v[242:245], v[32:35]
	ds_read_b128 v[206:209], v210 offset:64
	s_waitcnt lgkmcnt(3)
	v_mfma_f32_16x16x32_bf16 v[28:31], v[190:193], v[246:249], v[28:31]
	v_mfma_f32_16x16x32_bf16 v[24:27], v[194:197], v[246:249], v[24:27]
	v_mfma_f32_16x16x32_bf16 v[20:23], v[198:201], v[246:249], v[20:23]
	s_waitcnt vmcnt(7)
	ds_write_b128 v254, v[144:147] offset:36864
	v_mfma_f32_16x16x32_bf16 v[16:19], v[202:205], v[246:249], v[16:19]
	ds_read_b128 v[242:245], v210 offset:2368
	s_waitcnt lgkmcnt(4)
	v_mfma_f32_16x16x32_bf16 v[12:15], v[190:193], v[250:253], v[12:15]
	ds_read_b128 v[190:193], v211 offset:36928
	s_add_u32 s26, s2, s99
	s_addc_u32 s27, s3, 0
	v_lshl_add_u64 v[144:145], s[26:27], 0, v[162:163]
	s_nop 0
	global_load_dwordx4 v[144:147], v[144:145], off offset:256
	v_mfma_f32_16x16x32_bf16 v[8:11], v[194:197], v[250:253], v[8:11]
	ds_read_b128 v[194:197], v211 offset:39232
	v_mfma_f32_16x16x32_bf16 v[4:7], v[198:201], v[250:253], v[4:7]
	ds_read_b128 v[198:201], v211 offset:41536
	v_mfma_f32_16x16x32_bf16 v[0:3], v[202:205], v[250:253], v[0:3]
	ds_read_b128 v[202:205], v211 offset:43840
	ds_read_b128 v[246:249], v210 offset:4672
	s_waitcnt lgkmcnt(4)
	v_mfma_f32_16x16x32_bf16 v[124:127], v[190:193], v[206:209], v[124:127]
	s_waitcnt vmcnt(7)
	ds_write_b128 v238, v[148:151] offset:36864
	s_waitcnt lgkmcnt(4)
	v_mfma_f32_16x16x32_bf16 v[120:123], v[194:197], v[206:209], v[120:123]
	s_waitcnt lgkmcnt(3)
	v_mfma_f32_16x16x32_bf16 v[116:119], v[198:201], v[206:209], v[116:119]
	v_lshl_add_u64 v[148:149], s[26:27], 0, v[164:165]
	s_nop 0
	global_load_dwordx4 v[148:151], v[148:149], off offset:256
	s_waitcnt lgkmcnt(2)
	v_mfma_f32_16x16x32_bf16 v[112:115], v[202:205], v[206:209], v[112:115]
	ds_read_b128 v[250:253], v210 offset:6976
	v_mfma_f32_16x16x32_bf16 v[108:111], v[190:193], v[242:245], v[108:111]
	v_mfma_f32_16x16x32_bf16 v[104:107], v[194:197], v[242:245], v[104:107]
	v_mfma_f32_16x16x32_bf16 v[100:103], v[198:201], v[242:245], v[100:103]
	s_waitcnt vmcnt(7)
	ds_write_b128 v239, v[152:155] offset:36864
	v_mfma_f32_16x16x32_bf16 v[96:99], v[202:205], v[242:245], v[96:99]
	ds_read_b128 v[206:209], v210 offset:9280
	s_waitcnt lgkmcnt(4)
	v_mfma_f32_16x16x32_bf16 v[92:95], v[190:193], v[246:249], v[92:95]
	v_lshl_add_u64 v[152:153], s[26:27], 0, v[166:167]
	s_nop 0
	global_load_dwordx4 v[152:155], v[152:153], off offset:256
	v_mfma_f32_16x16x32_bf16 v[88:91], v[194:197], v[246:249], v[88:91]
	v_mfma_f32_16x16x32_bf16 v[84:87], v[198:201], v[246:249], v[84:87]
	v_mfma_f32_16x16x32_bf16 v[80:83], v[202:205], v[246:249], v[80:83]
	ds_read_b128 v[242:245], v210 offset:11584
	s_waitcnt lgkmcnt(3)
	v_mfma_f32_16x16x32_bf16 v[76:79], v[190:193], v[250:253], v[76:79]
	s_waitcnt vmcnt(7)
	ds_write_b128 v255, v[156:159] offset:36864
	v_mfma_f32_16x16x32_bf16 v[72:75], v[194:197], v[250:253], v[72:75]
	v_mfma_f32_16x16x32_bf16 v[68:71], v[198:201], v[250:253], v[68:71]
	v_lshl_add_u64 v[156:157], s[26:27], 0, v[168:169]
	s_nop 0
	global_load_dwordx4 v[156:159], v[156:157], off offset:256
	v_mfma_f32_16x16x32_bf16 v[64:67], v[202:205], v[250:253], v[64:67]
	ds_read_b128 v[246:249], v210 offset:13888
	s_waitcnt lgkmcnt(3)
	v_mfma_f32_16x16x32_bf16 v[60:63], v[190:193], v[206:209], v[60:63]
	v_mfma_f32_16x16x32_bf16 v[56:59], v[194:197], v[206:209], v[56:59]
	v_mfma_f32_16x16x32_bf16 v[52:55], v[198:201], v[206:209], v[52:55]
	v_mfma_f32_16x16x32_bf16 v[48:51], v[202:205], v[206:209], v[48:51]
	ds_read_b128 v[250:253], v210 offset:16192
	s_waitcnt lgkmcnt(3)
	v_mfma_f32_16x16x32_bf16 v[44:47], v[190:193], v[242:245], v[44:47]
	v_mfma_f32_16x16x32_bf16 v[40:43], v[194:197], v[242:245], v[40:43]
	v_mfma_f32_16x16x32_bf16 v[36:39], v[198:201], v[242:245], v[36:39]
	v_mfma_f32_16x16x32_bf16 v[32:35], v[202:205], v[242:245], v[32:35]
	s_waitcnt lgkmcnt(0)
	s_barrier
; DI f32x4 mfma16(bf16x8 a, bf16x8 b, f32x4 c) { return __builtin_amdgcn_mfma_f32_16x16x32_bf16(a, b, c, 0, 0, 0); }
; template <int MI, int NJ, bool SWAP, class AP, class BP>
; DI void gemm_main(f32x4 (&acc)[MI][NJ], const AP& ap, int a_kstep, const BP& bp, int b_kstep, int nk, bf16_t* smem) {
;     ...
;   for (int kt = 0; kt < nk; ++kt) {
;     const int buf = kt & 1;
;     sstore(buf ^ 1);
;     gload(kt + 2 < nk ? kt + 2 : nk - 1);
;     __builtin_amdgcn_sched_barrier(0);
;     const bf16_t* As = smem + buf * L::STAGE + (wm * 16 * MI + l15) * LDT + quad * 8;
;     const bf16_t* Bs = smem + buf * L::STAGE + L::A_ELEMS + (wn * 16 * NJ + l15) * LDT + quad * 8;
; #pragma unroll
;     for (int ks = 0; ks < 2; ++ks) {
;       if (MI * NJ >= 32 && ks == 1) asm volatile("" ::: "memory");
;       bf16x8 b[NJ];
; #pragma unroll
;       for (int j = 0; j < NJ; ++j) b[j] = *(const bf16x8*)(Bs + j * 16 * LDT + ks * 32);
; #pragma unroll
;       for (int i = 0; i < MI; ++i) {
;         const bf16x8 a = *(const bf16x8*)(As + i * 16 * LDT + ks * 32);
; #pragma unroll
;         for (int j = 0; j < NJ; ++j) acc[i][j] = SWAP ? mfma16(b[j], a, acc[i][j]) : mfma16(a, b[j], acc[i][j]);
;       }
;     }
;     __syncthreads();
;   }
	s_add_i32 s4, s4, 1
	s_cmp_lg_u32 s4, 16
	s_cbranch_scc0 .Lgm8_exit
	s_and_b32 s98, s4, 1
	s_mul_i32 s98, s98, 0x12000
	v_add3_u32 v210, s98, v184, v186
	v_add3_u32 v211, s98, v160, v186
	ds_read_b128 v[206:209], v210
	ds_read_b128 v[242:245], v210 offset:2304
	v_mfma_f32_16x16x32_bf16 v[28:31], v[190:193], v[246:249], v[28:31]
	v_mfma_f32_16x16x32_bf16 v[12:15], v[190:193], v[250:253], v[12:15]
	ds_read_b128 v[190:193], v211 offset:36864
	v_mfma_f32_16x16x32_bf16 v[24:27], v[194:197], v[246:249], v[24:27]
	v_mfma_f32_16x16x32_bf16 v[8:11], v[194:197], v[250:253], v[8:11]
	ds_read_b128 v[194:197], v211 offset:39168
	v_mfma_f32_16x16x32_bf16 v[20:23], v[198:201], v[246:249], v[20:23]
	v_mfma_f32_16x16x32_bf16 v[4:7], v[198:201], v[250:253], v[4:7]
	ds_read_b128 v[198:201], v211 offset:41472
	v_mfma_f32_16x16x32_bf16 v[16:19], v[202:205], v[246:249], v[16:19]
	v_mfma_f32_16x16x32_bf16 v[0:3], v[202:205], v[250:253], v[0:3]
	ds_read_b128 v[202:205], v211 offset:43776
	s_branch .Lgm8_main

; DI f32x4 mfma16(bf16x8 a, bf16x8 b, f32x4 c) { return __builtin_amdgcn_mfma_f32_16x16x32_bf16(a, b, c, 0, 0, 0); }
; template <int MI, int NJ, bool SWAP, class AP, class BP>
; DI void gemm_main(f32x4 (&acc)[MI][NJ], const AP& ap, int a_kstep, const BP& bp, int b_kstep, int nk, bf16_t* smem) {
;     ...
;   for (int kt = 0; kt < nk; ++kt) {
;     const int buf = kt & 1;
;     sstore(buf ^ 1);
;     gload(kt + 2 < nk ? kt + 2 : nk - 1);
;     __builtin_amdgcn_sched_barrier(0);
;     const bf16_t* As = smem + buf * L::STAGE + (wm * 16 * MI + l15) * LDT + quad * 8;
;     const bf16_t* Bs = smem + buf * L::STAGE + L::A_ELEMS + (wn * 16 * NJ + l15) * LDT + quad * 8;
; #pragma unroll
;     for (int ks = 0; ks < 2; ++ks) {
;       if (MI * NJ >= 32 && ks == 1) asm volatile("" ::: "memory");
;       bf16x8 b[NJ];
; #pragma unroll
;       for (int j = 0; j < NJ; ++j) b[j] = *(const bf16x8*)(Bs + j * 16 * LDT + ks * 32);
; #pragma unroll
;       for (int i = 0; i < MI; ++i) {
;         const bf16x8 a = *(const bf16x8*)(As + i * 16 * LDT + ks * 32);
; #pragma unroll
;         for (int j = 0; j < NJ; ++j) acc[i][j] = SWAP ? mfma16(b[j], a, acc[i][j]) : mfma16(a, b[j], acc[i][j]);
;       }
;     }
;     __syncthreads();
;   }
.Lgm10_main:
	ds_read_b128 v[246:249], v198 offset:4608
	s_waitcnt lgkmcnt(4)
	v_mfma_f32_16x16x32_bf16 v[156:159], v[178:181], v[194:197], v[156:159]
	s_waitcnt lgkmcnt(3)
	v_mfma_f32_16x16x32_bf16 v[152:155], v[182:185], v[194:197], v[152:155]
	s_waitcnt lgkmcnt(2)
	v_mfma_f32_16x16x32_bf16 v[148:151], v[186:189], v[194:197], v[148:151]
	s_and_b32 s33, s8, 1
	s_xor_b32 s37, s33, 1
	s_mul_i32 s37, s37, 0x12000
	v_add3_u32 v254, s37, v173, v171
	s_waitcnt vmcnt(7)
	ds_write_b128 v254, v[112:115]
	s_waitcnt lgkmcnt(2)
	v_mfma_f32_16x16x32_bf16 v[144:147], v[190:193], v[194:197], v[144:147]
	ds_read_b128 v[250:253], v198 offset:6912
	v_mfma_f32_16x16x32_bf16 v[108:111], v[178:181], v[242:245], v[108:111]
	s_min_u32 s99, s8, 3
	s_lshl_b32 s99, s99, 7
	s_add_u32 s38, s0, s99
	s_addc_u32 s39, s1, 0
	v_lshl_add_u64 v[112:113], s[38:39], 0, v[162:163]
	s_nop 0
	global_load_dwordx4 v[112:115], v[112:113], off offset:256
	v_mfma_f32_16x16x32_bf16 v[104:107], v[182:185], v[242:245], v[104:107]
	v_mfma_f32_16x16x32_bf16 v[100:103], v[186:189], v[242:245], v[100:103]
	v_mfma_f32_16x16x32_bf16 v[96:99], v[190:193], v[242:245], v[96:99]
	ds_read_b128 v[194:197], v198 offset:9216
	s_waitcnt lgkmcnt(3)
	v_mfma_f32_16x16x32_bf16 v[92:95], v[178:181], v[246:249], v[92:95]
	v_add3_u32 v238, s37, v174, v171
	s_waitcnt vmcnt(6)
	ds_write_b128 v238, v[116:119]
	v_mfma_f32_16x16x32_bf16 v[88:91], v[182:185], v[246:249], v[88:91]
	v_mfma_f32_16x16x32_bf16 v[84:87], v[186:189], v[246:249], v[84:87]
	v_lshl_add_u64 v[116:117], s[38:39], 0, v[164:165]
	s_nop 0
	global_load_dwordx4 v[116:119], v[116:117], off offset:256
	v_mfma_f32_16x16x32_bf16 v[80:83], v[190:193], v[246:249], v[80:83]
	ds_read_b128 v[242:245], v198 offset:11520
	s_waitcnt lgkmcnt(3)
	v_mfma_f32_16x16x32_bf16 v[76:79], v[178:181], v[250:253], v[76:79]
	v_mfma_f32_16x16x32_bf16 v[72:75], v[182:185], v[250:253], v[72:75]
	v_mfma_f32_16x16x32_bf16 v[68:71], v[186:189], v[250:253], v[68:71]
	v_add3_u32 v239, s37, v175, v171
	s_waitcnt vmcnt(6)
	ds_write_b128 v239, v[120:123]
	v_mfma_f32_16x16x32_bf16 v[64:67], v[190:193], v[250:253], v[64:67]
	ds_read_b128 v[246:249], v198 offset:13824
	s_waitcnt lgkmcnt(4)
	v_mfma_f32_16x16x32_bf16 v[60:63], v[178:181], v[194:197], v[60:63]
	v_lshl_add_u64 v[120:121], s[38:39], 0, v[166:167]
	s_nop 0
	global_load_dwordx4 v[120:123], v[120:121], off offset:256
	v_mfma_f32_16x16x32_bf16 v[56:59], v[182:185], v[194:197], v[56:59]
	v_mfma_f32_16x16x32_bf16 v[52:55], v[186:189], v[194:197], v[52:55]
	v_mfma_f32_16x16x32_bf16 v[48:51], v[190:193], v[194:197], v[48:51]
	ds_read_b128 v[250:253], v198 offset:16128
	s_waitcnt lgkmcnt(3)
	v_mfma_f32_16x16x32_bf16 v[44:47], v[178:181], v[242:245], v[44:47]
	v_add3_u32 v255, s37, v176, v171
	s_waitcnt vmcnt(6)
	ds_write_b128 v255, v[124:127]
	v_mfma_f32_16x16x32_bf16 v[40:43], v[182:185], v[242:245], v[40:43]
	v_mfma_f32_16x16x32_bf16 v[36:39], v[186:189], v[242:245], v[36:39]
	v_lshl_add_u64 v[124:125], s[38:39], 0, v[168:169]
	s_nop 0
	global_load_dwordx4 v[124:127], v[124:125], off offset:256
	v_mfma_f32_16x16x32_bf16 v[32:35], v[190:193], v[242:245], v[32:35]
	ds_read_b128 v[194:197], v198 offset:64
	s_waitcnt lgkmcnt(3)
	v_mfma_f32_16x16x32_bf16 v[28:31], v[178:181], v[246:249], v[28:31]
	v_mfma_f32_16x16x32_bf16 v[24:27], v[182:185], v[246:249], v[24:27]
	v_mfma_f32_16x16x32_bf16 v[20:23], v[186:189], v[246:249], v[20:23]
	ds_write_b128 v254, v[128:131] offset:36864
	v_mfma_f32_16x16x32_bf16 v[16:19], v[190:193], v[246:249], v[16:19]
	ds_read_b128 v[242:245], v198 offset:2368
	s_waitcnt lgkmcnt(4)
	v_mfma_f32_16x16x32_bf16 v[12:15], v[178:181], v[250:253], v[12:15]
	ds_read_b128 v[178:181], v199 offset:36928
	s_add_u32 s38, s2, s99
	s_addc_u32 s39, s3, 0
	v_lshl_add_u64 v[128:129], s[38:39], 0, v[162:163]
	s_nop 0
	global_load_dwordx4 v[128:131], v[128:129], off offset:256
	v_mfma_f32_16x16x32_bf16 v[8:11], v[182:185], v[250:253], v[8:11]
	ds_read_b128 v[182:185], v199 offset:39232
	v_mfma_f32_16x16x32_bf16 v[4:7], v[186:189], v[250:253], v[4:7]
	ds_read_b128 v[186:189], v199 offset:41536
	v_mfma_f32_16x16x32_bf16 v[0:3], v[190:193], v[250:253], v[0:3]
	ds_read_b128 v[190:193], v199 offset:43840
	ds_read_b128 v[246:249], v198 offset:4672
	s_waitcnt lgkmcnt(4)
	v_mfma_f32_16x16x32_bf16 v[156:159], v[178:181], v[194:197], v[156:159]
	s_waitcnt vmcnt(7)
	ds_write_b128 v238, v[132:135] offset:36864
	s_waitcnt lgkmcnt(4)
	v_mfma_f32_16x16x32_bf16 v[152:155], v[182:185], v[194:197], v[152:155]
	s_waitcnt lgkmcnt(3)
	v_mfma_f32_16x16x32_bf16 v[148:151], v[186:189], v[194:197], v[148:151]
	v_lshl_add_u64 v[132:133], s[38:39], 0, v[164:165]
	s_nop 0
	global_load_dwordx4 v[132:135], v[132:133], off offset:256
	s_waitcnt lgkmcnt(2)
	v_mfma_f32_16x16x32_bf16 v[144:147], v[190:193], v[194:197], v[144:147]
	ds_read_b128 v[250:253], v198 offset:6976
	v_mfma_f32_16x16x32_bf16 v[108:111], v[178:181], v[242:245], v[108:111]
	v_mfma_f32_16x16x32_bf16 v[104:107], v[182:185], v[242:245], v[104:107]
	v_mfma_f32_16x16x32_bf16 v[100:103], v[186:189], v[242:245], v[100:103]
	s_waitcnt vmcnt(7)
	ds_write_b128 v239, v[136:139] offset:36864
	v_mfma_f32_16x16x32_bf16 v[96:99], v[190:193], v[242:245], v[96:99]
	ds_read_b128 v[194:197], v198 offset:9280
	s_waitcnt lgkmcnt(4)
	v_mfma_f32_16x16x32_bf16 v[92:95], v[178:181], v[246:249], v[92:95]
	v_lshl_add_u64 v[136:137], s[38:39], 0, v[166:167]
	s_nop 0
	global_load_dwordx4 v[136:139], v[136:137], off offset:256
	v_mfma_f32_16x16x32_bf16 v[88:91], v[182:185], v[246:249], v[88:91]
	v_mfma_f32_16x16x32_bf16 v[84:87], v[186:189], v[246:249], v[84:87]
	v_mfma_f32_16x16x32_bf16 v[80:83], v[190:193], v[246:249], v[80:83]
	ds_read_b128 v[242:245], v198 offset:11584
	s_waitcnt lgkmcnt(3)
	v_mfma_f32_16x16x32_bf16 v[76:79], v[178:181], v[250:253], v[76:79]
	s_waitcnt vmcnt(7)
	ds_write_b128 v255, v[140:143] offset:36864
	v_mfma_f32_16x16x32_bf16 v[72:75], v[182:185], v[250:253], v[72:75]
	v_mfma_f32_16x16x32_bf16 v[68:71], v[186:189], v[250:253], v[68:71]
	v_lshl_add_u64 v[140:141], s[38:39], 0, v[168:169]
	s_nop 0
	global_load_dwordx4 v[140:143], v[140:141], off offset:256
	v_mfma_f32_16x16x32_bf16 v[64:67], v[190:193], v[250:253], v[64:67]
	ds_read_b128 v[246:249], v198 offset:13888
	s_waitcnt lgkmcnt(3)
	v_mfma_f32_16x16x32_bf16 v[60:63], v[178:181], v[194:197], v[60:63]
	v_mfma_f32_16x16x32_bf16 v[56:59], v[182:185], v[194:197], v[56:59]
	v_mfma_f32_16x16x32_bf16 v[52:55], v[186:189], v[194:197], v[52:55]
	v_mfma_f32_16x16x32_bf16 v[48:51], v[190:193], v[194:197], v[48:51]
	ds_read_b128 v[250:253], v198 offset:16192
	s_waitcnt lgkmcnt(3)
	v_mfma_f32_16x16x32_bf16 v[44:47], v[178:181], v[242:245], v[44:47]
	v_mfma_f32_16x16x32_bf16 v[40:43], v[182:185], v[242:245], v[40:43]
	v_mfma_f32_16x16x32_bf16 v[36:39], v[186:189], v[242:245], v[36:39]
	v_mfma_f32_16x16x32_bf16 v[32:35], v[190:193], v[242:245], v[32:35]
	s_waitcnt lgkmcnt(0)
	s_barrier
; DI f32x4 mfma16(bf16x8 a, bf16x8 b, f32x4 c) { return __builtin_amdgcn_mfma_f32_16x16x32_bf16(a, b, c, 0, 0, 0); }
; template <int MI, int NJ, bool SWAP, class AP, class BP>
; DI void gemm_main(f32x4 (&acc)[MI][NJ], const AP& ap, int a_kstep, const BP& bp, int b_kstep, int nk, bf16_t* smem) {
;     ...
;   for (int kt = 0; kt < nk; ++kt) {
;     const int buf = kt & 1;
;     sstore(buf ^ 1);
;     gload(kt + 2 < nk ? kt + 2 : nk - 1);
;     __builtin_amdgcn_sched_barrier(0);
;     const bf16_t* As = smem + buf * L::STAGE + (wm * 16 * MI + l15) * LDT + quad * 8;
;     const bf16_t* Bs = smem + buf * L::STAGE + L::A_ELEMS + (wn * 16 * NJ + l15) * LDT + quad * 8;
; #pragma unroll
;     for (int ks = 0; ks < 2; ++ks) {
;       if (MI * NJ >= 32 && ks == 1) asm volatile("" ::: "memory");
;       bf16x8 b[NJ];
; #pragma unroll
;       for (int j = 0; j < NJ; ++j) b[j] = *(const bf16x8*)(Bs + j * 16 * LDT + ks * 32);
; #pragma unroll
;       for (int i = 0; i < MI; ++i) {
;         const bf16x8 a = *(const bf16x8*)(As + i * 16 * LDT + ks * 32);
; #pragma unroll
;         for (int j = 0; j < NJ; ++j) acc[i][j] = SWAP ? mfma16(b[j], a, acc[i][j]) : mfma16(a, b[j], acc[i][j]);
;       }
;     }
;     __syncthreads();
;   }
	s_add_i32 s8, s8, 1
	s_cmp_lg_u32 s8, 6
	s_cbranch_scc0 .Lgm10_exit
	s_and_b32 s98, s8, 1
	s_mul_i32 s98, s98, 0x12000
	v_add3_u32 v198, s98, v172, v177
	v_add3_u32 v199, s98, v160, v177
	ds_read_b128 v[194:197], v198
	ds_read_b128 v[242:245], v198 offset:2304
	v_mfma_f32_16x16x32_bf16 v[28:31], v[178:181], v[246:249], v[28:31]
	v_mfma_f32_16x16x32_bf16 v[12:15], v[178:181], v[250:253], v[12:15]
	ds_read_b128 v[178:181], v199 offset:36864
	v_mfma_f32_16x16x32_bf16 v[24:27], v[182:185], v[246:249], v[24:27]
	v_mfma_f32_16x16x32_bf16 v[8:11], v[182:185], v[250:253], v[8:11]
	ds_read_b128 v[182:185], v199 offset:39168
	v_mfma_f32_16x16x32_bf16 v[20:23], v[186:189], v[246:249], v[20:23]
	v_mfma_f32_16x16x32_bf16 v[4:7], v[186:189], v[250:253], v[4:7]
	ds_read_b128 v[186:189], v199 offset:41472
	v_mfma_f32_16x16x32_bf16 v[16:19], v[190:193], v[246:249], v[16:19]
	v_mfma_f32_16x16x32_bf16 v[0:3], v[190:193], v[250:253], v[0:3]
	ds_read_b128 v[190:193], v199 offset:43776
	s_branch .Lgm10_main

; DI float ex2(float x) { return __builtin_amdgcn_exp2f(x); }
; template <int MODE>
; DI void flash_pass(AState& st, const bf16x8* qf, u64 tmask, u64 wmask,
;                    const bf16_t* kbase, size_t kld, const bf16_t* kpe, const bf16_t* vtbase, const float* fbias,
;                    int tq, u64 mysel, bf16_t* smem) {
;     ...
;       int im = (int)0x80000000;
; #pragma unroll
;       for (int r = 0; r < 16; ++r) im = max(im, max(__float_as_int(s0[r]), __float_as_int(s1[r])));
;       im = max(im, __shfl_xor(im, 32));
;       constexpr int TBITS = 0x41800000;
;       f32x16 e0, e1;
; #pragma unroll
;       for (int r = 0; r < 16; ++r) { e0[r] = ex2(s0[r]); e1[r] = ex2(s1[r]); }
;       if (__any(im > TBITS)) {
;         const float d = im > TBITS ? __int_as_float(im) : 0.f;
;         const float a = ex2(-d);
; #pragma unroll
;         for (int r = 0; r < 16; ++r) { e0[r] = ex2(s0[r] - d); e1[r] = ex2(s1[r] - d); st.o[0][r] *= a; st.o[1][r] *= a; }
;         st.l *= a; st.m += d;
; #pragma unroll
;         for (int r = 0; r < 16; ++r) st.mr[r] = -st.m;
;       }
.LBB0_1646:
	s_nop 10
	v_max_i32_e32 v2, v81, v65
	v_max3_i32 v2, v80, v64, v2
	v_max_i32_e32 v3, v82, v66
	v_max_i32_e32 v4, v83, v67
	v_max3_i32 v2, v2, v3, v4
	v_max_i32_e32 v3, v84, v68
	v_max_i32_e32 v4, v85, v69
	v_max3_i32 v2, v2, v3, v4
	v_max_i32_e32 v3, v86, v70
	v_max_i32_e32 v4, v87, v71
	v_max3_i32 v2, v2, v3, v4
	v_max_i32_e32 v3, v88, v72
	v_max_i32_e32 v4, v89, v73
	v_max3_i32 v2, v2, v3, v4
	v_max_i32_e32 v3, v90, v74
	v_max_i32_e32 v4, v91, v75
	v_max3_i32 v2, v2, v3, v4
	v_max_i32_e32 v3, v92, v76
	v_max_i32_e32 v4, v93, v77
	v_max3_i32 v2, v2, v3, v4
	v_max_i32_e32 v3, v94, v78
	v_max_i32_e32 v4, v95, v79
	v_max3_i32 v2, v2, v3, v4
	v_mov_b32_e32 v3, v2
	s_nop 1
	v_permlane32_swap_b32_e32 v3, v2
	v_max_i32_e32 v2, v2, v3
	v_cmp_lt_i32_e32 vcc, s88, v2
	s_cbranch_vccz .LBB0_1648
	s_nop 0
	v_cndmask_b32_e32 v49, 0, v2, vcc
	v_sub_f32_e32 v2, v80, v49
	v_exp_f32_e32 v152, v2
	v_sub_f32_e32 v2, v64, v49
	v_exp_f32_e32 v147, v2
	v_sub_f32_e32 v2, v81, v49
	v_exp_f32_e32 v150, v2
	v_sub_f32_e32 v2, v65, v49
	v_exp_f32_e32 v148, v2
	v_sub_f32_e32 v2, v82, v49
	v_exp_f32_e32 v149, v2
	v_sub_f32_e32 v2, v66, v49
	v_sub_f32_e32 v50, v92, v49
	v_exp_f32_e32 v82, v2
	v_sub_f32_e32 v2, v83, v49
	v_exp_f32_e32 v64, v50
	v_sub_f32_e32 v50, v76, v49
	v_exp_f32_e32 v151, v2
	v_sub_f32_e32 v2, v67, v49
	v_exp_f32_e32 v66, v50
	v_sub_f32_e32 v50, v93, v49
	v_exp_f32_e32 v83, v2
	v_sub_f32_e32 v2, v84, v49
	v_exp_f32_e32 v65, v50
	v_sub_f32_e32 v50, v77, v49
	v_exp_f32_e32 v80, v2
	v_sub_f32_e32 v2, v68, v49
	v_exp_f32_e32 v67, v50
	v_sub_f32_e32 v50, v94, v49
	v_exp_f32_e32 v8, v2
	v_sub_f32_e32 v2, v85, v49
	v_sub_f32_e32 v4, v71, v49
	v_exp_f32_e32 v68, v50
	v_sub_f32_e32 v50, v78, v49
	v_exp_f32_e64 v48, -v49
	v_exp_f32_e32 v81, v2
	v_sub_f32_e32 v2, v69, v49
	v_sub_f32_e32 v3, v70, v49
	v_exp_f32_e32 v7, v4
	v_sub_f32_e32 v4, v88, v49
	v_sub_f32_e32 v5, v89, v49
	v_sub_f32_e32 v12, v90, v49
	v_sub_f32_e32 v13, v91, v49
	v_exp_f32_e32 v70, v50
	v_sub_f32_e32 v50, v95, v49
	v_exp_f32_e32 v9, v2
	v_sub_f32_e32 v2, v86, v49
	v_exp_f32_e32 v6, v3
	v_sub_f32_e32 v3, v87, v49
	v_exp_f32_e32 v10, v4
	v_sub_f32_e32 v4, v72, v49
	v_exp_f32_e32 v11, v5
	v_sub_f32_e32 v5, v73, v49
	v_exp_f32_e32 v14, v12
	v_sub_f32_e32 v12, v74, v49
	v_exp_f32_e32 v15, v13
	v_sub_f32_e32 v13, v75, v49
	v_exp_f32_e32 v69, v50
	v_sub_f32_e32 v50, v79, v49
	v_exp_f32_e32 v2, v2
	v_exp_f32_e32 v3, v3
	v_exp_f32_e32 v4, v4
	v_exp_f32_e32 v5, v5
	v_exp_f32_e32 v12, v12
	v_exp_f32_e32 v13, v13
	v_exp_f32_e32 v71, v50
	v_add_f32_e32 v146, v146, v49
	v_pk_mul_f32 v[46:47], v[46:47], v[48:49] op_sel_hi:[1,0]
	v_pk_mul_f32 v[44:45], v[44:45], v[48:49] op_sel_hi:[1,0]
	v_pk_mul_f32 v[42:43], v[42:43], v[48:49] op_sel_hi:[1,0]
	v_pk_mul_f32 v[40:41], v[40:41], v[48:49] op_sel_hi:[1,0]
	v_pk_mul_f32 v[38:39], v[38:39], v[48:49] op_sel_hi:[1,0]
	v_pk_mul_f32 v[36:37], v[36:37], v[48:49] op_sel_hi:[1,0]
	v_pk_mul_f32 v[34:35], v[34:35], v[48:49] op_sel_hi:[1,0]
	v_pk_mul_f32 v[32:33], v[32:33], v[48:49] op_sel_hi:[1,0]
	v_pk_mul_f32 v[30:31], v[30:31], v[48:49] op_sel_hi:[1,0]
	v_pk_mul_f32 v[28:29], v[28:29], v[48:49] op_sel_hi:[1,0]
	v_pk_mul_f32 v[26:27], v[26:27], v[48:49] op_sel_hi:[1,0]
	v_pk_mul_f32 v[24:25], v[24:25], v[48:49] op_sel_hi:[1,0]
	v_pk_mul_f32 v[22:23], v[22:23], v[48:49] op_sel_hi:[1,0]
	v_pk_mul_f32 v[20:21], v[20:21], v[48:49] op_sel_hi:[1,0]
	v_pk_mul_f32 v[18:19], v[18:19], v[48:49] op_sel_hi:[1,0]
	v_pk_mul_f32 v[16:17], v[16:17], v[48:49] op_sel_hi:[1,0]
	v_mul_f32_e32 v178, v178, v48
	v_xor_b32_e32 v48, 0x80000000, v146
	v_mov_b32_e32 v49, v48
	v_mov_b32_e32 v50, v48
	v_mov_b32_e32 v51, v48
	v_mov_b32_e32 v52, v48
	v_mov_b32_e32 v53, v48
	v_mov_b32_e32 v54, v48
	v_mov_b32_e32 v55, v48
	v_mov_b32_e32 v56, v48
	v_mov_b32_e32 v57, v48
	v_mov_b32_e32 v58, v48
	v_mov_b32_e32 v59, v48
	v_mov_b32_e32 v60, v48
	v_mov_b32_e32 v61, v48
	v_mov_b32_e32 v62, v48
	v_mov_b32_e32 v63, v48
	s_branch .LBB0_1649

; template <int MODE>
; DI void flash_pass(AState& st, const bf16x8* qf, u64 tmask, u64 wmask,
;                    const bf16_t* kbase, size_t kld, const bf16_t* kpe, const bf16_t* vtbase, const float* fbias,
;                    int tq, u64 mysel, bf16_t* smem) {
;     ...
;     { const int d = tid >> 3, kc = tid & 7; rv[S] = *(const u32x4*)(vtbase + (size_t)d * S_ + k0 + kc * 8); }
;     if constexpr (MODE == M_FOX) rf[S] = fbias[k0 + (tid & 63)];
;   };
;   auto sstore = [&](int stg, auto setc) {
;     constexpr int S = decltype(setc)::value;
;     bf16_t* Ks = smem + stg * C::STAGE; bf16_t* Vs = Ks + C::K_ELEMS;
; #pragma unroll
;     for (int i = 0; i < C::KCH; ++i) {
;       const int c = tid + NTHR * i;
;       if (c < C::NKC) {
;         if constexpr (MODE == M_MLA) { const int key = c / 12, dc = c % 12; *(u32x4*)(Ks + key * C::KLD + dc * 8) = rk[S][i]; }
;         else { const int key = c >> 3, dc = c & 7; *(u32x4*)(Ks + key * C::KLD + dc * 8) = rk[S][i]; }
;       }
;     }
;     {
;       const int d = tid >> 3, kc = tid & 7, cgp = kc >> 1, a = kc & 1;
;       bf16_t* dst = Vs + d * 72 + cgp * 16 + 4 * a;
;       *(u32x2*)dst = (u32x2){rv[S][0], rv[S][1]}; *(u32x2*)(dst + 8) = (u32x2){rv[S][2], rv[S][3]};
;     }
;     if constexpr (MODE == M_FOX) { if (tid < 64) ((float*)(Vs + C::V_ELEMS))[tid] = rf[S]; }
;   };
;   const int tmin = __builtin_amdgcn_readfirstlane(tq - l31), tmax = tmin + 31;
;   auto compute = [&](int j, int stg) {
;     bool active = (wmask >> j) & 1;
;     if constexpr (MODE == M_SLC) active = active && __any((mysel >> j) & 1);
;     if (active) {
;       const bf16_t* Ks = smem + stg * C::STAGE; const bf16_t* Vs = Ks + C::K_ELEMS;
;       f32x16 s0 = st.mr, s1 = st.mr;
;       const bf16_t* kr = Ks + l31 * C::KLD + half * 8;
; #pragma unroll
;       for (int ks = 0; ks < C::DQK / 16; ++ks) {
;         s0 = mfma32(*(const bf16x8*)(kr + ks * 16), qf[ks], s0);
;         s1 = mfma32(*(const bf16x8*)(kr + 32 * C::KLD + ks * 16), qf[ks], s1);
;       }
;       const int k0 = j * 64;
;       if constexpr (MODE == M_FOX) {
;         const float* fb = (const float*)(Vs + C::V_ELEMS) + 4 * half;
; #pragma unroll
;         for (int g4 = 0; g4 < 4; ++g4) {
;           const f32x4 b0 = *(const f32x4*)(fb + 8 * g4), b1 = *(const f32x4*)(fb + 32 + 8 * g4);
; #pragma unroll
.LBB0_1668:
	s_or_b64 exec, exec, s[2:3]
	s_cmp_eq_u64 s[10:11], 0
	s_cselect_b64 s[8:9], -1, 0
	s_ff1_i32_b64 s17, s[10:11]
	s_and_b64 s[2:3], s[8:9], exec
	s_cselect_b32 s2, s13, s17
	s_lshl_b32 s68, s2, 6
	v_lshl_add_u32 v0, v182, 1, s5
	v_add_u32_e32 v2, s68, v181
	v_add3_u32 v0, v0, v184, v185
	v_ashrrev_i32_e32 v3, 31, v2
	v_add_u32_e32 v0, 0x2000, v0
	v_lshlrev_b64 v[2:3], 8, v[2:3]
	s_waitcnt vmcnt(2)
	ds_write2_b64 v0, v[144:145], v[146:147] offset0:128 offset1:130
	v_lshl_add_u64 v[2:3], v[170:171], 0, v[2:3]
	v_lshl_add_u64 v[4:5], s[68:69], 1, v[172:173]
	global_load_dwordx4 v[148:151], v[2:3], off
	global_load_dwordx4 v[144:147], v[4:5], off
	s_lshl_b64 s[2:3], 1, s13
	s_and_b64 s[20:21], s[2:3], s[6:7]
	s_cmp_eq_u64 s[20:21], 0
	s_cbranch_scc1 .LBB0_1679
	v_and_b32_e32 v3, s3, v167
	v_and_b32_e32 v2, s2, v166
	v_cmp_ne_u64_e64 s[2:3], 0, v[2:3]
	s_mov_b64 vcc, s[2:3]
	s_cbranch_vccz .LBB0_1679
	v_lshl_add_u32 v0, s4, 1, v187
	ds_read_b128 v[2:5], v0
	ds_read_b128 v[6:9], v0 offset:32
	s_lshl_b32 s13, s13, 6
	s_or_b32 s4, s13, 63
	s_cmp_gt_i32 s4, s14
	s_waitcnt lgkmcnt(1)
	v_mfma_f32_32x32x16_bf16 v[96:111], v[2:5], v[140:143], v[80:95]
	ds_read_b128 v[2:5], v0 offset:4608
	ds_read_b128 v[10:13], v0 offset:4640
	s_cselect_b64 s[4:5], -1, 0
	s_and_b64 vcc, exec, s[4:5]
	s_waitcnt lgkmcnt(1)
	v_mfma_f32_32x32x16_bf16 v[112:127], v[2:5], v[140:143], v[80:95]
	v_mfma_f32_32x32x16_bf16 v[96:111], v[6:9], v[128:131], v[96:111]
	ds_read_b128 v[2:5], v0 offset:64
	ds_read_b128 v[6:9], v0 offset:96
	s_waitcnt lgkmcnt(2)
	v_mfma_f32_32x32x16_bf16 v[112:127], v[10:13], v[128:131], v[112:127]
	s_waitcnt lgkmcnt(1)
	v_mfma_f32_32x32x16_bf16 v[96:111], v[2:5], v[132:135], v[96:111]
	ds_read_b128 v[2:5], v0 offset:4672
	ds_read_b128 v[10:13], v0 offset:4704
	s_waitcnt lgkmcnt(1)
	v_mfma_f32_32x32x16_bf16 v[112:127], v[2:5], v[132:135], v[112:127]
	v_mfma_f32_32x32x16_bf16 v[96:111], v[6:9], v[136:139], v[96:111]
	s_waitcnt lgkmcnt(0)
	v_mfma_f32_32x32x16_bf16 v[112:127], v[10:13], v[136:139], v[112:127]
	s_cbranch_vccnz .LBB0_1673
	v_cndmask_b32_e64 v2, 0, 1, s[2:3]
	v_cmp_ne_u32_e32 vcc, 0, v2
	s_cmp_eq_u64 vcc, exec
	s_cbranch_scc1 .LBB0_1673
	s_nop 4
	v_cndmask_b32_e64 v96, v175, v96, s[2:3]
	s_nop 0
	v_cndmask_b32_e64 v112, v175, v112, s[2:3]
	v_cndmask_b32_e64 v97, v175, v97, s[2:3]
	v_cndmask_b32_e64 v113, v175, v113, s[2:3]
	v_cndmask_b32_e64 v98, v175, v98, s[2:3]
	v_cndmask_b32_e64 v114, v175, v114, s[2:3]
	v_cndmask_b32_e64 v99, v175, v99, s[2:3]
	v_cndmask_b32_e64 v115, v175, v115, s[2:3]
	v_cndmask_b32_e64 v100, v175, v100, s[2:3]
	v_cndmask_b32_e64 v116, v175, v116, s[2:3]
	v_cndmask_b32_e64 v101, v175, v101, s[2:3]
	v_cndmask_b32_e64 v117, v175, v117, s[2:3]
	v_cndmask_b32_e64 v102, v175, v102, s[2:3]
	v_cndmask_b32_e64 v118, v175, v118, s[2:3]
	v_cndmask_b32_e64 v103, v175, v103, s[2:3]
	v_cndmask_b32_e64 v119, v175, v119, s[2:3]
	v_cndmask_b32_e64 v104, v175, v104, s[2:3]
	v_cndmask_b32_e64 v120, v175, v120, s[2:3]
	v_cndmask_b32_e64 v105, v175, v105, s[2:3]
	v_cndmask_b32_e64 v121, v175, v121, s[2:3]
	v_cndmask_b32_e64 v106, v175, v106, s[2:3]
	v_cndmask_b32_e64 v122, v175, v122, s[2:3]
	v_cndmask_b32_e64 v107, v175, v107, s[2:3]
	v_cndmask_b32_e64 v123, v175, v123, s[2:3]
	v_cndmask_b32_e64 v108, v175, v108, s[2:3]
	v_cndmask_b32_e64 v124, v175, v124, s[2:3]
	v_cndmask_b32_e64 v109, v175, v109, s[2:3]
	v_cndmask_b32_e64 v125, v175, v125, s[2:3]
	v_cndmask_b32_e64 v110, v175, v110, s[2:3]
	v_cndmask_b32_e64 v126, v175, v126, s[2:3]
	v_cndmask_b32_e64 v111, v175, v111, s[2:3]
	v_cndmask_b32_e64 v127, v175, v127, s[2:3]

; DI float ex2(float x) { return __builtin_amdgcn_exp2f(x); }
; template <int MODE>
; DI void flash_pass(AState& st, const bf16x8* qf, u64 tmask, u64 wmask,
;                    const bf16_t* kbase, size_t kld, const bf16_t* kpe, const bf16_t* vtbase, const float* fbias,
;                    int tq, u64 mysel, bf16_t* smem) {
;     ...
;       int im = (int)0x80000000;
; #pragma unroll
;       for (int r = 0; r < 16; ++r) im = max(im, max(__float_as_int(s0[r]), __float_as_int(s1[r])));
;       im = max(im, __shfl_xor(im, 32));
;       constexpr int TBITS = 0x41800000;
;       f32x16 e0, e1;
; #pragma unroll
;       for (int r = 0; r < 16; ++r) { e0[r] = ex2(s0[r]); e1[r] = ex2(s1[r]); }
;       if (__any(im > TBITS)) {
;         const float d = im > TBITS ? __int_as_float(im) : 0.f;
;         const float a = ex2(-d);
; #pragma unroll
;         for (int r = 0; r < 16; ++r) { e0[r] = ex2(s0[r] - d); e1[r] = ex2(s1[r] - d); st.o[0][r] *= a; st.o[1][r] *= a; }
;         st.l *= a; st.m += d;
; #pragma unroll
;         for (int r = 0; r < 16; ++r) st.mr[r] = -st.m;
;       }
.LBB0_1675:
	s_nop 8
	v_max_i32_e32 v2, v97, v113
	v_max3_i32 v2, v96, v112, v2
	v_max_i32_e32 v3, v98, v114
	v_max_i32_e32 v4, v99, v115
	v_max3_i32 v2, v2, v3, v4
	v_max_i32_e32 v3, v100, v116
	v_max_i32_e32 v4, v101, v117
	v_max3_i32 v2, v2, v3, v4
	v_max_i32_e32 v3, v102, v118
	v_max_i32_e32 v4, v103, v119
	v_max3_i32 v2, v2, v3, v4
	v_max_i32_e32 v3, v104, v120
	v_max_i32_e32 v4, v105, v121
	v_max3_i32 v2, v2, v3, v4
	v_max_i32_e32 v3, v106, v122
	v_max_i32_e32 v4, v107, v123
	v_max3_i32 v2, v2, v3, v4
	v_max_i32_e32 v3, v108, v124
	v_max_i32_e32 v4, v109, v125
	v_max3_i32 v2, v2, v3, v4
	v_max_i32_e32 v3, v110, v126
	v_max_i32_e32 v4, v111, v127
	v_max3_i32 v2, v2, v3, v4
	v_mov_b32_e32 v3, v2
	s_nop 1
	v_permlane32_swap_b32_e32 v3, v2
	v_max_i32_e32 v2, v2, v3
	v_cmp_lt_i32_e32 vcc, s88, v2
	s_cbranch_vccz .LBB0_1677
	s_nop 0
	v_cndmask_b32_e32 v81, 0, v2, vcc
	v_sub_f32_e32 v2, v96, v81
	v_exp_f32_e32 v192, v2
	v_sub_f32_e32 v2, v112, v81
	v_exp_f32_e32 v112, v2
	v_sub_f32_e32 v2, v97, v81
	v_exp_f32_e32 v190, v2
	v_sub_f32_e32 v2, v113, v81
	v_exp_f32_e32 v113, v2
	v_sub_f32_e32 v2, v98, v81
	v_exp_f32_e32 v189, v2
	v_sub_f32_e32 v2, v114, v81
	v_exp_f32_e32 v114, v2
	v_sub_f32_e32 v2, v99, v81
	v_exp_f32_e32 v191, v2
	v_sub_f32_e32 v2, v115, v81
	v_sub_f32_e32 v82, v108, v81
	v_exp_f32_e32 v115, v2
	v_sub_f32_e32 v2, v100, v81
	v_exp_f32_e32 v96, v82
	v_sub_f32_e32 v82, v124, v81
	v_exp_f32_e32 v100, v2
	v_sub_f32_e32 v2, v116, v81
	v_exp_f32_e32 v98, v82
	v_sub_f32_e32 v82, v109, v81
	v_exp_f32_e32 v8, v2
	v_sub_f32_e32 v2, v101, v81
	v_exp_f32_e32 v97, v82
	v_sub_f32_e32 v82, v125, v81
	v_exp_f32_e32 v101, v2
	v_sub_f32_e32 v2, v117, v81
	v_exp_f32_e32 v99, v82
	v_sub_f32_e32 v82, v110, v81
	v_exp_f32_e32 v9, v2
	v_sub_f32_e32 v2, v102, v81
	v_sub_f32_e32 v4, v119, v81
	v_exp_f32_e32 v102, v82
	v_sub_f32_e32 v82, v126, v81
	v_exp_f32_e64 v80, -v81
	v_sub_f32_e32 v3, v118, v81
	v_exp_f32_e32 v7, v4
	v_sub_f32_e32 v4, v104, v81
	v_sub_f32_e32 v5, v105, v81
	v_sub_f32_e32 v12, v106, v81
	v_sub_f32_e32 v13, v107, v81
	v_exp_f32_e32 v104, v82
	v_sub_f32_e32 v82, v111, v81
	v_exp_f32_e32 v6, v3
	v_sub_f32_e32 v3, v103, v81
	v_exp_f32_e32 v10, v4
	v_sub_f32_e32 v4, v120, v81
	v_exp_f32_e32 v11, v5
	v_sub_f32_e32 v5, v121, v81
	v_exp_f32_e32 v14, v12
	v_sub_f32_e32 v12, v122, v81
	v_exp_f32_e32 v15, v13
	v_sub_f32_e32 v13, v123, v81
	v_exp_f32_e32 v103, v82
	v_sub_f32_e32 v82, v127, v81
	v_exp_f32_e32 v2, v2
	v_exp_f32_e32 v3, v3
	v_exp_f32_e32 v4, v4
	v_exp_f32_e32 v5, v5
	v_exp_f32_e32 v12, v12
	v_exp_f32_e32 v13, v13
	v_exp_f32_e32 v105, v82
	v_add_f32_e32 v188, v188, v81
	v_pk_mul_f32 v[78:79], v[78:79], v[80:81] op_sel_hi:[1,0]
	v_pk_mul_f32 v[76:77], v[76:77], v[80:81] op_sel_hi:[1,0]
	v_pk_mul_f32 v[74:75], v[74:75], v[80:81] op_sel_hi:[1,0]
	v_pk_mul_f32 v[72:73], v[72:73], v[80:81] op_sel_hi:[1,0]
	v_pk_mul_f32 v[70:71], v[70:71], v[80:81] op_sel_hi:[1,0]
	v_pk_mul_f32 v[68:69], v[68:69], v[80:81] op_sel_hi:[1,0]
	v_pk_mul_f32 v[66:67], v[66:67], v[80:81] op_sel_hi:[1,0]
	v_pk_mul_f32 v[64:65], v[64:65], v[80:81] op_sel_hi:[1,0]
	v_pk_mul_f32 v[62:63], v[62:63], v[80:81] op_sel_hi:[1,0]
	v_pk_mul_f32 v[60:61], v[60:61], v[80:81] op_sel_hi:[1,0]
	v_pk_mul_f32 v[58:59], v[58:59], v[80:81] op_sel_hi:[1,0]
	v_pk_mul_f32 v[56:57], v[56:57], v[80:81] op_sel_hi:[1,0]
	v_pk_mul_f32 v[54:55], v[54:55], v[80:81] op_sel_hi:[1,0]
	v_pk_mul_f32 v[52:53], v[52:53], v[80:81] op_sel_hi:[1,0]
	v_pk_mul_f32 v[50:51], v[50:51], v[80:81] op_sel_hi:[1,0]
	v_pk_mul_f32 v[48:49], v[48:49], v[80:81] op_sel_hi:[1,0]
	v_mul_f32_e32 v169, v169, v80
	v_xor_b32_e32 v80, 0x80000000, v188
	v_mov_b32_e32 v81, v80
	v_mov_b32_e32 v82, v80
	v_mov_b32_e32 v83, v80
	v_mov_b32_e32 v84, v80
	v_mov_b32_e32 v85, v80
	v_mov_b32_e32 v86, v80
	v_mov_b32_e32 v87, v80
	v_mov_b32_e32 v88, v80
	v_mov_b32_e32 v89, v80
	v_mov_b32_e32 v90, v80
	v_mov_b32_e32 v91, v80
	v_mov_b32_e32 v92, v80
	v_mov_b32_e32 v93, v80
	v_mov_b32_e32 v94, v80
	v_mov_b32_e32 v95, v80
	s_branch .LBB0_1678

; DI float ex2(float x) { return __builtin_amdgcn_exp2f(x); }
; template <int MODE>
; DI void flash_pass(AState& st, const bf16x8* qf, u64 tmask, u64 wmask,
;                    const bf16_t* kbase, size_t kld, const bf16_t* kpe, const bf16_t* vtbase, const float* fbias,
;                    int tq, u64 mysel, bf16_t* smem) {
;     ...
;       int im = (int)0x80000000;
; #pragma unroll
;       for (int r = 0; r < 16; ++r) im = max(im, max(__float_as_int(s0[r]), __float_as_int(s1[r])));
;       im = max(im, __shfl_xor(im, 32));
;       constexpr int TBITS = 0x41800000;
;       f32x16 e0, e1;
; #pragma unroll
;       for (int r = 0; r < 16; ++r) { e0[r] = ex2(s0[r]); e1[r] = ex2(s1[r]); }
;       if (__any(im > TBITS)) {
;         const float d = im > TBITS ? __int_as_float(im) : 0.f;
;         const float a = ex2(-d);
; #pragma unroll
;         for (int r = 0; r < 16; ++r) { e0[r] = ex2(s0[r] - d); e1[r] = ex2(s1[r] - d); st.o[0][r] *= a; st.o[1][r] *= a; }
;         st.l *= a; st.m += d;
; #pragma unroll
;         for (int r = 0; r < 16; ++r) st.mr[r] = -st.m;
;       }
.LBB0_1709:
	v_max_i32_e32 v90, v157, v161
	v_max3_i32 v90, v156, v160, v90
	v_max_i32_e32 v91, v158, v96
	v_max_i32_e32 v92, v159, v97
	v_max3_i32 v90, v90, v91, v92
	v_max_i32_e32 v91, v14, v10
	v_max_i32_e32 v92, v15, v11
	v_max3_i32 v90, v90, v91, v92
	v_max_i32_e32 v91, v84, v80
	v_max_i32_e32 v92, v85, v81
	v_max3_i32 v90, v90, v91, v92
	v_max_i32_e32 v91, v88, v86
	v_max_i32_e32 v92, v89, v87
	v_max3_i32 v90, v90, v91, v92
	v_max_i32_e32 v91, v82, v12
	v_max_i32_e32 v92, v83, v13
	v_max3_i32 v90, v90, v91, v92
	v_max_i32_e32 v91, v8, v6
	v_max_i32_e32 v92, v9, v7
	v_max3_i32 v90, v90, v91, v92
	v_max_i32_e32 v91, v2, v4
	v_max_i32_e32 v92, v3, v5
	v_max3_i32 v90, v90, v91, v92
	v_mov_b32_e32 v91, v90
	s_nop 1
	v_permlane32_swap_b32_e32 v91, v90
	v_max_i32_e32 v90, v90, v91
	v_cmp_lt_i32_e32 vcc, s88, v90
	s_cbranch_vccz .LBB0_1738
	s_nop 0
	v_cndmask_b32_e32 v65, 0, v90, vcc
	v_sub_f32_e32 v66, v156, v65
	v_exp_f32_e32 v101, v66
	v_sub_f32_e32 v66, v160, v65
	v_exp_f32_e32 v94, v66
	v_sub_f32_e32 v66, v157, v65
	v_exp_f32_e32 v99, v66
	v_sub_f32_e32 v66, v161, v65
	v_exp_f32_e32 v95, v66
	v_sub_f32_e32 v66, v158, v65
	v_exp_f32_e32 v98, v66
	v_sub_f32_e32 v66, v96, v65
	v_exp_f32_e32 v96, v66
	v_sub_f32_e32 v66, v159, v65
	v_sub_f32_e32 v14, v14, v65
	v_sub_f32_e32 v10, v10, v65
	v_exp_f32_e32 v100, v66
	v_sub_f32_e32 v66, v97, v65
	v_exp_f32_e32 v92, v14
	v_exp_f32_e32 v90, v10
	v_sub_f32_e32 v10, v15, v65
	v_sub_f32_e32 v14, v81, v65
	v_exp_f32_e64 v64, -v65
	v_exp_f32_e32 v97, v66
	v_exp_f32_e32 v93, v10
	v_sub_f32_e32 v10, v11, v65
	v_sub_f32_e32 v11, v80, v65
	v_exp_f32_e32 v81, v14
	v_sub_f32_e32 v14, v88, v65
	v_sub_f32_e32 v15, v89, v65
	v_sub_f32_e32 v66, v82, v65
	v_exp_f32_e32 v91, v10
	v_sub_f32_e32 v10, v84, v65
	v_exp_f32_e32 v80, v11
	v_sub_f32_e32 v11, v85, v65
	v_exp_f32_e32 v84, v14
	v_sub_f32_e32 v14, v86, v65
	v_exp_f32_e32 v85, v15
	v_sub_f32_e32 v15, v87, v65
	v_exp_f32_e32 v82, v66
	v_sub_f32_e32 v12, v12, v65
	v_sub_f32_e32 v66, v83, v65
	v_sub_f32_e32 v13, v13, v65
	v_sub_f32_e32 v8, v8, v65
	v_sub_f32_e32 v6, v6, v65
	v_sub_f32_e32 v9, v9, v65
	v_sub_f32_e32 v7, v7, v65
	v_sub_f32_e32 v2, v2, v65
	v_sub_f32_e32 v4, v4, v65
	v_sub_f32_e32 v3, v3, v65
	v_sub_f32_e32 v5, v5, v65
	v_exp_f32_e32 v10, v10
	v_exp_f32_e32 v11, v11
	v_exp_f32_e32 v14, v14
	v_exp_f32_e32 v15, v15
	v_exp_f32_e32 v12, v12
	v_exp_f32_e32 v83, v66
	v_exp_f32_e32 v13, v13
	v_exp_f32_e32 v8, v8
	v_exp_f32_e32 v6, v6
	v_exp_f32_e32 v9, v9
	v_exp_f32_e32 v7, v7
	v_exp_f32_e32 v2, v2
	v_exp_f32_e32 v4, v4
	v_exp_f32_e32 v3, v3
	v_exp_f32_e32 v5, v5
	v_add_f32_e32 v177, v177, v65
	v_pk_mul_f32 v[46:47], v[46:47], v[64:65] op_sel_hi:[1,0]
	v_pk_mul_f32 v[44:45], v[44:45], v[64:65] op_sel_hi:[1,0]
	v_pk_mul_f32 v[42:43], v[42:43], v[64:65] op_sel_hi:[1,0]
	v_pk_mul_f32 v[40:41], v[40:41], v[64:65] op_sel_hi:[1,0]
	v_pk_mul_f32 v[38:39], v[38:39], v[64:65] op_sel_hi:[1,0]
	v_pk_mul_f32 v[36:37], v[36:37], v[64:65] op_sel_hi:[1,0]
	v_pk_mul_f32 v[34:35], v[34:35], v[64:65] op_sel_hi:[1,0]
	v_pk_mul_f32 v[32:33], v[32:33], v[64:65] op_sel_hi:[1,0]
	v_pk_mul_f32 v[30:31], v[30:31], v[64:65] op_sel_hi:[1,0]
	v_pk_mul_f32 v[28:29], v[28:29], v[64:65] op_sel_hi:[1,0]
	v_pk_mul_f32 v[26:27], v[26:27], v[64:65] op_sel_hi:[1,0]
	v_pk_mul_f32 v[24:25], v[24:25], v[64:65] op_sel_hi:[1,0]
	v_pk_mul_f32 v[22:23], v[22:23], v[64:65] op_sel_hi:[1,0]
	v_pk_mul_f32 v[20:21], v[20:21], v[64:65] op_sel_hi:[1,0]
	v_pk_mul_f32 v[18:19], v[18:19], v[64:65] op_sel_hi:[1,0]
	v_pk_mul_f32 v[16:17], v[16:17], v[64:65] op_sel_hi:[1,0]
	v_mul_f32_e32 v173, v173, v64
	v_xor_b32_e32 v64, 0x80000000, v177
	v_mov_b32_e32 v65, v64
	v_mov_b32_e32 v66, v64
	v_mov_b32_e32 v67, v64
	v_mov_b32_e32 v68, v64
	v_mov_b32_e32 v69, v64
	v_mov_b32_e32 v70, v64
	v_mov_b32_e32 v71, v64
	v_mov_b32_e32 v72, v64
	v_mov_b32_e32 v73, v64
	v_mov_b32_e32 v74, v64
	v_mov_b32_e32 v75, v64
	v_mov_b32_e32 v76, v64
	v_mov_b32_e32 v77, v64
	v_mov_b32_e32 v78, v64
	v_mov_b32_e32 v79, v64

; template <int MODE>
; DI void flash_pass(AState& st, const bf16x8* qf, u64 tmask, u64 wmask,
;                    const bf16_t* kbase, size_t kld, const bf16_t* kpe, const bf16_t* vtbase, const float* fbias,
;                    int tq, u64 mysel, bf16_t* smem) {
;     ...
;   auto sstore = [&](int stg, auto setc) {
;     constexpr int S = decltype(setc)::value;
;     bf16_t* Ks = smem + stg * C::STAGE; bf16_t* Vs = Ks + C::K_ELEMS;
; #pragma unroll
;     for (int i = 0; i < C::KCH; ++i) {
;       const int c = tid + NTHR * i;
;       if (c < C::NKC) {
;         if constexpr (MODE == M_MLA) { const int key = c / 12, dc = c % 12; *(u32x4*)(Ks + key * C::KLD + dc * 8) = rk[S][i]; }
;         else { const int key = c >> 3, dc = c & 7; *(u32x4*)(Ks + key * C::KLD + dc * 8) = rk[S][i]; }
;       }
;     }
;     {
;       const int d = tid >> 3, kc = tid & 7, cgp = kc >> 1, a = kc & 1;
;       bf16_t* dst = Vs + d * 72 + cgp * 16 + 4 * a;
;       *(u32x2*)dst = (u32x2){rv[S][0], rv[S][1]}; *(u32x2*)(dst + 8) = (u32x2){rv[S][2], rv[S][3]};
;     }
;     if constexpr (MODE == M_FOX) { if (tid < 64) ((float*)(Vs + C::V_ELEMS))[tid] = rf[S]; }
;   };
.LBB0_1714:
	s_mul_i32 s6, s82, 0x2480
	s_xor_b32 s4, s82, 2
	s_mul_i32 s4, s4, 0x2480
	s_nop 0
	s_lshl_b32 s7, s4, 1
	s_and_saveexec_b64 s[4:5], s[0:1]
	s_cbranch_execz .LBB0_1716
	v_add3_u32 v0, s7, v167, v148
	s_waitcnt vmcnt(5)
	ds_write_b128 v0, v[132:135]
.LBB0_1716:
	s_or_b64 exec, exec, s[4:5]
	v_lshl_add_u32 v0, v166, 1, s7
	v_add3_u32 v0, v0, v168, v169
	v_add_u32_e32 v0, 0x2000, v0
	s_waitcnt vmcnt(4)
	ds_write2_b64 v0, v[128:129], v[130:131] offset0:128 offset1:130
	s_and_saveexec_b64 s[4:5], s[2:3]
	s_cbranch_execz .LBB0_1718
	v_lshl_add_u32 v0, v163, 2, s7
	s_waitcnt vmcnt(3)
	ds_write_b32 v0, v170 offset:18432

; DI float ex2(float x) { return __builtin_amdgcn_exp2f(x); }
; template <int MODE>
; DI void flash_pass(AState& st, const bf16x8* qf, u64 tmask, u64 wmask,
;                    const bf16_t* kbase, size_t kld, const bf16_t* kpe, const bf16_t* vtbase, const float* fbias,
;                    int tq, u64 mysel, bf16_t* smem) {
;     ...
;       int im = (int)0x80000000;
; #pragma unroll
;       for (int r = 0; r < 16; ++r) im = max(im, max(__float_as_int(s0[r]), __float_as_int(s1[r])));
;       im = max(im, __shfl_xor(im, 32));
;       constexpr int TBITS = 0x41800000;
;       f32x16 e0, e1;
; #pragma unroll
;       for (int r = 0; r < 16; ++r) { e0[r] = ex2(s0[r]); e1[r] = ex2(s1[r]); }
;       if (__any(im > TBITS)) {
;         const float d = im > TBITS ? __int_as_float(im) : 0.f;
;         const float a = ex2(-d);
; #pragma unroll
;         for (int r = 0; r < 16; ++r) { e0[r] = ex2(s0[r] - d); e1[r] = ex2(s1[r] - d); st.o[0][r] *= a; st.o[1][r] *= a; }
;         st.l *= a; st.m += d;
; #pragma unroll
;         for (int r = 0; r < 16; ++r) st.mr[r] = -st.m;
;       }
.LBB0_1723:
	v_max_i32_e32 v90, v157, v161
	v_max3_i32 v90, v156, v160, v90
	v_max_i32_e32 v91, v158, v96
	v_max_i32_e32 v92, v159, v97
	v_max3_i32 v90, v90, v91, v92
	v_max_i32_e32 v91, v14, v10
	v_max_i32_e32 v92, v15, v11
	v_max3_i32 v90, v90, v91, v92
	v_max_i32_e32 v91, v84, v80
	v_max_i32_e32 v92, v85, v81
	v_max3_i32 v90, v90, v91, v92
	v_max_i32_e32 v91, v88, v86
	v_max_i32_e32 v92, v89, v87
	v_max3_i32 v90, v90, v91, v92
	v_max_i32_e32 v91, v82, v12
	v_max_i32_e32 v92, v83, v13
	v_max3_i32 v90, v90, v91, v92
	v_max_i32_e32 v91, v8, v6
	v_max_i32_e32 v92, v9, v7
	v_max3_i32 v90, v90, v91, v92
	v_max_i32_e32 v91, v2, v4
	v_max_i32_e32 v92, v3, v5
	v_max3_i32 v90, v90, v91, v92
	v_mov_b32_e32 v91, v90
	s_nop 1
	v_permlane32_swap_b32_e32 v91, v90
	v_max_i32_e32 v90, v90, v91
	v_cmp_lt_i32_e32 vcc, s88, v90
	s_cbranch_vccz .LBB0_1725
	s_nop 0
	v_cndmask_b32_e32 v65, 0, v90, vcc
	v_sub_f32_e32 v66, v156, v65
	v_exp_f32_e32 v101, v66
	v_sub_f32_e32 v66, v160, v65
	v_exp_f32_e32 v94, v66
	v_sub_f32_e32 v66, v157, v65
	v_exp_f32_e32 v99, v66
	v_sub_f32_e32 v66, v161, v65
	v_exp_f32_e32 v95, v66
	v_sub_f32_e32 v66, v158, v65
	v_exp_f32_e32 v98, v66
	v_sub_f32_e32 v66, v96, v65
	v_exp_f32_e32 v96, v66
	v_sub_f32_e32 v66, v159, v65
	v_sub_f32_e32 v14, v14, v65
	v_sub_f32_e32 v10, v10, v65
	v_exp_f32_e32 v100, v66
	v_sub_f32_e32 v66, v97, v65
	v_exp_f32_e32 v92, v14
	v_exp_f32_e32 v90, v10
	v_sub_f32_e32 v10, v15, v65
	v_sub_f32_e32 v14, v81, v65
	v_exp_f32_e64 v64, -v65
	v_exp_f32_e32 v97, v66
	v_exp_f32_e32 v93, v10
	v_sub_f32_e32 v10, v11, v65
	v_sub_f32_e32 v11, v80, v65
	v_exp_f32_e32 v81, v14
	v_sub_f32_e32 v14, v88, v65
	v_sub_f32_e32 v15, v89, v65
	v_sub_f32_e32 v66, v82, v65
	v_exp_f32_e32 v91, v10
	v_sub_f32_e32 v10, v84, v65
	v_exp_f32_e32 v80, v11
	v_sub_f32_e32 v11, v85, v65
	v_exp_f32_e32 v84, v14
	v_sub_f32_e32 v14, v86, v65
	v_exp_f32_e32 v85, v15
	v_sub_f32_e32 v15, v87, v65
	v_exp_f32_e32 v82, v66
	v_sub_f32_e32 v12, v12, v65
	v_sub_f32_e32 v66, v83, v65
	v_sub_f32_e32 v13, v13, v65
	v_sub_f32_e32 v8, v8, v65
	v_sub_f32_e32 v6, v6, v65
	v_sub_f32_e32 v9, v9, v65
	v_sub_f32_e32 v7, v7, v65
	v_sub_f32_e32 v2, v2, v65
	v_sub_f32_e32 v4, v4, v65
	v_sub_f32_e32 v3, v3, v65
	v_sub_f32_e32 v5, v5, v65
	v_exp_f32_e32 v10, v10
	v_exp_f32_e32 v11, v11
	v_exp_f32_e32 v14, v14
	v_exp_f32_e32 v15, v15
	v_exp_f32_e32 v12, v12
	v_exp_f32_e32 v83, v66
	v_exp_f32_e32 v13, v13
	v_exp_f32_e32 v8, v8
	v_exp_f32_e32 v6, v6
	v_exp_f32_e32 v9, v9
	v_exp_f32_e32 v7, v7
	v_exp_f32_e32 v2, v2
	v_exp_f32_e32 v4, v4
	v_exp_f32_e32 v3, v3
	v_exp_f32_e32 v5, v5
	v_add_f32_e32 v177, v177, v65
	v_pk_mul_f32 v[46:47], v[46:47], v[64:65] op_sel_hi:[1,0]
	v_pk_mul_f32 v[44:45], v[44:45], v[64:65] op_sel_hi:[1,0]
	v_pk_mul_f32 v[42:43], v[42:43], v[64:65] op_sel_hi:[1,0]
	v_pk_mul_f32 v[40:41], v[40:41], v[64:65] op_sel_hi:[1,0]
	v_pk_mul_f32 v[38:39], v[38:39], v[64:65] op_sel_hi:[1,0]
	v_pk_mul_f32 v[36:37], v[36:37], v[64:65] op_sel_hi:[1,0]
	v_pk_mul_f32 v[34:35], v[34:35], v[64:65] op_sel_hi:[1,0]
	v_pk_mul_f32 v[32:33], v[32:33], v[64:65] op_sel_hi:[1,0]
	v_pk_mul_f32 v[30:31], v[30:31], v[64:65] op_sel_hi:[1,0]
	v_pk_mul_f32 v[28:29], v[28:29], v[64:65] op_sel_hi:[1,0]
	v_pk_mul_f32 v[26:27], v[26:27], v[64:65] op_sel_hi:[1,0]
	v_pk_mul_f32 v[24:25], v[24:25], v[64:65] op_sel_hi:[1,0]
	v_pk_mul_f32 v[22:23], v[22:23], v[64:65] op_sel_hi:[1,0]
	v_pk_mul_f32 v[20:21], v[20:21], v[64:65] op_sel_hi:[1,0]
	v_pk_mul_f32 v[18:19], v[18:19], v[64:65] op_sel_hi:[1,0]
	v_pk_mul_f32 v[16:17], v[16:17], v[64:65] op_sel_hi:[1,0]
	v_mul_f32_e32 v173, v173, v64
	v_xor_b32_e32 v64, 0x80000000, v177
	v_mov_b32_e32 v65, v64
	v_mov_b32_e32 v66, v64
	v_mov_b32_e32 v67, v64
	v_mov_b32_e32 v68, v64
	v_mov_b32_e32 v69, v64
	v_mov_b32_e32 v70, v64
	v_mov_b32_e32 v71, v64
	v_mov_b32_e32 v72, v64
	v_mov_b32_e32 v73, v64
	v_mov_b32_e32 v74, v64
	v_mov_b32_e32 v75, v64
	v_mov_b32_e32 v76, v64
	v_mov_b32_e32 v77, v64
	v_mov_b32_e32 v78, v64
	v_mov_b32_e32 v79, v64
	s_branch .LBB0_1726

; template <int MODE>
; DI void flash_pass(AState& st, const bf16x8* qf, u64 tmask, u64 wmask,
;                    const bf16_t* kbase, size_t kld, const bf16_t* kpe, const bf16_t* vtbase, const float* fbias,
;                    int tq, u64 mysel, bf16_t* smem) {
;     ...
;       const int c0 = tid + NTHR * i, c = c0 < C::NKC ? c0 : C::NKC - 1;
;       if constexpr (MODE == M_MLA) {
;         const int key = c / 12, dc = c % 12;
;         const bf16_t* src = dc < 8 ? kbase + (size_t)(k0 + key) * kld + dc * 8 : kpe + (size_t)(k0 + key) * 32 + (dc - 8) * 8;
;         rk[S][i] = *(const u32x4*)src;
;       } else { const int key = c >> 3, dc = c & 7; rk[S][i] = *(const u32x4*)(kbase + (size_t)(k0 + key) * kld + dc * 8); }
;     }
;     { const int d = tid >> 3, kc = tid & 7; rv[S] = *(const u32x4*)(vtbase + (size_t)d * S_ + k0 + kc * 8); }
;     ...
;       const bf16_t* Ks = smem + stg * C::STAGE; const bf16_t* Vs = Ks + C::K_ELEMS;
;       f32x16 s0 = st.mr, s1 = st.mr;
;       const bf16_t* kr = Ks + l31 * C::KLD + half * 8;
; #pragma unroll
;       for (int ks = 0; ks < C::DQK / 16; ++ks) {
;         s0 = mfma32(*(const bf16x8*)(kr + ks * 16), qf[ks], s0);
;         s1 = mfma32(*(const bf16x8*)(kr + 32 * C::KLD + ks * 16), qf[ks], s1);
;       }
;       const int k0 = j * 64;
;       if constexpr (MODE == M_FOX) {
;         const float* fb = (const float*)(Vs + C::V_ELEMS) + 4 * half;
; #pragma unroll
;         for (int g4 = 0; g4 < 4; ++g4) {
;           const f32x4 b0 = *(const f32x4*)(fb + 8 * g4), b1 = *(const f32x4*)(fb + 32 + 8 * g4);
; #pragma unroll
;           for (int r = 0; r < 4; ++r) { s0[4 * g4 + r] += b0[r]; s1[4 * g4 + r] += b1[r]; }
;         }
;       }
;       bool need = k0 + 63 > tmin;
;       if constexpr (MODE == M_WIN) need = need || (k0 <= tmax - 512);
;       if constexpr (MODE == M_SLC) {
;         if (!need) {
;           const bool rsel = ((mysel >> j) & 1) != 0;
;           if (!__all(rsel)) {
; #pragma unroll
;             for (int r = 0; r < 16; ++r) { s0[r] = rsel ? s0[r] : -INFINITY; s1[r] = rsel ? s1[r] : -INFINITY; }
;           }
;         }
;       }
;       if (need) {
;         const bool rowok = MODE == M_SLC ? ((mysel >> j) & 1) != 0 : true;
; #pragma unroll
;         for (int r = 0; r < 16; ++r) {
;           const int key = k0 + (r & 3) + 8 * (r >> 2) + 4 * half;
.LBB0_1788:
	s_or_b64 exec, exec, s[8:9]
	s_cmp_eq_u64 s[10:11], 0
	s_cselect_b64 s[8:9], -1, 0
	s_ff1_i32_b64 s19, s[10:11]
	v_lshl_add_u32 v2, v162, 1, s12
	v_lshlrev_b32_e32 v176, 1, v164
	s_and_b64 s[12:13], s[8:9], exec
	v_add3_u32 v2, v2, v163, v176
	s_cselect_b32 s12, s25, s19
	v_add_u32_e32 v2, 0x3000, v2
	s_lshl_b32 s68, s12, 6
	s_waitcnt vmcnt(3)
	ds_write2_b64 v2, v[124:125], v[126:127] offset0:128 offset1:130
	v_add_u32_e32 v2, s68, v147
	v_ashrrev_i32_e32 v3, 31, v2
	v_lshlrev_b64 v[4:5], 10, v[2:3]
	v_lshlrev_b64 v[2:3], 6, v[2:3]
	v_lshl_add_u64 v[2:3], v[152:153], 0, v[2:3]
	v_lshl_add_u64 v[4:5], v[154:155], 0, v[4:5]
	v_lshl_add_u64 v[2:3], v[2:3], 0, s[70:71]
	v_cndmask_b32_e64 v3, v3, v5, s[0:1]
	v_cndmask_b32_e64 v2, v2, v4, s[0:1]
	global_load_dwordx4 v[120:123], v[2:3], off
	v_add_u32_e32 v2, s68, v161
	v_ashrrev_i32_e32 v3, 31, v2
	v_lshlrev_b64 v[4:5], 10, v[2:3]
	v_lshlrev_b64 v[2:3], 6, v[2:3]
	v_lshl_add_u64 v[2:3], v[156:157], 0, v[2:3]
	v_lshl_add_u64 v[4:5], v[158:159], 0, v[4:5]
	v_lshl_add_u64 v[2:3], v[2:3], 0, s[70:71]
	v_cndmask_b32_e64 v3, v3, v5, s[2:3]
	v_cndmask_b32_e64 v2, v2, v4, s[2:3]
	global_load_dwordx4 v[128:131], v[2:3], off
	v_lshl_add_u64 v[2:3], s[68:69], 1, v[150:151]
	global_load_dwordx4 v[124:127], v[2:3], off
	v_lshrrev_b64 v[2:3], s25, v[148:149]
	v_and_b32_e32 v2, 1, v2
	v_cmp_eq_u32_e32 vcc, 1, v2
	s_and_saveexec_b64 s[12:13], vcc
	s_cbranch_execz .LBB0_1795
	v_lshl_add_u32 v177, s14, 1, v172
	v_lshl_add_u32 v14, v169, 1, v177
	ds_read_b128 v[2:5], v14
	ds_read_b128 v[6:9], v14 offset:32
	s_lshl_b32 s14, s25, 6
	s_or_b32 s15, s14, 63
	s_cmp_le_i32 s15, s24
	s_waitcnt lgkmcnt(1)
	v_mfma_f32_32x32x16_bf16 v[64:79], v[2:5], v[96:99], v[48:63]
	ds_read_b128 v[2:5], v14 offset:6656
	ds_read_b128 v[10:13], v14 offset:6688
	s_waitcnt lgkmcnt(1)
	v_mfma_f32_32x32x16_bf16 v[80:95], v[2:5], v[96:99], v[48:63]
	v_mfma_f32_32x32x16_bf16 v[64:79], v[6:9], v[100:103], v[64:79]
	ds_read_b128 v[2:5], v14 offset:64
	ds_read_b128 v[6:9], v14 offset:96
	s_waitcnt lgkmcnt(2)
	v_mfma_f32_32x32x16_bf16 v[80:95], v[10:13], v[100:103], v[80:95]
	s_waitcnt lgkmcnt(1)
	v_mfma_f32_32x32x16_bf16 v[64:79], v[2:5], v[104:107], v[64:79]
	ds_read_b128 v[2:5], v14 offset:6720
	ds_read_b128 v[10:13], v14 offset:6752
	s_waitcnt lgkmcnt(1)
	v_mfma_f32_32x32x16_bf16 v[80:95], v[2:5], v[104:107], v[80:95]
	v_mfma_f32_32x32x16_bf16 v[64:79], v[6:9], v[108:111], v[64:79]
	ds_read_b128 v[2:5], v14 offset:128
	ds_read_b128 v[6:9], v14 offset:160
	s_waitcnt lgkmcnt(2)
	v_mfma_f32_32x32x16_bf16 v[80:95], v[10:13], v[108:111], v[80:95]
	s_waitcnt lgkmcnt(1)
	v_mfma_f32_32x32x16_bf16 v[64:79], v[2:5], v[112:115], v[64:79]
	ds_read_b128 v[2:5], v14 offset:6784
	ds_read_b128 v[10:13], v14 offset:6816
	s_waitcnt lgkmcnt(1)
	v_mfma_f32_32x32x16_bf16 v[80:95], v[2:5], v[112:115], v[80:95]
	v_mfma_f32_32x32x16_bf16 v[64:79], v[6:9], v[116:119], v[64:79]
	s_waitcnt lgkmcnt(0)
	v_mfma_f32_32x32x16_bf16 v[80:95], v[10:13], v[116:119], v[80:95]
	s_cbranch_scc1 .LBB0_1791
	v_or_b32_e32 v2, s14, v170
	v_or_b32_e32 v3, 32, v2
	v_cmp_le_i32_e32 vcc, v2, v146
	v_or_b32_e32 v4, 34, v2
	s_nop 4
	v_cndmask_b32_e32 v64, v175, v64, vcc
	v_cmp_le_i32_e32 vcc, v3, v146
	v_or_b32_e32 v3, 33, v2
	s_nop 0
	v_cndmask_b32_e32 v80, v175, v80, vcc
	v_cmp_lt_i32_e32 vcc, v2, v146
	s_nop 1
	v_cndmask_b32_e32 v65, v175, v65, vcc
	v_cmp_le_i32_e32 vcc, v3, v146
	v_or_b32_e32 v3, 2, v2
	s_nop 0
	v_cndmask_b32_e32 v81, v175, v81, vcc
	v_cmp_le_i32_e32 vcc, v3, v146
	v_or_b32_e32 v3, 3, v2
	s_nop 0
	v_cndmask_b32_e32 v66, v175, v66, vcc
	v_cmp_le_i32_e32 vcc, v4, v146
	v_or_b32_e32 v4, 35, v2
	s_nop 0
	v_cndmask_b32_e32 v82, v175, v82, vcc
	v_cmp_le_i32_e32 vcc, v3, v146
	v_or_b32_e32 v3, 8, v2
	s_nop 0
	v_cndmask_b32_e32 v67, v175, v67, vcc
	v_cmp_le_i32_e32 vcc, v4, v146
	v_or_b32_e32 v4, 40, v2
	s_nop 0
	v_cndmask_b32_e32 v83, v175, v83, vcc
	v_cmp_le_i32_e32 vcc, v3, v146
	v_or_b32_e32 v3, 9, v2
	s_nop 0
	v_cndmask_b32_e32 v68, v175, v68, vcc
	v_cmp_le_i32_e32 vcc, v4, v146
	v_or_b32_e32 v4, 41, v2
	s_nop 0
	v_cndmask_b32_e32 v84, v175, v84, vcc
	v_cmp_le_i32_e32 vcc, v3, v146
	v_or_b32_e32 v3, 10, v2
	s_nop 0
	v_cndmask_b32_e32 v69, v175, v69, vcc
	v_cmp_le_i32_e32 vcc, v4, v146
	v_or_b32_e32 v4, 42, v2
	s_nop 0
	v_cndmask_b32_e32 v85, v175, v85, vcc
	v_cmp_le_i32_e32 vcc, v3, v146
	v_or_b32_e32 v3, 11, v2
	s_nop 0
	v_cndmask_b32_e32 v70, v175, v70, vcc
	v_cmp_le_i32_e32 vcc, v4, v146
	v_or_b32_e32 v4, 43, v2
	s_nop 0
	v_cndmask_b32_e32 v86, v175, v86, vcc
	v_cmp_le_i32_e32 vcc, v3, v146
	v_or_b32_e32 v3, 16, v2
	s_nop 0
	v_cndmask_b32_e32 v71, v175, v71, vcc
	v_cmp_le_i32_e32 vcc, v4, v146
	v_or_b32_e32 v4, 48, v2
	s_nop 0
	v_cndmask_b32_e32 v87, v175, v87, vcc
	v_cmp_le_i32_e32 vcc, v3, v146
	v_or_b32_e32 v3, 17, v2
	s_nop 0
	v_cndmask_b32_e32 v72, v175, v72, vcc
	v_cmp_le_i32_e32 vcc, v4, v146
	v_or_b32_e32 v4, 49, v2
	s_nop 0
	v_cndmask_b32_e32 v88, v175, v88, vcc
	v_cmp_le_i32_e32 vcc, v3, v146
	v_or_b32_e32 v3, 18, v2
	s_nop 0
	v_cndmask_b32_e32 v73, v175, v73, vcc
	v_cmp_le_i32_e32 vcc, v4, v146
	v_or_b32_e32 v4, 50, v2
	s_nop 0
	v_cndmask_b32_e32 v89, v175, v89, vcc
	v_cmp_le_i32_e32 vcc, v3, v146
	v_or_b32_e32 v3, 19, v2
	s_nop 0
	v_cndmask_b32_e32 v74, v175, v74, vcc
	v_cmp_le_i32_e32 vcc, v4, v146
	v_or_b32_e32 v4, 51, v2
	s_nop 0
	v_cndmask_b32_e32 v90, v175, v90, vcc
	v_cmp_le_i32_e32 vcc, v3, v146
	v_or_b32_e32 v3, 24, v2
	s_nop 0
	v_cndmask_b32_e32 v75, v175, v75, vcc
	v_cmp_le_i32_e32 vcc, v4, v146
	v_or_b32_e32 v4, 56, v2
	s_nop 0
	v_cndmask_b32_e32 v91, v175, v91, vcc
	v_cmp_le_i32_e32 vcc, v3, v146
	v_or_b32_e32 v3, 25, v2
	s_nop 0
	v_cndmask_b32_e32 v76, v175, v76, vcc
	v_cmp_le_i32_e32 vcc, v4, v146
	v_or_b32_e32 v4, 57, v2
	s_nop 0
	v_cndmask_b32_e32 v92, v175, v92, vcc
	v_cmp_le_i32_e32 vcc, v3, v146
	v_or_b32_e32 v3, 26, v2
	s_nop 0
	v_cndmask_b32_e32 v77, v175, v77, vcc
	v_cmp_le_i32_e32 vcc, v4, v146
	v_or_b32_e32 v4, 58, v2
	s_nop 0
	v_cndmask_b32_e32 v93, v175, v93, vcc
	v_cmp_le_i32_e32 vcc, v3, v146
	v_or_b32_e32 v3, 27, v2
	v_or_b32_e32 v2, 59, v2
	v_cndmask_b32_e32 v78, v175, v78, vcc
	v_cmp_le_i32_e32 vcc, v4, v146
	s_nop 1
	v_cndmask_b32_e32 v94, v175, v94, vcc
	v_cmp_le_i32_e32 vcc, v3, v146
	s_nop 1
	v_cndmask_b32_e32 v79, v175, v79, vcc
	v_cmp_le_i32_e32 vcc, v2, v146
	s_nop 1
	v_cndmask_b32_e32 v95, v175, v95, vcc
; DI float ex2(float x) { return __builtin_amdgcn_exp2f(x); }
; template <int MODE>
; DI void flash_pass(AState& st, const bf16x8* qf, u64 tmask, u64 wmask,
;                    const bf16_t* kbase, size_t kld, const bf16_t* kpe, const bf16_t* vtbase, const float* fbias,
;                    int tq, u64 mysel, bf16_t* smem) {
;     ...
;       int im = (int)0x80000000;
; #pragma unroll
;       for (int r = 0; r < 16; ++r) im = max(im, max(__float_as_int(s0[r]), __float_as_int(s1[r])));
;       im = max(im, __shfl_xor(im, 32));
;       constexpr int TBITS = 0x41800000;
;       f32x16 e0, e1;
; #pragma unroll
;       for (int r = 0; r < 16; ++r) { e0[r] = ex2(s0[r]); e1[r] = ex2(s1[r]); }
;       if (__any(im > TBITS)) {
;         const float d = im > TBITS ? __int_as_float(im) : 0.f;
;         const float a = ex2(-d);
; #pragma unroll
;         for (int r = 0; r < 16; ++r) { e0[r] = ex2(s0[r] - d); e1[r] = ex2(s1[r] - d); st.o[0][r] *= a; st.o[1][r] *= a; }
;         st.l *= a; st.m += d;
; #pragma unroll
;         for (int r = 0; r < 16; ++r) st.mr[r] = -st.m;
;       }
.LBB0_1791:
	s_nop 10
	v_max_i32_e32 v2, v65, v81
	v_max3_i32 v2, v64, v80, v2
	v_max_i32_e32 v3, v66, v82
	v_max_i32_e32 v4, v67, v83
	v_max3_i32 v2, v2, v3, v4
	v_max_i32_e32 v3, v68, v84
	v_max_i32_e32 v4, v69, v85
	v_max3_i32 v2, v2, v3, v4
	v_max_i32_e32 v3, v70, v86
	v_max_i32_e32 v4, v71, v87
	v_max3_i32 v2, v2, v3, v4
	v_max_i32_e32 v3, v72, v88
	v_max_i32_e32 v4, v73, v89
	v_max3_i32 v2, v2, v3, v4
	v_max_i32_e32 v3, v74, v90
	v_max_i32_e32 v4, v75, v91
	v_max3_i32 v2, v2, v3, v4
	v_max_i32_e32 v3, v76, v92
	v_max_i32_e32 v4, v77, v93
	v_max3_i32 v2, v2, v3, v4
	v_max_i32_e32 v3, v78, v94
	v_max_i32_e32 v4, v79, v95
	v_max3_i32 v2, v2, v3, v4
	v_mov_b32_e32 v3, v2
	s_nop 1
	v_permlane32_swap_b32_e32 v3, v2
	v_max_i32_e32 v2, v2, v3
	v_cmp_lt_i32_e32 vcc, s88, v2
	s_cbranch_vccz .LBB0_1793
	s_nop 0
	v_cndmask_b32_e32 v49, 0, v2, vcc
	v_sub_f32_e32 v2, v64, v49
	v_exp_f32_e32 v181, v2
	v_sub_f32_e32 v2, v80, v49
	v_exp_f32_e32 v80, v2
	v_sub_f32_e32 v2, v65, v49
	v_exp_f32_e32 v179, v2
	v_sub_f32_e32 v2, v81, v49
	v_exp_f32_e32 v81, v2
	v_sub_f32_e32 v2, v66, v49
	v_exp_f32_e32 v178, v2
	v_sub_f32_e32 v2, v82, v49
	v_exp_f32_e32 v82, v2
	v_sub_f32_e32 v2, v67, v49
	v_exp_f32_e32 v180, v2
	v_sub_f32_e32 v2, v83, v49
	v_sub_f32_e32 v50, v76, v49
	v_exp_f32_e32 v83, v2
	v_sub_f32_e32 v2, v68, v49
	v_exp_f32_e32 v64, v50
	v_sub_f32_e32 v50, v92, v49
	v_exp_f32_e32 v68, v2
	v_sub_f32_e32 v2, v84, v49
	v_exp_f32_e32 v66, v50
	v_sub_f32_e32 v50, v77, v49
	v_exp_f32_e32 v8, v2
	v_sub_f32_e32 v2, v69, v49
	v_exp_f32_e32 v65, v50
	v_sub_f32_e32 v50, v93, v49
	v_exp_f32_e32 v69, v2
	v_sub_f32_e32 v2, v85, v49
	v_exp_f32_e32 v67, v50
	v_sub_f32_e32 v50, v78, v49
	v_exp_f32_e32 v9, v2
	v_sub_f32_e32 v2, v70, v49
	v_sub_f32_e32 v4, v87, v49
	v_exp_f32_e32 v70, v50
	v_sub_f32_e32 v50, v94, v49
	v_exp_f32_e64 v48, -v49
	v_sub_f32_e32 v3, v86, v49
	v_exp_f32_e32 v7, v4
	v_sub_f32_e32 v4, v72, v49
	v_sub_f32_e32 v5, v73, v49
	v_sub_f32_e32 v12, v74, v49
	v_sub_f32_e32 v13, v75, v49
	v_exp_f32_e32 v72, v50
	v_sub_f32_e32 v50, v79, v49
	v_exp_f32_e32 v6, v3
	v_sub_f32_e32 v3, v71, v49
	v_exp_f32_e32 v10, v4
	v_sub_f32_e32 v4, v88, v49
	v_exp_f32_e32 v11, v5
	v_sub_f32_e32 v5, v89, v49
	v_exp_f32_e32 v14, v12
	v_sub_f32_e32 v12, v90, v49
	v_exp_f32_e32 v15, v13
	v_sub_f32_e32 v13, v91, v49
	v_exp_f32_e32 v71, v50
	v_sub_f32_e32 v50, v95, v49
	v_exp_f32_e32 v2, v2
	v_exp_f32_e32 v3, v3
	v_exp_f32_e32 v4, v4
	v_exp_f32_e32 v5, v5
	v_exp_f32_e32 v12, v12
	v_exp_f32_e32 v13, v13
	v_exp_f32_e32 v73, v50
	v_add_f32_e32 v0, v0, v49
	v_pk_mul_f32 v[46:47], v[46:47], v[48:49] op_sel_hi:[1,0]
	v_pk_mul_f32 v[44:45], v[44:45], v[48:49] op_sel_hi:[1,0]
	v_pk_mul_f32 v[42:43], v[42:43], v[48:49] op_sel_hi:[1,0]
	v_pk_mul_f32 v[40:41], v[40:41], v[48:49] op_sel_hi:[1,0]
	v_pk_mul_f32 v[38:39], v[38:39], v[48:49] op_sel_hi:[1,0]
	v_pk_mul_f32 v[36:37], v[36:37], v[48:49] op_sel_hi:[1,0]
	v_pk_mul_f32 v[34:35], v[34:35], v[48:49] op_sel_hi:[1,0]
	v_pk_mul_f32 v[32:33], v[32:33], v[48:49] op_sel_hi:[1,0]
	v_pk_mul_f32 v[30:31], v[30:31], v[48:49] op_sel_hi:[1,0]
	v_pk_mul_f32 v[28:29], v[28:29], v[48:49] op_sel_hi:[1,0]
	v_pk_mul_f32 v[26:27], v[26:27], v[48:49] op_sel_hi:[1,0]
	v_pk_mul_f32 v[24:25], v[24:25], v[48:49] op_sel_hi:[1,0]
	v_pk_mul_f32 v[22:23], v[22:23], v[48:49] op_sel_hi:[1,0]
	v_pk_mul_f32 v[20:21], v[20:21], v[48:49] op_sel_hi:[1,0]
	v_pk_mul_f32 v[18:19], v[18:19], v[48:49] op_sel_hi:[1,0]
	v_pk_mul_f32 v[16:17], v[16:17], v[48:49] op_sel_hi:[1,0]
	v_mul_f32_e32 v171, v171, v48
	v_xor_b32_e32 v48, 0x80000000, v0
	v_mov_b32_e32 v49, v48
	v_mov_b32_e32 v50, v48
	v_mov_b32_e32 v51, v48
	v_mov_b32_e32 v52, v48
	v_mov_b32_e32 v53, v48
	v_mov_b32_e32 v54, v48
	v_mov_b32_e32 v55, v48
	v_mov_b32_e32 v56, v48
	v_mov_b32_e32 v57, v48
	v_mov_b32_e32 v58, v48
	v_mov_b32_e32 v59, v48
	v_mov_b32_e32 v60, v48
	v_mov_b32_e32 v61, v48
	v_mov_b32_e32 v62, v48
	v_mov_b32_e32 v63, v48
	s_branch .LBB0_1794

; DI float ex2(float x) { return __builtin_amdgcn_exp2f(x); }
; template <int MODE>
; DI void flash_pass(AState& st, const bf16x8* qf, u64 tmask, u64 wmask,
;                    const bf16_t* kbase, size_t kld, const bf16_t* kpe, const bf16_t* vtbase, const float* fbias,
;                    int tq, u64 mysel, bf16_t* smem) {
;     ...
;       int im = (int)0x80000000;
; #pragma unroll
;       for (int r = 0; r < 16; ++r) im = max(im, max(__float_as_int(s0[r]), __float_as_int(s1[r])));
;       im = max(im, __shfl_xor(im, 32));
;       constexpr int TBITS = 0x41800000;
;       f32x16 e0, e1;
; #pragma unroll
;       for (int r = 0; r < 16; ++r) { e0[r] = ex2(s0[r]); e1[r] = ex2(s1[r]); }
;       if (__any(im > TBITS)) {
;         const float d = im > TBITS ? __int_as_float(im) : 0.f;
;         const float a = ex2(-d);
; #pragma unroll
;         for (int r = 0; r < 16; ++r) { e0[r] = ex2(s0[r] - d); e1[r] = ex2(s1[r] - d); st.o[0][r] *= a; st.o[1][r] *= a; }
;         st.l *= a; st.m += d;
; #pragma unroll
;         for (int r = 0; r < 16; ++r) st.mr[r] = -st.m;
;       }
.LBB0_1803:
	s_nop 10
	v_max_i32_e32 v2, v65, v81
	v_max3_i32 v2, v64, v80, v2
	v_max_i32_e32 v3, v66, v82
	v_max_i32_e32 v4, v67, v83
	v_max3_i32 v2, v2, v3, v4
	v_max_i32_e32 v3, v68, v84
	v_max_i32_e32 v4, v69, v85
	v_max3_i32 v2, v2, v3, v4
	v_max_i32_e32 v3, v70, v86
	v_max_i32_e32 v4, v71, v87
	v_max3_i32 v2, v2, v3, v4
	v_max_i32_e32 v3, v72, v88
	v_max_i32_e32 v4, v73, v89
	v_max3_i32 v2, v2, v3, v4
	v_max_i32_e32 v3, v74, v90
	v_max_i32_e32 v4, v75, v91
	v_max3_i32 v2, v2, v3, v4
	v_max_i32_e32 v3, v76, v92
	v_max_i32_e32 v4, v77, v93
	v_max3_i32 v2, v2, v3, v4
	v_max_i32_e32 v3, v78, v94
	v_max_i32_e32 v4, v79, v95
	v_max3_i32 v2, v2, v3, v4
	v_mov_b32_e32 v3, v2
	s_nop 1
	v_permlane32_swap_b32_e32 v3, v2
	v_max_i32_e32 v2, v2, v3
	v_cmp_lt_i32_e32 vcc, s88, v2
	s_cbranch_vccz .LBB0_1805
	s_nop 0
	v_cndmask_b32_e32 v49, 0, v2, vcc
	v_sub_f32_e32 v2, v64, v49
	v_exp_f32_e32 v180, v2
	v_sub_f32_e32 v2, v80, v49
	v_exp_f32_e32 v80, v2
	v_sub_f32_e32 v2, v65, v49
	v_exp_f32_e32 v178, v2
	v_sub_f32_e32 v2, v81, v49
	v_exp_f32_e32 v81, v2
	v_sub_f32_e32 v2, v66, v49
	v_exp_f32_e32 v177, v2
	v_sub_f32_e32 v2, v82, v49
	v_exp_f32_e32 v82, v2
	v_sub_f32_e32 v2, v67, v49
	v_exp_f32_e32 v179, v2
	v_sub_f32_e32 v2, v83, v49
	v_sub_f32_e32 v50, v76, v49
	v_exp_f32_e32 v83, v2
	v_sub_f32_e32 v2, v68, v49
	v_exp_f32_e32 v64, v50
	v_sub_f32_e32 v50, v92, v49
	v_exp_f32_e32 v68, v2
	v_sub_f32_e32 v2, v84, v49
	v_exp_f32_e32 v66, v50
	v_sub_f32_e32 v50, v77, v49
	v_exp_f32_e32 v8, v2
	v_sub_f32_e32 v2, v69, v49
	v_exp_f32_e32 v65, v50
	v_sub_f32_e32 v50, v93, v49
	v_exp_f32_e32 v69, v2
	v_sub_f32_e32 v2, v85, v49
	v_exp_f32_e32 v67, v50
	v_sub_f32_e32 v50, v78, v49
	v_exp_f32_e32 v9, v2
	v_sub_f32_e32 v2, v70, v49
	v_sub_f32_e32 v4, v87, v49
	v_exp_f32_e32 v70, v50
	v_sub_f32_e32 v50, v94, v49
	v_exp_f32_e64 v48, -v49
	v_sub_f32_e32 v3, v86, v49
	v_exp_f32_e32 v7, v4
	v_sub_f32_e32 v4, v72, v49
	v_sub_f32_e32 v5, v73, v49
	v_sub_f32_e32 v12, v74, v49
	v_sub_f32_e32 v13, v75, v49
	v_exp_f32_e32 v72, v50
	v_sub_f32_e32 v50, v79, v49
	v_exp_f32_e32 v6, v3
	v_sub_f32_e32 v3, v71, v49
	v_exp_f32_e32 v10, v4
	v_sub_f32_e32 v4, v88, v49
	v_exp_f32_e32 v11, v5
	v_sub_f32_e32 v5, v89, v49
	v_exp_f32_e32 v14, v12
	v_sub_f32_e32 v12, v90, v49
	v_exp_f32_e32 v15, v13
	v_sub_f32_e32 v13, v91, v49
	v_exp_f32_e32 v71, v50
	v_sub_f32_e32 v50, v95, v49
	v_exp_f32_e32 v2, v2
	v_exp_f32_e32 v3, v3
	v_exp_f32_e32 v4, v4
	v_exp_f32_e32 v5, v5
	v_exp_f32_e32 v12, v12
	v_exp_f32_e32 v13, v13
	v_exp_f32_e32 v73, v50
	v_add_f32_e32 v0, v0, v49
	v_pk_mul_f32 v[46:47], v[46:47], v[48:49] op_sel_hi:[1,0]
	v_pk_mul_f32 v[44:45], v[44:45], v[48:49] op_sel_hi:[1,0]
	v_pk_mul_f32 v[42:43], v[42:43], v[48:49] op_sel_hi:[1,0]
	v_pk_mul_f32 v[40:41], v[40:41], v[48:49] op_sel_hi:[1,0]
	v_pk_mul_f32 v[38:39], v[38:39], v[48:49] op_sel_hi:[1,0]
	v_pk_mul_f32 v[36:37], v[36:37], v[48:49] op_sel_hi:[1,0]
	v_pk_mul_f32 v[34:35], v[34:35], v[48:49] op_sel_hi:[1,0]
	v_pk_mul_f32 v[32:33], v[32:33], v[48:49] op_sel_hi:[1,0]
	v_pk_mul_f32 v[30:31], v[30:31], v[48:49] op_sel_hi:[1,0]
	v_pk_mul_f32 v[28:29], v[28:29], v[48:49] op_sel_hi:[1,0]
	v_pk_mul_f32 v[26:27], v[26:27], v[48:49] op_sel_hi:[1,0]
	v_pk_mul_f32 v[24:25], v[24:25], v[48:49] op_sel_hi:[1,0]
	v_pk_mul_f32 v[22:23], v[22:23], v[48:49] op_sel_hi:[1,0]
	v_pk_mul_f32 v[20:21], v[20:21], v[48:49] op_sel_hi:[1,0]
	v_pk_mul_f32 v[18:19], v[18:19], v[48:49] op_sel_hi:[1,0]
	v_pk_mul_f32 v[16:17], v[16:17], v[48:49] op_sel_hi:[1,0]
	v_mul_f32_e32 v171, v171, v48
	v_xor_b32_e32 v48, 0x80000000, v0
	v_mov_b32_e32 v49, v48
	v_mov_b32_e32 v50, v48
	v_mov_b32_e32 v51, v48
	v_mov_b32_e32 v52, v48
	v_mov_b32_e32 v53, v48
	v_mov_b32_e32 v54, v48
	v_mov_b32_e32 v55, v48
	v_mov_b32_e32 v56, v48
	v_mov_b32_e32 v57, v48
	v_mov_b32_e32 v58, v48
	v_mov_b32_e32 v59, v48
	v_mov_b32_e32 v60, v48
	v_mov_b32_e32 v61, v48
	v_mov_b32_e32 v62, v48
	v_mov_b32_e32 v63, v48
	s_branch .LBB0_1806

; DI f32x4 mfma16(bf16x8 a, bf16x8 b, f32x4 c) { return __builtin_amdgcn_mfma_f32_16x16x32_bf16(a, b, c, 0, 0, 0); }
; template <int MI, int NJ, bool SWAP, class AP, class BP>
; DI void gemm_main(f32x4 (&acc)[MI][NJ], const AP& ap, int a_kstep, const BP& bp, int b_kstep, int nk, bf16_t* smem) {
;     ...
;   for (int kt = 0; kt < nk; ++kt) {
;     const int buf = kt & 1;
;     sstore(buf ^ 1);
;     gload(kt + 2 < nk ? kt + 2 : nk - 1);
;     __builtin_amdgcn_sched_barrier(0);
;     const bf16_t* As = smem + buf * L::STAGE + (wm * 16 * MI + l15) * LDT + quad * 8;
;     const bf16_t* Bs = smem + buf * L::STAGE + L::A_ELEMS + (wn * 16 * NJ + l15) * LDT + quad * 8;
; #pragma unroll
;     for (int ks = 0; ks < 2; ++ks) {
;       if (MI * NJ >= 32 && ks == 1) asm volatile("" ::: "memory");
;       bf16x8 b[NJ];
; #pragma unroll
;       for (int j = 0; j < NJ; ++j) b[j] = *(const bf16x8*)(Bs + j * 16 * LDT + ks * 32);
; #pragma unroll
;       for (int i = 0; i < MI; ++i) {
;         const bf16x8 a = *(const bf16x8*)(As + i * 16 * LDT + ks * 32);
; #pragma unroll
;         for (int j = 0; j < NJ; ++j) acc[i][j] = SWAP ? mfma16(b[j], a, acc[i][j]) : mfma16(a, b[j], acc[i][j]);
;       }
;     }
;     __syncthreads();
;   }
.Lgm13_main:
	ds_read_b128 v[242:245], v177 offset:4608
	s_waitcnt lgkmcnt(4)
	v_mfma_f32_16x16x32_bf16 v[156:159], v[178:181], v[194:197], v[156:159]
	s_waitcnt lgkmcnt(3)
	v_mfma_f32_16x16x32_bf16 v[152:155], v[182:185], v[194:197], v[152:155]
	s_waitcnt lgkmcnt(2)
	v_mfma_f32_16x16x32_bf16 v[148:151], v[186:189], v[194:197], v[148:151]
	s_and_b32 s15, s1, 1
	s_min_u32 s16, s1, 13
	s_xor_b32 s17, s15, 1
	s_mul_i32 s17, s17, 0x12000
	v_add3_u32 v250, s17, v172, v170
	s_waitcnt vmcnt(7)
	ds_write_b128 v250, v[112:115]
	s_waitcnt lgkmcnt(2)
	v_mfma_f32_16x16x32_bf16 v[144:147], v[190:193], v[194:197], v[144:147]
	ds_read_b128 v[246:249], v177 offset:6912
	v_mfma_f32_16x16x32_bf16 v[108:111], v[178:181], v[198:201], v[108:111]
	s_lshl_b32 s26, s16, 7
	s_add_u32 s16, s2, s26
	v_add3_u32 v251, s17, v174, v170
	v_add3_u32 v252, s17, v175, v170
	v_add3_u32 v253, s17, v176, v170
	s_addc_u32 s17, s3, 0
	v_lshl_add_u64 v[112:113], s[16:17], 0, v[162:163]
	s_nop 0
	global_load_dwordx4 v[112:115], v[112:113], off offset:256
	v_mfma_f32_16x16x32_bf16 v[104:107], v[182:185], v[198:201], v[104:107]
	v_mfma_f32_16x16x32_bf16 v[100:103], v[186:189], v[198:201], v[100:103]
	v_mfma_f32_16x16x32_bf16 v[96:99], v[190:193], v[198:201], v[96:99]
	ds_read_b128 v[194:197], v177 offset:9216
	s_waitcnt lgkmcnt(3)
	v_mfma_f32_16x16x32_bf16 v[92:95], v[178:181], v[242:245], v[92:95]
	s_waitcnt vmcnt(7)
	ds_write_b128 v251, v[116:119]
	v_mfma_f32_16x16x32_bf16 v[88:91], v[182:185], v[242:245], v[88:91]
	v_mfma_f32_16x16x32_bf16 v[84:87], v[186:189], v[242:245], v[84:87]
	v_lshl_add_u64 v[116:117], s[16:17], 0, v[164:165]
	s_nop 0
	global_load_dwordx4 v[116:119], v[116:117], off offset:256
	v_mfma_f32_16x16x32_bf16 v[80:83], v[190:193], v[242:245], v[80:83]
	ds_read_b128 v[198:201], v177 offset:11520
	s_waitcnt lgkmcnt(3)
	v_mfma_f32_16x16x32_bf16 v[76:79], v[178:181], v[246:249], v[76:79]
	v_mfma_f32_16x16x32_bf16 v[72:75], v[182:185], v[246:249], v[72:75]
	v_mfma_f32_16x16x32_bf16 v[68:71], v[186:189], v[246:249], v[68:71]
	s_waitcnt vmcnt(7)
	ds_write_b128 v252, v[120:123]
	v_mfma_f32_16x16x32_bf16 v[64:67], v[190:193], v[246:249], v[64:67]
	ds_read_b128 v[242:245], v177 offset:13824
	s_waitcnt lgkmcnt(4)
	v_mfma_f32_16x16x32_bf16 v[60:63], v[178:181], v[194:197], v[60:63]
	v_lshl_add_u64 v[120:121], s[16:17], 0, v[166:167]
	s_nop 0
	global_load_dwordx4 v[120:123], v[120:121], off offset:256
	v_mfma_f32_16x16x32_bf16 v[56:59], v[182:185], v[194:197], v[56:59]
	v_mfma_f32_16x16x32_bf16 v[52:55], v[186:189], v[194:197], v[52:55]
	v_mfma_f32_16x16x32_bf16 v[48:51], v[190:193], v[194:197], v[48:51]
	ds_read_b128 v[246:249], v177 offset:16128
	s_waitcnt lgkmcnt(3)
	v_mfma_f32_16x16x32_bf16 v[44:47], v[178:181], v[198:201], v[44:47]
	s_waitcnt vmcnt(7)
	ds_write_b128 v253, v[124:127]
	v_mfma_f32_16x16x32_bf16 v[40:43], v[182:185], v[198:201], v[40:43]
	v_mfma_f32_16x16x32_bf16 v[36:39], v[186:189], v[198:201], v[36:39]
	v_lshl_add_u64 v[124:125], s[16:17], 0, v[168:169]
	s_nop 0
	global_load_dwordx4 v[124:127], v[124:125], off offset:256
	v_mfma_f32_16x16x32_bf16 v[32:35], v[190:193], v[198:201], v[32:35]
	ds_read_b128 v[194:197], v177 offset:64
	s_waitcnt lgkmcnt(3)
	v_mfma_f32_16x16x32_bf16 v[28:31], v[178:181], v[242:245], v[28:31]
	v_mfma_f32_16x16x32_bf16 v[24:27], v[182:185], v[242:245], v[24:27]
	v_mfma_f32_16x16x32_bf16 v[20:23], v[186:189], v[242:245], v[20:23]
	s_waitcnt vmcnt(7)
	ds_write_b128 v250, v[128:131] offset:36864
	v_mfma_f32_16x16x32_bf16 v[16:19], v[190:193], v[242:245], v[16:19]
	ds_read_b128 v[198:201], v177 offset:2368
	s_waitcnt lgkmcnt(4)
	v_mfma_f32_16x16x32_bf16 v[8:11], v[178:181], v[246:249], v[8:11]
	ds_read_b128 v[178:181], v202 offset:36928
	s_add_u32 s16, s12, s26
	s_addc_u32 s17, s13, 0
	v_lshl_add_u64 v[128:129], s[16:17], 0, v[162:163]
	s_nop 0
	global_load_dwordx4 v[128:131], v[128:129], off offset:256
	v_mfma_f32_16x16x32_bf16 v[4:7], v[182:185], v[246:249], v[4:7]
	ds_read_b128 v[182:185], v202 offset:39232
	v_mfma_f32_16x16x32_bf16 v[0:3], v[186:189], v[246:249], v[0:3]
	ds_read_b128 v[186:189], v202 offset:41536
	v_mfma_f32_16x16x32_bf16 v[12:15], v[190:193], v[246:249], v[12:15]
	ds_read_b128 v[190:193], v202 offset:43840
	ds_read_b128 v[242:245], v177 offset:4672
	s_waitcnt lgkmcnt(4)
	v_mfma_f32_16x16x32_bf16 v[156:159], v[178:181], v[194:197], v[156:159]
	s_waitcnt vmcnt(7)
	ds_write_b128 v251, v[132:135] offset:36864
	s_waitcnt lgkmcnt(4)
	v_mfma_f32_16x16x32_bf16 v[152:155], v[182:185], v[194:197], v[152:155]
	s_waitcnt lgkmcnt(3)
	v_mfma_f32_16x16x32_bf16 v[148:151], v[186:189], v[194:197], v[148:151]
	v_lshl_add_u64 v[132:133], s[16:17], 0, v[164:165]
	s_nop 0
	global_load_dwordx4 v[132:135], v[132:133], off offset:256
	s_waitcnt lgkmcnt(2)
	v_mfma_f32_16x16x32_bf16 v[144:147], v[190:193], v[194:197], v[144:147]
	ds_read_b128 v[246:249], v177 offset:6976
	v_mfma_f32_16x16x32_bf16 v[108:111], v[178:181], v[198:201], v[108:111]
	v_mfma_f32_16x16x32_bf16 v[104:107], v[182:185], v[198:201], v[104:107]
	v_mfma_f32_16x16x32_bf16 v[100:103], v[186:189], v[198:201], v[100:103]
	s_waitcnt vmcnt(7)
	ds_write_b128 v252, v[136:139] offset:36864
	v_mfma_f32_16x16x32_bf16 v[96:99], v[190:193], v[198:201], v[96:99]
	ds_read_b128 v[194:197], v177 offset:9280
	s_waitcnt lgkmcnt(4)
	v_mfma_f32_16x16x32_bf16 v[92:95], v[178:181], v[242:245], v[92:95]
	v_lshl_add_u64 v[136:137], s[16:17], 0, v[166:167]
	s_nop 0
	global_load_dwordx4 v[136:139], v[136:137], off offset:256
	v_mfma_f32_16x16x32_bf16 v[88:91], v[182:185], v[242:245], v[88:91]
	v_mfma_f32_16x16x32_bf16 v[84:87], v[186:189], v[242:245], v[84:87]
	v_mfma_f32_16x16x32_bf16 v[80:83], v[190:193], v[242:245], v[80:83]
	ds_read_b128 v[198:201], v177 offset:11584
	s_waitcnt lgkmcnt(3)
	v_mfma_f32_16x16x32_bf16 v[76:79], v[178:181], v[246:249], v[76:79]
	s_waitcnt vmcnt(7)
	ds_write_b128 v253, v[140:143] offset:36864
	v_mfma_f32_16x16x32_bf16 v[72:75], v[182:185], v[246:249], v[72:75]
	v_mfma_f32_16x16x32_bf16 v[68:71], v[186:189], v[246:249], v[68:71]
	v_lshl_add_u64 v[140:141], s[16:17], 0, v[168:169]
	s_nop 0
	global_load_dwordx4 v[140:143], v[140:141], off offset:256
	v_mfma_f32_16x16x32_bf16 v[64:67], v[190:193], v[246:249], v[64:67]
	ds_read_b128 v[242:245], v177 offset:13888
	s_waitcnt lgkmcnt(3)
	v_mfma_f32_16x16x32_bf16 v[60:63], v[178:181], v[194:197], v[60:63]
	v_mfma_f32_16x16x32_bf16 v[56:59], v[182:185], v[194:197], v[56:59]
	v_mfma_f32_16x16x32_bf16 v[52:55], v[186:189], v[194:197], v[52:55]
	v_mfma_f32_16x16x32_bf16 v[48:51], v[190:193], v[194:197], v[48:51]
	ds_read_b128 v[246:249], v177 offset:16192
	s_waitcnt lgkmcnt(3)
	v_mfma_f32_16x16x32_bf16 v[44:47], v[178:181], v[198:201], v[44:47]
	v_mfma_f32_16x16x32_bf16 v[40:43], v[182:185], v[198:201], v[40:43]
	v_mfma_f32_16x16x32_bf16 v[36:39], v[186:189], v[198:201], v[36:39]
	v_mfma_f32_16x16x32_bf16 v[32:35], v[190:193], v[198:201], v[32:35]
	s_waitcnt lgkmcnt(0)
	s_barrier
; DI f32x4 mfma16(bf16x8 a, bf16x8 b, f32x4 c) { return __builtin_amdgcn_mfma_f32_16x16x32_bf16(a, b, c, 0, 0, 0); }
; template <int MI, int NJ, bool SWAP, class AP, class BP>
; DI void gemm_main(f32x4 (&acc)[MI][NJ], const AP& ap, int a_kstep, const BP& bp, int b_kstep, int nk, bf16_t* smem) {
;     ...
;   for (int kt = 0; kt < nk; ++kt) {
;     const int buf = kt & 1;
;     sstore(buf ^ 1);
;     gload(kt + 2 < nk ? kt + 2 : nk - 1);
;     __builtin_amdgcn_sched_barrier(0);
;     const bf16_t* As = smem + buf * L::STAGE + (wm * 16 * MI + l15) * LDT + quad * 8;
;     const bf16_t* Bs = smem + buf * L::STAGE + L::A_ELEMS + (wn * 16 * NJ + l15) * LDT + quad * 8;
; #pragma unroll
;     for (int ks = 0; ks < 2; ++ks) {
;       if (MI * NJ >= 32 && ks == 1) asm volatile("" ::: "memory");
;       bf16x8 b[NJ];
; #pragma unroll
;       for (int j = 0; j < NJ; ++j) b[j] = *(const bf16x8*)(Bs + j * 16 * LDT + ks * 32);
; #pragma unroll
;       for (int i = 0; i < MI; ++i) {
;         const bf16x8 a = *(const bf16x8*)(As + i * 16 * LDT + ks * 32);
; #pragma unroll
;         for (int j = 0; j < NJ; ++j) acc[i][j] = SWAP ? mfma16(b[j], a, acc[i][j]) : mfma16(a, b[j], acc[i][j]);
;       }
;     }
;     __syncthreads();
;   }
	s_add_i32 s1, s1, 1
	s_cmp_lg_u32 s1, 16
	s_cbranch_scc0 .Lgm13_exit
	s_and_b32 s98, s1, 1
	s_mul_i32 s98, s98, 0x12000
	v_add3_u32 v202, s98, v160, v173
	v_add3_u32 v177, s98, v171, v173
	ds_read_b128 v[194:197], v177
	ds_read_b128 v[198:201], v177 offset:2304
	v_mfma_f32_16x16x32_bf16 v[28:31], v[178:181], v[242:245], v[28:31]
	v_mfma_f32_16x16x32_bf16 v[8:11], v[178:181], v[246:249], v[8:11]
	ds_read_b128 v[178:181], v202 offset:36864
	v_mfma_f32_16x16x32_bf16 v[24:27], v[182:185], v[242:245], v[24:27]
	v_mfma_f32_16x16x32_bf16 v[4:7], v[182:185], v[246:249], v[4:7]
	ds_read_b128 v[182:185], v202 offset:39168
	v_mfma_f32_16x16x32_bf16 v[20:23], v[186:189], v[242:245], v[20:23]
	v_mfma_f32_16x16x32_bf16 v[0:3], v[186:189], v[246:249], v[0:3]
	ds_read_b128 v[186:189], v202 offset:41472
	v_mfma_f32_16x16x32_bf16 v[16:19], v[190:193], v[242:245], v[16:19]
	v_mfma_f32_16x16x32_bf16 v[12:15], v[190:193], v[246:249], v[12:15]
	ds_read_b128 v[190:193], v202 offset:43776
	s_branch .Lgm13_main

; DI f32x4 mfma16(bf16x8 a, bf16x8 b, f32x4 c) { return __builtin_amdgcn_mfma_f32_16x16x32_bf16(a, b, c, 0, 0, 0); }
; template <int MI, int NJ, bool SWAP, class AP, class BP>
; DI void gemm_main(f32x4 (&acc)[MI][NJ], const AP& ap, int a_kstep, const BP& bp, int b_kstep, int nk, bf16_t* smem) {
;     ...
;   for (int kt = 0; kt < nk; ++kt) {
;     const int buf = kt & 1;
;     sstore(buf ^ 1);
;     gload(kt + 2 < nk ? kt + 2 : nk - 1);
;     __builtin_amdgcn_sched_barrier(0);
;     const bf16_t* As = smem + buf * L::STAGE + (wm * 16 * MI + l15) * LDT + quad * 8;
;     const bf16_t* Bs = smem + buf * L::STAGE + L::A_ELEMS + (wn * 16 * NJ + l15) * LDT + quad * 8;
; #pragma unroll
;     for (int ks = 0; ks < 2; ++ks) {
;       if (MI * NJ >= 32 && ks == 1) asm volatile("" ::: "memory");
;       bf16x8 b[NJ];
; #pragma unroll
;       for (int j = 0; j < NJ; ++j) b[j] = *(const bf16x8*)(Bs + j * 16 * LDT + ks * 32);
; #pragma unroll
;       for (int i = 0; i < MI; ++i) {
;         const bf16x8 a = *(const bf16x8*)(As + i * 16 * LDT + ks * 32);
; #pragma unroll
;         for (int j = 0; j < NJ; ++j) acc[i][j] = SWAP ? mfma16(b[j], a, acc[i][j]) : mfma16(a, b[j], acc[i][j]);
;       }
;     }
;     __syncthreads();
;   }
.Lgm15_main:
	ds_read_b128 v[242:245], v177 offset:4608
	s_waitcnt lgkmcnt(4)
	v_mfma_f32_16x16x32_bf16 v[156:159], v[178:181], v[194:197], v[156:159]
	s_waitcnt lgkmcnt(3)
	v_mfma_f32_16x16x32_bf16 v[152:155], v[182:185], v[194:197], v[152:155]
	s_waitcnt lgkmcnt(2)
	v_mfma_f32_16x16x32_bf16 v[148:151], v[186:189], v[194:197], v[148:151]
	s_and_b32 s17, s16, 1
	s_min_u32 s18, s16, 41
	s_xor_b32 s19, s17, 1
	s_mul_i32 s19, s19, 0x12000
	v_add3_u32 v250, s19, v172, v170
	s_waitcnt vmcnt(7)
	ds_write_b128 v250, v[112:115]
	s_waitcnt lgkmcnt(2)
	v_mfma_f32_16x16x32_bf16 v[144:147], v[190:193], v[194:197], v[144:147]
	ds_read_b128 v[246:249], v177 offset:6912
	v_mfma_f32_16x16x32_bf16 v[108:111], v[178:181], v[198:201], v[108:111]
	s_lshl_b32 s20, s18, 7
	s_add_u32 s18, s2, s20
	v_add3_u32 v251, s19, v173, v170
	v_add3_u32 v252, s19, v174, v170
	v_add3_u32 v253, s19, v175, v170
	s_addc_u32 s19, s3, 0
	v_lshl_add_u64 v[112:113], s[18:19], 0, v[162:163]
	s_nop 0
	global_load_dwordx4 v[112:115], v[112:113], off offset:256
	v_mfma_f32_16x16x32_bf16 v[104:107], v[182:185], v[198:201], v[104:107]
	v_mfma_f32_16x16x32_bf16 v[100:103], v[186:189], v[198:201], v[100:103]
	v_mfma_f32_16x16x32_bf16 v[96:99], v[190:193], v[198:201], v[96:99]
	ds_read_b128 v[194:197], v177 offset:9216
	s_waitcnt lgkmcnt(3)
	v_mfma_f32_16x16x32_bf16 v[92:95], v[178:181], v[242:245], v[92:95]
	s_waitcnt vmcnt(7)
	ds_write_b128 v251, v[116:119]
	v_mfma_f32_16x16x32_bf16 v[88:91], v[182:185], v[242:245], v[88:91]
	v_mfma_f32_16x16x32_bf16 v[84:87], v[186:189], v[242:245], v[84:87]
	v_lshl_add_u64 v[116:117], s[18:19], 0, v[164:165]
	s_nop 0
	global_load_dwordx4 v[116:119], v[116:117], off offset:256
	v_mfma_f32_16x16x32_bf16 v[80:83], v[190:193], v[242:245], v[80:83]
	ds_read_b128 v[198:201], v177 offset:11520
	s_waitcnt lgkmcnt(3)
	v_mfma_f32_16x16x32_bf16 v[76:79], v[178:181], v[246:249], v[76:79]
	v_mfma_f32_16x16x32_bf16 v[72:75], v[182:185], v[246:249], v[72:75]
	v_mfma_f32_16x16x32_bf16 v[68:71], v[186:189], v[246:249], v[68:71]
	s_waitcnt vmcnt(7)
	ds_write_b128 v252, v[120:123]
	v_mfma_f32_16x16x32_bf16 v[64:67], v[190:193], v[246:249], v[64:67]
	ds_read_b128 v[242:245], v177 offset:13824
	s_waitcnt lgkmcnt(4)
	v_mfma_f32_16x16x32_bf16 v[60:63], v[178:181], v[194:197], v[60:63]
	v_lshl_add_u64 v[120:121], s[18:19], 0, v[166:167]
	s_nop 0
	global_load_dwordx4 v[120:123], v[120:121], off offset:256
	v_mfma_f32_16x16x32_bf16 v[56:59], v[182:185], v[194:197], v[56:59]
	v_mfma_f32_16x16x32_bf16 v[52:55], v[186:189], v[194:197], v[52:55]
	v_mfma_f32_16x16x32_bf16 v[48:51], v[190:193], v[194:197], v[48:51]
	ds_read_b128 v[246:249], v177 offset:16128
	s_waitcnt lgkmcnt(3)
	v_mfma_f32_16x16x32_bf16 v[44:47], v[178:181], v[198:201], v[44:47]
	s_waitcnt vmcnt(7)
	ds_write_b128 v253, v[124:127]
	v_mfma_f32_16x16x32_bf16 v[40:43], v[182:185], v[198:201], v[40:43]
	v_mfma_f32_16x16x32_bf16 v[36:39], v[186:189], v[198:201], v[36:39]
	v_lshl_add_u64 v[124:125], s[18:19], 0, v[168:169]
	s_nop 0
	global_load_dwordx4 v[124:127], v[124:125], off offset:256
	v_mfma_f32_16x16x32_bf16 v[32:35], v[190:193], v[198:201], v[32:35]
	ds_read_b128 v[194:197], v177 offset:64
	s_waitcnt lgkmcnt(3)
	v_mfma_f32_16x16x32_bf16 v[28:31], v[178:181], v[242:245], v[28:31]
	v_mfma_f32_16x16x32_bf16 v[24:27], v[182:185], v[242:245], v[24:27]
	v_mfma_f32_16x16x32_bf16 v[20:23], v[186:189], v[242:245], v[20:23]
	s_waitcnt vmcnt(7)
	ds_write_b128 v250, v[128:131] offset:36864
	v_mfma_f32_16x16x32_bf16 v[16:19], v[190:193], v[242:245], v[16:19]
	ds_read_b128 v[198:201], v177 offset:2368
	s_waitcnt lgkmcnt(4)
	v_mfma_f32_16x16x32_bf16 v[8:11], v[178:181], v[246:249], v[8:11]
	ds_read_b128 v[178:181], v202 offset:36928
	s_add_u32 s18, s4, s20
	s_addc_u32 s19, s5, 0
	v_lshl_add_u64 v[128:129], s[18:19], 0, v[162:163]
	s_nop 0
	global_load_dwordx4 v[128:131], v[128:129], off offset:256
	v_mfma_f32_16x16x32_bf16 v[4:7], v[182:185], v[246:249], v[4:7]
	ds_read_b128 v[182:185], v202 offset:39232
	v_mfma_f32_16x16x32_bf16 v[0:3], v[186:189], v[246:249], v[0:3]
	ds_read_b128 v[186:189], v202 offset:41536
	v_mfma_f32_16x16x32_bf16 v[12:15], v[190:193], v[246:249], v[12:15]
	ds_read_b128 v[190:193], v202 offset:43840
	ds_read_b128 v[242:245], v177 offset:4672
	s_waitcnt lgkmcnt(4)
	v_mfma_f32_16x16x32_bf16 v[156:159], v[178:181], v[194:197], v[156:159]
	s_waitcnt vmcnt(7)
	ds_write_b128 v251, v[132:135] offset:36864
	s_waitcnt lgkmcnt(4)
	v_mfma_f32_16x16x32_bf16 v[152:155], v[182:185], v[194:197], v[152:155]
	s_waitcnt lgkmcnt(3)
	v_mfma_f32_16x16x32_bf16 v[148:151], v[186:189], v[194:197], v[148:151]
	v_lshl_add_u64 v[132:133], s[18:19], 0, v[164:165]
	s_nop 0
	global_load_dwordx4 v[132:135], v[132:133], off offset:256
	s_waitcnt lgkmcnt(2)
	v_mfma_f32_16x16x32_bf16 v[144:147], v[190:193], v[194:197], v[144:147]
	ds_read_b128 v[246:249], v177 offset:6976
	v_mfma_f32_16x16x32_bf16 v[108:111], v[178:181], v[198:201], v[108:111]
	v_mfma_f32_16x16x32_bf16 v[104:107], v[182:185], v[198:201], v[104:107]
	v_mfma_f32_16x16x32_bf16 v[100:103], v[186:189], v[198:201], v[100:103]
	s_waitcnt vmcnt(7)
	ds_write_b128 v252, v[136:139] offset:36864
	v_mfma_f32_16x16x32_bf16 v[96:99], v[190:193], v[198:201], v[96:99]
	ds_read_b128 v[194:197], v177 offset:9280
	s_waitcnt lgkmcnt(4)
	v_mfma_f32_16x16x32_bf16 v[92:95], v[178:181], v[242:245], v[92:95]
	v_lshl_add_u64 v[136:137], s[18:19], 0, v[166:167]
	s_nop 0
	global_load_dwordx4 v[136:139], v[136:137], off offset:256
	v_mfma_f32_16x16x32_bf16 v[88:91], v[182:185], v[242:245], v[88:91]
	v_mfma_f32_16x16x32_bf16 v[84:87], v[186:189], v[242:245], v[84:87]
	v_mfma_f32_16x16x32_bf16 v[80:83], v[190:193], v[242:245], v[80:83]
	ds_read_b128 v[198:201], v177 offset:11584
	s_waitcnt lgkmcnt(3)
	v_mfma_f32_16x16x32_bf16 v[76:79], v[178:181], v[246:249], v[76:79]
	s_waitcnt vmcnt(7)
	ds_write_b128 v253, v[140:143] offset:36864
	v_mfma_f32_16x16x32_bf16 v[72:75], v[182:185], v[246:249], v[72:75]
	v_mfma_f32_16x16x32_bf16 v[68:71], v[186:189], v[246:249], v[68:71]
	v_lshl_add_u64 v[140:141], s[18:19], 0, v[168:169]
	s_nop 0
	global_load_dwordx4 v[140:143], v[140:141], off offset:256
	v_mfma_f32_16x16x32_bf16 v[64:67], v[190:193], v[246:249], v[64:67]
	ds_read_b128 v[242:245], v177 offset:13888
	s_waitcnt lgkmcnt(3)
	v_mfma_f32_16x16x32_bf16 v[60:63], v[178:181], v[194:197], v[60:63]
	v_mfma_f32_16x16x32_bf16 v[56:59], v[182:185], v[194:197], v[56:59]
	v_mfma_f32_16x16x32_bf16 v[52:55], v[186:189], v[194:197], v[52:55]
	v_mfma_f32_16x16x32_bf16 v[48:51], v[190:193], v[194:197], v[48:51]
	ds_read_b128 v[246:249], v177 offset:16192
	s_waitcnt lgkmcnt(3)
	v_mfma_f32_16x16x32_bf16 v[44:47], v[178:181], v[198:201], v[44:47]
	v_mfma_f32_16x16x32_bf16 v[40:43], v[182:185], v[198:201], v[40:43]
	v_mfma_f32_16x16x32_bf16 v[36:39], v[186:189], v[198:201], v[36:39]
	v_mfma_f32_16x16x32_bf16 v[32:35], v[190:193], v[198:201], v[32:35]
	s_waitcnt lgkmcnt(0)
	s_barrier
; DI f32x4 mfma16(bf16x8 a, bf16x8 b, f32x4 c) { return __builtin_amdgcn_mfma_f32_16x16x32_bf16(a, b, c, 0, 0, 0); }
; template <int MI, int NJ, bool SWAP, class AP, class BP>
; DI void gemm_main(f32x4 (&acc)[MI][NJ], const AP& ap, int a_kstep, const BP& bp, int b_kstep, int nk, bf16_t* smem) {
;     ...
;   for (int kt = 0; kt < nk; ++kt) {
;     const int buf = kt & 1;
;     sstore(buf ^ 1);
;     gload(kt + 2 < nk ? kt + 2 : nk - 1);
;     __builtin_amdgcn_sched_barrier(0);
;     const bf16_t* As = smem + buf * L::STAGE + (wm * 16 * MI + l15) * LDT + quad * 8;
;     const bf16_t* Bs = smem + buf * L::STAGE + L::A_ELEMS + (wn * 16 * NJ + l15) * LDT + quad * 8;
; #pragma unroll
;     for (int ks = 0; ks < 2; ++ks) {
;       if (MI * NJ >= 32 && ks == 1) asm volatile("" ::: "memory");
;       bf16x8 b[NJ];
; #pragma unroll
;       for (int j = 0; j < NJ; ++j) b[j] = *(const bf16x8*)(Bs + j * 16 * LDT + ks * 32);
; #pragma unroll
;       for (int i = 0; i < MI; ++i) {
;         const bf16x8 a = *(const bf16x8*)(As + i * 16 * LDT + ks * 32);
; #pragma unroll
;         for (int j = 0; j < NJ; ++j) acc[i][j] = SWAP ? mfma16(b[j], a, acc[i][j]) : mfma16(a, b[j], acc[i][j]);
;       }
;     }
;     __syncthreads();
;   }
	s_add_i32 s16, s16, 1
	s_cmp_lg_u32 s16, 44
	s_cbranch_scc0 .Lgm15_exit
	s_and_b32 s98, s16, 1
	s_mul_i32 s98, s98, 0x12000
	v_add3_u32 v202, s98, v160, v176
	v_add3_u32 v177, s98, v171, v176
	ds_read_b128 v[194:197], v177
	ds_read_b128 v[198:201], v177 offset:2304
	v_mfma_f32_16x16x32_bf16 v[28:31], v[178:181], v[242:245], v[28:31]
	v_mfma_f32_16x16x32_bf16 v[8:11], v[178:181], v[246:249], v[8:11]
	ds_read_b128 v[178:181], v202 offset:36864
	v_mfma_f32_16x16x32_bf16 v[24:27], v[182:185], v[242:245], v[24:27]
	v_mfma_f32_16x16x32_bf16 v[4:7], v[182:185], v[246:249], v[4:7]
	ds_read_b128 v[182:185], v202 offset:39168
	v_mfma_f32_16x16x32_bf16 v[20:23], v[186:189], v[242:245], v[20:23]
	v_mfma_f32_16x16x32_bf16 v[0:3], v[186:189], v[246:249], v[0:3]
	ds_read_b128 v[186:189], v202 offset:41472
	v_mfma_f32_16x16x32_bf16 v[16:19], v[190:193], v[242:245], v[16:19]
	v_mfma_f32_16x16x32_bf16 v[12:15], v[190:193], v[246:249], v[12:15]
	ds_read_b128 v[190:193], v202 offset:43776
	s_branch .Lgm15_main
